# DPP row reductions replace LDS bpermute hops in conv LayerNorm and rstd table update
# speedup vs baseline: 1.0036x; 1.0036x over previous
; #define LAS __attribute__((address_space(3)))
; __device__ __forceinline__ void conv_phase(LAS unsigned char* lds, const bf16_t* U, bf16_t* C, const float* wdw, const float* bdw, const float* lng, const float* lnb,
;                                            int first, int stride, int end, int tid, int wave, int lane) {
;     ...
;         asm volatile("s_waitcnt lgkmcnt(0)" ::: "memory"); __builtin_amdgcn_s_barrier(); asm volatile("" ::: "memory");
;         typedef float f32x2 __attribute__((ext_vector_type(2)));
;         f32x2 acc[2][4][4];
; #pragma unroll
;         for (int p = 0; p < 2; ++p) {
; #pragma unroll
;             for (int j = 0; j < 4; ++j)
; #pragma unroll
;                 for (int c = 0; c < 4; ++c) acc[p][j][c] = (f32x2){0.f, 0.f};
;             f32x4 wt[8][2];
;             typedef const __attribute__((address_space(1))) f32x4 gf32x4;
;             const gf32x4* wq = (const gf32x4*)(wdw + p * 512 + lane * 8);
; #pragma unroll
;             for (int t = 0; t < 4; ++t) { wt[t][0] = wq[0]; wt[t][1] = wq[1]; wq += D / 4; asm volatile("" : "+v"(wq)); }
; #pragma unroll
;             for (int r = 0; r < TT / NWAVES + CW - 1; ++r) {
;                 if (r + 4 < CW) { wt[(r + 4) & 7][0] = wq[0]; wt[(r + 4) & 7][1] = wq[1]; wq += D / 4; asm volatile("" : "+v"(wq)); }
;                 const u32x4 xv = *(const LAS u32x4*)(lds + (4 * wave + r) * 2048 + p * 1024 + lane * 16);
;                 f32x2 x[4];
; #pragma unroll
;                 for (int i = 0; i < 4; ++i) x[i] = (f32x2){__uint_as_float(xv[i] << 16), __uint_as_float(xv[i] & 0xffff0000u)};
; #pragma unroll
;                 for (int j = 0; j < 4; ++j) { const int w = r - j;
;                     if (w >= 0 && w < CW) {
; #pragma unroll
;                         for (int c = 0; c < 4; ++c) { const f32x4 wv = wt[w & 7][c >> 1]; const f32x2 w2 = (c & 1) ? (f32x2){wv.z, wv.w} : (f32x2){wv.x, wv.y}; acc[p][j][c] = __builtin_elementwise_fma(w2, x[c], acc[p][j][c]); } } }
;                 asm volatile("" ::: "memory");
;             }
.LBB0_89:
	s_or_b64 exec, exec, s[4:5]
	s_waitcnt lgkmcnt(0)
	s_barrier
	global_load_dwordx4 v[56:59], v[84:85], off offset:16
	global_load_dwordx4 v[60:63], v[84:85], off
	v_mov_b64_e32 v[0:1], v[96:97]
	global_load_dwordx4 v[48:51], v[0:1], off offset:16
	global_load_dwordx4 v[52:55], v[0:1], off
	v_lshl_add_u64 v[0:1], v[0:1], 0, s[0:1]
	global_load_dwordx4 v[40:43], v[0:1], off offset:16
	global_load_dwordx4 v[44:47], v[0:1], off
	v_lshl_add_u64 v[0:1], v[0:1], 0, s[0:1]
	global_load_dwordx4 v[24:27], v[0:1], off offset:16
	global_load_dwordx4 v[28:31], v[0:1], off
	v_lshl_add_u64 v[8:9], v[0:1], 0, s[0:1]
	global_load_dwordx4 v[0:3], v[8:9], off offset:16
	global_load_dwordx4 v[4:7], v[8:9], off
	v_lshl_add_u64 v[16:17], v[8:9], 0, s[0:1]
	ds_read_b128 v[8:11], v134
	v_lshl_add_u64 v[36:37], v[16:17], 0, s[0:1]
	v_cmp_lt_i32_e64 s[40:41], v226, v225
	s_mov_b32 s4, 0x3727c5ac
	s_waitcnt lgkmcnt(0)
	v_lshlrev_b32_e32 v12, 16, v11
	v_and_b32_e32 v13, 0xffff0000, v11
	v_lshlrev_b32_e32 v14, 16, v10
	v_and_b32_e32 v15, 0xffff0000, v10
	v_lshlrev_b32_e32 v10, 16, v9
	v_and_b32_e32 v11, 0xffff0000, v9
	v_lshlrev_b32_e32 v18, 16, v8
	v_and_b32_e32 v19, 0xffff0000, v8
	v_add_u32_e32 v140, v140, v133
	s_waitcnt vmcnt(9)
	v_pk_fma_f32 v[32:33], v[56:57], v[14:15], 0 op_sel_hi:[1,1,0]
	s_waitcnt vmcnt(8)
	v_pk_fma_f32 v[20:21], v[60:61], v[18:19], 0 op_sel_hi:[1,1,0]
	v_pk_fma_f32 v[22:23], v[62:63], v[10:11], 0 op_sel_hi:[1,1,0]
	v_pk_fma_f32 v[34:35], v[58:59], v[12:13], 0 op_sel_hi:[1,1,0]
	global_load_dwordx4 v[8:11], v[16:17], off offset:16
	global_load_dwordx4 v[12:15], v[16:17], off
	ds_read_b128 v[16:19], v134 offset:2048
	v_lshl_add_u64 v[104:105], v[36:37], 0, s[0:1]
	s_waitcnt lgkmcnt(0)
	v_lshlrev_b32_e32 v38, 16, v16
	v_and_b32_e32 v39, 0xffff0000, v16
	v_lshlrev_b32_e32 v16, 16, v17
	v_and_b32_e32 v17, 0xffff0000, v17
	v_lshlrev_b32_e32 v64, 16, v18
	v_and_b32_e32 v65, 0xffff0000, v18
	v_lshlrev_b32_e32 v18, 16, v19
	v_and_b32_e32 v19, 0xffff0000, v19
	s_waitcnt vmcnt(8)
	v_pk_fma_f32 v[66:67], v[52:53], v[38:39], v[20:21]
	v_pk_fma_f32 v[68:69], v[54:55], v[16:17], v[22:23]
	v_pk_fma_f32 v[72:73], v[50:51], v[18:19], v[34:35]
	v_pk_fma_f32 v[74:75], v[62:63], v[16:17], 0 op_sel_hi:[1,1,0]
	v_pk_fma_f32 v[78:79], v[58:59], v[18:19], 0 op_sel_hi:[1,1,0]
	global_load_dwordx4 v[16:19], v[36:37], off offset:16
	global_load_dwordx4 v[20:23], v[36:37], off
	v_pk_fma_f32 v[70:71], v[48:49], v[64:65], v[32:33]
	ds_read_b128 v[32:35], v134 offset:4096
	v_pk_fma_f32 v[38:39], v[60:61], v[38:39], 0 op_sel_hi:[1,1,0]
	v_pk_fma_f32 v[76:77], v[56:57], v[64:65], 0 op_sel_hi:[1,1,0]
	v_lshl_add_u64 v[108:109], v[104:105], 0, s[0:1]
	s_waitcnt lgkmcnt(0)
	v_lshlrev_b32_e32 v36, 16, v32
	v_and_b32_e32 v37, 0xffff0000, v32
	v_lshlrev_b32_e32 v32, 16, v33
	v_and_b32_e32 v33, 0xffff0000, v33
	v_lshlrev_b32_e32 v80, 16, v34
	v_and_b32_e32 v81, 0xffff0000, v34
	v_lshlrev_b32_e32 v34, 16, v35
	v_and_b32_e32 v35, 0xffff0000, v35
	s_waitcnt vmcnt(8)
	v_pk_fma_f32 v[102:103], v[44:45], v[36:37], v[66:67]
	v_pk_fma_f32 v[100:101], v[46:47], v[32:33], v[68:69]
	v_pk_fma_f32 v[82:83], v[40:41], v[80:81], v[70:71]
	v_pk_fma_f32 v[64:65], v[42:43], v[34:35], v[72:73]
	v_pk_fma_f32 v[66:67], v[52:53], v[36:37], v[38:39]
	v_pk_fma_f32 v[68:69], v[54:55], v[32:33], v[74:75]
	v_pk_fma_f32 v[70:71], v[48:49], v[80:81], v[76:77]
	v_pk_fma_f32 v[72:73], v[50:51], v[34:35], v[78:79]
	v_pk_fma_f32 v[74:75], v[60:61], v[36:37], 0 op_sel_hi:[1,1,0]
	v_pk_fma_f32 v[76:77], v[62:63], v[32:33], 0 op_sel_hi:[1,1,0]
	v_pk_fma_f32 v[78:79], v[56:57], v[80:81], 0 op_sel_hi:[1,1,0]
	v_pk_fma_f32 v[80:81], v[58:59], v[34:35], 0 op_sel_hi:[1,1,0]
	global_load_dwordx4 v[32:35], v[104:105], off offset:16
	global_load_dwordx4 v[36:39], v[104:105], off
	ds_read_b128 v[104:107], v134 offset:6144
	s_waitcnt lgkmcnt(0)
	v_lshlrev_b32_e32 v110, 16, v104
	v_and_b32_e32 v111, 0xffff0000, v104
	v_lshlrev_b32_e32 v104, 16, v105
	v_and_b32_e32 v105, 0xffff0000, v105
	v_lshlrev_b32_e32 v112, 16, v106
	v_and_b32_e32 v113, 0xffff0000, v106
	v_lshlrev_b32_e32 v106, 16, v107
	v_and_b32_e32 v107, 0xffff0000, v107
	s_waitcnt vmcnt(8)
	v_pk_fma_f32 v[102:103], v[28:29], v[110:111], v[102:103]
	v_pk_fma_f32 v[100:101], v[30:31], v[104:105], v[100:101]
	v_pk_fma_f32 v[82:83], v[24:25], v[112:113], v[82:83]
	v_pk_fma_f32 v[114:115], v[26:27], v[106:107], v[64:65]
	v_pk_fma_f32 v[116:117], v[44:45], v[110:111], v[66:67]
	v_pk_fma_f32 v[68:69], v[46:47], v[104:105], v[68:69]
	v_pk_fma_f32 v[70:71], v[40:41], v[112:113], v[70:71]
	v_pk_fma_f32 v[72:73], v[42:43], v[106:107], v[72:73]
	v_pk_fma_f32 v[74:75], v[52:53], v[110:111], v[74:75]
	v_pk_fma_f32 v[76:77], v[54:55], v[104:105], v[76:77]
	v_pk_fma_f32 v[78:79], v[48:49], v[112:113], v[78:79]
	v_pk_fma_f32 v[80:81], v[50:51], v[106:107], v[80:81]
	v_pk_fma_f32 v[110:111], v[60:61], v[110:111], 0 op_sel_hi:[1,1,0]
	v_pk_fma_f32 v[104:105], v[62:63], v[104:105], 0 op_sel_hi:[1,1,0]
	v_pk_fma_f32 v[112:113], v[56:57], v[112:113], 0 op_sel_hi:[1,1,0]
	v_pk_fma_f32 v[106:107], v[58:59], v[106:107], 0 op_sel_hi:[1,1,0]
	global_load_dwordx4 v[56:59], v[108:109], off offset:16
	global_load_dwordx4 v[60:63], v[108:109], off
	v_lshl_add_u64 v[108:109], v[108:109], 0, s[0:1]
	ds_read_b128 v[64:67], v134 offset:8192
	s_waitcnt lgkmcnt(0)
; #define LAS __attribute__((address_space(3)))
; __device__ __forceinline__ void conv_phase(LAS unsigned char* lds, const bf16_t* U, bf16_t* C, const float* wdw, const float* bdw, const float* lng, const float* lnb,
;                                            int first, int stride, int end, int tid, int wave, int lane) {
;     ...
;             for (int r = 0; r < TT / NWAVES + CW - 1; ++r) {
;                 if (r + 4 < CW) { wt[(r + 4) & 7][0] = wq[0]; wt[(r + 4) & 7][1] = wq[1]; wq += D / 4; asm volatile("" : "+v"(wq)); }
;                 const u32x4 xv = *(const LAS u32x4*)(lds + (4 * wave + r) * 2048 + p * 1024 + lane * 16);
;                 f32x2 x[4];
; #pragma unroll
;                 for (int i = 0; i < 4; ++i) x[i] = (f32x2){__uint_as_float(xv[i] << 16), __uint_as_float(xv[i] & 0xffff0000u)};
; #pragma unroll
;                 for (int j = 0; j < 4; ++j) { const int w = r - j;
;                     if (w >= 0 && w < CW) {
; #pragma unroll
;                         for (int c = 0; c < 4; ++c) { const f32x4 wv = wt[w & 7][c >> 1]; const f32x2 w2 = (c & 1) ? (f32x2){wv.z, wv.w} : (f32x2){wv.x, wv.y}; acc[p][j][c] = __builtin_elementwise_fma(w2, x[c], acc[p][j][c]); } } }
;                 asm volatile("" ::: "memory");
;             }
	v_lshlrev_b32_e32 v118, 16, v64
	v_and_b32_e32 v119, 0xffff0000, v64
	v_lshlrev_b32_e32 v64, 16, v65
	v_and_b32_e32 v65, 0xffff0000, v65
	v_lshlrev_b32_e32 v120, 16, v66
	v_and_b32_e32 v121, 0xffff0000, v66
	v_lshlrev_b32_e32 v66, 16, v67
	v_and_b32_e32 v67, 0xffff0000, v67
	v_pk_fma_f32 v[110:111], v[52:53], v[118:119], v[110:111]
	v_pk_fma_f32 v[104:105], v[54:55], v[64:65], v[104:105]
	v_pk_fma_f32 v[112:113], v[48:49], v[120:121], v[112:113]
	v_pk_fma_f32 v[106:107], v[50:51], v[66:67], v[106:107]
	global_load_dwordx4 v[48:51], v[108:109], off offset:16
	global_load_dwordx4 v[52:55], v[108:109], off
	v_lshl_add_u64 v[108:109], v[108:109], 0, s[0:1]
	s_waitcnt vmcnt(10)
	v_pk_fma_f32 v[100:101], v[6:7], v[64:65], v[100:101]
	v_pk_fma_f32 v[114:115], v[2:3], v[66:67], v[114:115]
	v_pk_fma_f32 v[68:69], v[30:31], v[64:65], v[68:69]
	v_pk_fma_f32 v[72:73], v[26:27], v[66:67], v[72:73]
	v_pk_fma_f32 v[76:77], v[46:47], v[64:65], v[76:77]
	v_pk_fma_f32 v[80:81], v[42:43], v[66:67], v[80:81]
	ds_read_b128 v[64:67], v134 offset:10240
	v_pk_fma_f32 v[102:103], v[4:5], v[118:119], v[102:103]
	v_pk_fma_f32 v[82:83], v[0:1], v[120:121], v[82:83]
	v_pk_fma_f32 v[116:117], v[28:29], v[118:119], v[116:117]
	v_pk_fma_f32 v[70:71], v[24:25], v[120:121], v[70:71]
	v_pk_fma_f32 v[74:75], v[44:45], v[118:119], v[74:75]
	v_pk_fma_f32 v[78:79], v[40:41], v[120:121], v[78:79]
	s_waitcnt lgkmcnt(0)
	v_lshlrev_b32_e32 v118, 16, v64
	v_and_b32_e32 v119, 0xffff0000, v64
	v_lshlrev_b32_e32 v64, 16, v65
	v_and_b32_e32 v65, 0xffff0000, v65
	v_lshlrev_b32_e32 v120, 16, v66
	v_and_b32_e32 v121, 0xffff0000, v66
	v_lshlrev_b32_e32 v66, 16, v67
	v_and_b32_e32 v67, 0xffff0000, v67
	v_pk_fma_f32 v[110:111], v[44:45], v[118:119], v[110:111]
	v_pk_fma_f32 v[104:105], v[46:47], v[64:65], v[104:105]
	v_pk_fma_f32 v[112:113], v[40:41], v[120:121], v[112:113]
	v_pk_fma_f32 v[106:107], v[42:43], v[66:67], v[106:107]
	global_load_dwordx4 v[40:43], v[108:109], off offset:16
	global_load_dwordx4 v[44:47], v[108:109], off
	v_lshl_add_u64 v[108:109], v[108:109], 0, s[0:1]
	s_waitcnt vmcnt(10)
	v_pk_fma_f32 v[100:101], v[14:15], v[64:65], v[100:101]
	v_pk_fma_f32 v[114:115], v[10:11], v[66:67], v[114:115]
	v_pk_fma_f32 v[68:69], v[6:7], v[64:65], v[68:69]
	v_pk_fma_f32 v[72:73], v[2:3], v[66:67], v[72:73]
	v_pk_fma_f32 v[76:77], v[30:31], v[64:65], v[76:77]
	v_pk_fma_f32 v[80:81], v[26:27], v[66:67], v[80:81]
	ds_read_b128 v[64:67], v134 offset:12288
	v_pk_fma_f32 v[102:103], v[12:13], v[118:119], v[102:103]
	v_pk_fma_f32 v[82:83], v[8:9], v[120:121], v[82:83]
	v_pk_fma_f32 v[116:117], v[4:5], v[118:119], v[116:117]
	v_pk_fma_f32 v[70:71], v[0:1], v[120:121], v[70:71]
	v_pk_fma_f32 v[74:75], v[28:29], v[118:119], v[74:75]
	v_pk_fma_f32 v[78:79], v[24:25], v[120:121], v[78:79]
	s_waitcnt lgkmcnt(0)
	v_lshlrev_b32_e32 v118, 16, v64
	v_and_b32_e32 v119, 0xffff0000, v64
	v_lshlrev_b32_e32 v64, 16, v65
	v_and_b32_e32 v65, 0xffff0000, v65
	v_lshlrev_b32_e32 v120, 16, v66
	v_and_b32_e32 v121, 0xffff0000, v66
	v_lshlrev_b32_e32 v66, 16, v67
	v_and_b32_e32 v67, 0xffff0000, v67
	s_waitcnt vmcnt(8)
	v_pk_fma_f32 v[100:101], v[22:23], v[64:65], v[100:101]
	v_pk_fma_f32 v[114:115], v[18:19], v[66:67], v[114:115]
	v_pk_fma_f32 v[68:69], v[14:15], v[64:65], v[68:69]
	v_pk_fma_f32 v[72:73], v[10:11], v[66:67], v[72:73]
	v_pk_fma_f32 v[76:77], v[6:7], v[64:65], v[76:77]
	v_pk_fma_f32 v[80:81], v[2:3], v[66:67], v[80:81]
	v_pk_fma_f32 v[104:105], v[30:31], v[64:65], v[104:105]
	v_pk_fma_f32 v[112:113], v[24:25], v[120:121], v[112:113]
	v_pk_fma_f32 v[106:107], v[26:27], v[66:67], v[106:107]
	global_load_dwordx4 v[24:27], v[108:109], off offset:16
	global_load_dwordx4 v[64:67], v[108:109], off
	v_lshl_add_u64 v[108:109], v[108:109], 0, s[0:1]
	v_pk_fma_f32 v[110:111], v[28:29], v[118:119], v[110:111]
	ds_read_b128 v[28:31], v134 offset:14336
	v_pk_fma_f32 v[102:103], v[20:21], v[118:119], v[102:103]
	v_pk_fma_f32 v[82:83], v[16:17], v[120:121], v[82:83]
	v_pk_fma_f32 v[116:117], v[12:13], v[118:119], v[116:117]
	v_pk_fma_f32 v[70:71], v[8:9], v[120:121], v[70:71]
	v_pk_fma_f32 v[74:75], v[4:5], v[118:119], v[74:75]
	v_pk_fma_f32 v[78:79], v[0:1], v[120:121], v[78:79]
	s_waitcnt lgkmcnt(0)
	v_lshlrev_b32_e32 v118, 16, v28
	v_and_b32_e32 v119, 0xffff0000, v28
	v_lshlrev_b32_e32 v28, 16, v29
	v_and_b32_e32 v29, 0xffff0000, v29
	v_lshlrev_b32_e32 v120, 16, v30
	v_and_b32_e32 v121, 0xffff0000, v30
	v_lshlrev_b32_e32 v30, 16, v31
	v_and_b32_e32 v31, 0xffff0000, v31
	s_waitcnt vmcnt(8)
	v_pk_fma_f32 v[100:101], v[38:39], v[28:29], v[100:101]
	v_pk_fma_f32 v[114:115], v[34:35], v[30:31], v[114:115]
	v_pk_fma_f32 v[122:123], v[22:23], v[28:29], v[68:69]
	v_pk_fma_f32 v[124:125], v[16:17], v[120:121], v[70:71]
	v_pk_fma_f32 v[72:73], v[18:19], v[30:31], v[72:73]
	v_pk_fma_f32 v[76:77], v[14:15], v[28:29], v[76:77]
	v_pk_fma_f32 v[80:81], v[10:11], v[30:31], v[80:81]
	v_pk_fma_f32 v[28:29], v[6:7], v[28:29], v[104:105]
	v_pk_fma_f32 v[104:105], v[0:1], v[120:121], v[112:113]
	v_pk_fma_f32 v[30:31], v[2:3], v[30:31], v[106:107]
	global_load_dwordx4 v[0:3], v[108:109], off offset:16
	global_load_dwordx4 v[68:71], v[108:109], off
	v_lshl_add_u64 v[106:107], v[108:109], 0, s[0:1]
	v_pk_fma_f32 v[110:111], v[4:5], v[118:119], v[110:111]
	ds_read_b128 v[4:7], v134 offset:16384
	v_pk_fma_f32 v[74:75], v[12:13], v[118:119], v[74:75]
	v_pk_fma_f32 v[102:103], v[36:37], v[118:119], v[102:103]
	v_pk_fma_f32 v[82:83], v[32:33], v[120:121], v[82:83]
	s_waitcnt lgkmcnt(0)
; #define LAS __attribute__((address_space(3)))
; __device__ __forceinline__ void conv_phase(LAS unsigned char* lds, const bf16_t* U, bf16_t* C, const float* wdw, const float* bdw, const float* lng, const float* lnb,
;                                            int first, int stride, int end, int tid, int wave, int lane) {
;     ...
;             for (int r = 0; r < TT / NWAVES + CW - 1; ++r) {
;                 if (r + 4 < CW) { wt[(r + 4) & 7][0] = wq[0]; wt[(r + 4) & 7][1] = wq[1]; wq += D / 4; asm volatile("" : "+v"(wq)); }
;                 const u32x4 xv = *(const LAS u32x4*)(lds + (4 * wave + r) * 2048 + p * 1024 + lane * 16);
;                 f32x2 x[4];
; #pragma unroll
;                 for (int i = 0; i < 4; ++i) x[i] = (f32x2){__uint_as_float(xv[i] << 16), __uint_as_float(xv[i] & 0xffff0000u)};
; #pragma unroll
;                 for (int j = 0; j < 4; ++j) { const int w = r - j;
;                     if (w >= 0 && w < CW) {
; #pragma unroll
;                         for (int c = 0; c < 4; ++c) { const f32x4 wv = wt[w & 7][c >> 1]; const f32x2 w2 = (c & 1) ? (f32x2){wv.z, wv.w} : (f32x2){wv.x, wv.y}; acc[p][j][c] = __builtin_elementwise_fma(w2, x[c], acc[p][j][c]); } } }
;                 asm volatile("" ::: "memory");
;             }
	v_lshlrev_b32_e32 v108, 16, v4
	v_and_b32_e32 v109, 0xffff0000, v4
	v_lshlrev_b32_e32 v4, 16, v5
	v_and_b32_e32 v5, 0xffff0000, v5
	v_lshlrev_b32_e32 v112, 16, v6
	v_and_b32_e32 v113, 0xffff0000, v6
	v_lshlrev_b32_e32 v6, 16, v7
	v_and_b32_e32 v7, 0xffff0000, v7
	v_pk_fma_f32 v[116:117], v[20:21], v[118:119], v[116:117]
	v_pk_fma_f32 v[78:79], v[8:9], v[120:121], v[78:79]
	s_waitcnt vmcnt(8)
	v_pk_fma_f32 v[100:101], v[62:63], v[4:5], v[100:101]
	v_pk_fma_f32 v[114:115], v[58:59], v[6:7], v[114:115]
	v_pk_fma_f32 v[118:119], v[38:39], v[4:5], v[122:123]
	v_pk_fma_f32 v[120:121], v[32:33], v[112:113], v[124:125]
	v_pk_fma_f32 v[122:123], v[34:35], v[6:7], v[72:73]
	v_pk_fma_f32 v[124:125], v[20:21], v[108:109], v[74:75]
	v_pk_fma_f32 v[76:77], v[22:23], v[4:5], v[76:77]
	v_pk_fma_f32 v[80:81], v[18:19], v[6:7], v[80:81]
	v_pk_fma_f32 v[14:15], v[14:15], v[4:5], v[28:29]
	v_pk_fma_f32 v[30:31], v[10:11], v[6:7], v[30:31]
	global_load_dwordx4 v[4:7], v[106:107], off offset:16
	global_load_dwordx4 v[72:75], v[106:107], off
	v_pk_fma_f32 v[28:29], v[8:9], v[112:113], v[104:105]
	v_lshl_add_u64 v[104:105], v[106:107], 0, s[0:1]
	ds_read_b128 v[8:11], v134 offset:18432
	v_pk_fma_f32 v[102:103], v[60:61], v[108:109], v[102:103]
	v_pk_fma_f32 v[116:117], v[36:37], v[108:109], v[116:117]
	v_pk_fma_f32 v[78:79], v[16:17], v[112:113], v[78:79]
	v_pk_fma_f32 v[12:13], v[12:13], v[108:109], v[110:111]
	s_waitcnt lgkmcnt(0)
	v_lshlrev_b32_e32 v106, 16, v8
	v_and_b32_e32 v107, 0xffff0000, v8
	v_lshlrev_b32_e32 v8, 16, v9
	v_and_b32_e32 v9, 0xffff0000, v9
	v_lshlrev_b32_e32 v108, 16, v10
	v_and_b32_e32 v109, 0xffff0000, v10
	v_lshlrev_b32_e32 v10, 16, v11
	v_and_b32_e32 v11, 0xffff0000, v11
	v_pk_fma_f32 v[82:83], v[56:57], v[112:113], v[82:83]
	s_waitcnt vmcnt(8)
	v_pk_fma_f32 v[100:101], v[54:55], v[8:9], v[100:101]
	v_pk_fma_f32 v[110:111], v[50:51], v[10:11], v[114:115]
	v_pk_fma_f32 v[112:113], v[60:61], v[106:107], v[116:117]
	v_pk_fma_f32 v[114:115], v[62:63], v[8:9], v[118:119]
	v_pk_fma_f32 v[116:117], v[56:57], v[108:109], v[120:121]
	v_pk_fma_f32 v[118:119], v[58:59], v[10:11], v[122:123]
	v_pk_fma_f32 v[120:121], v[36:37], v[106:107], v[124:125]
	v_pk_fma_f32 v[122:123], v[38:39], v[8:9], v[76:77]
	v_pk_fma_f32 v[124:125], v[32:33], v[108:109], v[78:79]
	v_pk_fma_f32 v[80:81], v[34:35], v[10:11], v[80:81]
	v_pk_fma_f32 v[22:23], v[22:23], v[8:9], v[14:15]
	v_pk_fma_f32 v[16:17], v[16:17], v[108:109], v[28:29]
	v_pk_fma_f32 v[18:19], v[18:19], v[10:11], v[30:31]
	global_load_dwordx4 v[8:11], v[104:105], off offset:16
	global_load_dwordx4 v[76:79], v[104:105], off
	v_lshl_add_u64 v[28:29], v[104:105], 0, s[0:1]
	v_pk_fma_f32 v[20:21], v[20:21], v[106:107], v[12:13]
	ds_read_b128 v[12:15], v134 offset:20480
	v_pk_fma_f32 v[102:103], v[52:53], v[106:107], v[102:103]
	v_pk_fma_f32 v[82:83], v[48:49], v[108:109], v[82:83]
	s_waitcnt lgkmcnt(0)
	v_lshlrev_b32_e32 v30, 16, v12
	v_and_b32_e32 v31, 0xffff0000, v12
	v_lshlrev_b32_e32 v12, 16, v13
	v_and_b32_e32 v13, 0xffff0000, v13
	v_lshlrev_b32_e32 v104, 16, v14
	v_and_b32_e32 v105, 0xffff0000, v14
	v_lshlrev_b32_e32 v14, 16, v15
	v_and_b32_e32 v15, 0xffff0000, v15
	s_waitcnt vmcnt(8)
	v_pk_fma_f32 v[102:103], v[44:45], v[30:31], v[102:103]
	v_pk_fma_f32 v[100:101], v[46:47], v[12:13], v[100:101]
	v_pk_fma_f32 v[106:107], v[42:43], v[14:15], v[110:111]
	v_pk_fma_f32 v[108:109], v[52:53], v[30:31], v[112:113]
	v_pk_fma_f32 v[110:111], v[54:55], v[12:13], v[114:115]
	v_pk_fma_f32 v[112:113], v[48:49], v[104:105], v[116:117]
	v_pk_fma_f32 v[114:115], v[50:51], v[14:15], v[118:119]
	v_pk_fma_f32 v[116:117], v[60:61], v[30:31], v[120:121]
	v_pk_fma_f32 v[118:119], v[62:63], v[12:13], v[122:123]
	v_pk_fma_f32 v[80:81], v[58:59], v[14:15], v[80:81]
	v_pk_fma_f32 v[20:21], v[36:37], v[30:31], v[20:21]
	v_pk_fma_f32 v[22:23], v[38:39], v[12:13], v[22:23]
	v_pk_fma_f32 v[30:31], v[32:33], v[104:105], v[16:17]
	v_pk_fma_f32 v[32:33], v[34:35], v[14:15], v[18:19]
	global_load_dwordx4 v[12:15], v[28:29], off offset:16
	global_load_dwordx4 v[36:39], v[28:29], off
	v_lshl_add_u64 v[28:29], v[28:29], 0, s[0:1]
	ds_read_b128 v[16:19], v134 offset:22528
	v_pk_fma_f32 v[82:83], v[40:41], v[104:105], v[82:83]
	v_pk_fma_f32 v[120:121], v[56:57], v[104:105], v[124:125]
	s_waitcnt lgkmcnt(0)
	v_lshlrev_b32_e32 v34, 16, v16
	v_and_b32_e32 v35, 0xffff0000, v16
	v_lshlrev_b32_e32 v16, 16, v17
	v_and_b32_e32 v17, 0xffff0000, v17
	v_lshlrev_b32_e32 v104, 16, v18
	v_and_b32_e32 v105, 0xffff0000, v18
	v_lshlrev_b32_e32 v18, 16, v19
	v_and_b32_e32 v19, 0xffff0000, v19
	s_waitcnt vmcnt(8)
	v_pk_fma_f32 v[102:103], v[64:65], v[34:35], v[102:103]
	v_pk_fma_f32 v[100:101], v[66:67], v[16:17], v[100:101]
	v_pk_fma_f32 v[106:107], v[26:27], v[18:19], v[106:107]
	v_pk_fma_f32 v[108:109], v[44:45], v[34:35], v[108:109]
	v_pk_fma_f32 v[110:111], v[46:47], v[16:17], v[110:111]
	v_pk_fma_f32 v[114:115], v[42:43], v[18:19], v[114:115]
	v_pk_fma_f32 v[116:117], v[52:53], v[34:35], v[116:117]
	v_pk_fma_f32 v[118:119], v[54:55], v[16:17], v[118:119]
	v_pk_fma_f32 v[80:81], v[50:51], v[18:19], v[80:81]
	v_pk_fma_f32 v[34:35], v[60:61], v[34:35], v[20:21]
	v_pk_fma_f32 v[60:61], v[62:63], v[16:17], v[22:23]
	v_pk_fma_f32 v[30:31], v[56:57], v[104:105], v[30:31]
	v_pk_fma_f32 v[32:33], v[58:59], v[18:19], v[32:33]
	global_load_dwordx4 v[16:19], v[28:29], off offset:16
	global_load_dwordx4 v[56:59], v[28:29], off
	v_lshl_add_u64 v[28:29], v[28:29], 0, s[0:1]
	ds_read_b128 v[20:23], v134 offset:24576
	v_pk_fma_f32 v[82:83], v[24:25], v[104:105], v[82:83]
	v_pk_fma_f32 v[112:113], v[40:41], v[104:105], v[112:113]
	v_pk_fma_f32 v[120:121], v[48:49], v[104:105], v[120:121]
	s_waitcnt lgkmcnt(0)
; #define LAS __attribute__((address_space(3)))
; __device__ __forceinline__ void conv_phase(LAS unsigned char* lds, const bf16_t* U, bf16_t* C, const float* wdw, const float* bdw, const float* lng, const float* lnb,
;                                            int first, int stride, int end, int tid, int wave, int lane) {
;     ...
;             for (int r = 0; r < TT / NWAVES + CW - 1; ++r) {
;                 if (r + 4 < CW) { wt[(r + 4) & 7][0] = wq[0]; wt[(r + 4) & 7][1] = wq[1]; wq += D / 4; asm volatile("" : "+v"(wq)); }
;                 const u32x4 xv = *(const LAS u32x4*)(lds + (4 * wave + r) * 2048 + p * 1024 + lane * 16);
;                 f32x2 x[4];
; #pragma unroll
;                 for (int i = 0; i < 4; ++i) x[i] = (f32x2){__uint_as_float(xv[i] << 16), __uint_as_float(xv[i] & 0xffff0000u)};
; #pragma unroll
;                 for (int j = 0; j < 4; ++j) { const int w = r - j;
;                     if (w >= 0 && w < CW) {
; #pragma unroll
;                         for (int c = 0; c < 4; ++c) { const f32x4 wv = wt[w & 7][c >> 1]; const f32x2 w2 = (c & 1) ? (f32x2){wv.z, wv.w} : (f32x2){wv.x, wv.y}; acc[p][j][c] = __builtin_elementwise_fma(w2, x[c], acc[p][j][c]); } } }
;                 asm volatile("" ::: "memory");
;             }
	v_lshlrev_b32_e32 v62, 16, v20
	v_and_b32_e32 v63, 0xffff0000, v20
	v_lshlrev_b32_e32 v20, 16, v21
	v_and_b32_e32 v21, 0xffff0000, v21
	v_lshlrev_b32_e32 v104, 16, v22
	v_and_b32_e32 v105, 0xffff0000, v22
	v_lshlrev_b32_e32 v22, 16, v23
	v_and_b32_e32 v23, 0xffff0000, v23
	s_waitcnt vmcnt(8)
	v_pk_fma_f32 v[100:101], v[70:71], v[20:21], v[100:101]
	v_pk_fma_f32 v[106:107], v[2:3], v[22:23], v[106:107]
	v_pk_fma_f32 v[110:111], v[66:67], v[20:21], v[110:111]
	v_pk_fma_f32 v[114:115], v[26:27], v[22:23], v[114:115]
	v_pk_fma_f32 v[118:119], v[46:47], v[20:21], v[118:119]
	v_pk_fma_f32 v[80:81], v[42:43], v[22:23], v[80:81]
	v_pk_fma_f32 v[34:35], v[52:53], v[62:63], v[34:35]
	v_pk_fma_f32 v[52:53], v[54:55], v[20:21], v[60:61]
	v_pk_fma_f32 v[54:55], v[48:49], v[104:105], v[30:31]
	v_pk_fma_f32 v[32:33], v[50:51], v[22:23], v[32:33]
	global_load_dwordx4 v[20:23], v[28:29], off offset:16
	global_load_dwordx4 v[48:51], v[28:29], off
	v_lshl_add_u64 v[60:61], v[28:29], 0, s[0:1]
	ds_read_b128 v[28:31], v134 offset:26624
	v_pk_fma_f32 v[102:103], v[68:69], v[62:63], v[102:103]
	v_pk_fma_f32 v[82:83], v[0:1], v[104:105], v[82:83]
	v_pk_fma_f32 v[108:109], v[64:65], v[62:63], v[108:109]
	v_pk_fma_f32 v[112:113], v[24:25], v[104:105], v[112:113]
	v_pk_fma_f32 v[116:117], v[44:45], v[62:63], v[116:117]
	v_pk_fma_f32 v[120:121], v[40:41], v[104:105], v[120:121]
	s_waitcnt lgkmcnt(0)
	v_lshlrev_b32_e32 v62, 16, v28
	v_and_b32_e32 v63, 0xffff0000, v28
	v_lshlrev_b32_e32 v28, 16, v29
	v_and_b32_e32 v29, 0xffff0000, v29
	v_lshlrev_b32_e32 v104, 16, v30
	v_and_b32_e32 v105, 0xffff0000, v30
	v_lshlrev_b32_e32 v30, 16, v31
	v_and_b32_e32 v31, 0xffff0000, v31
	s_waitcnt vmcnt(8)
	v_pk_fma_f32 v[100:101], v[74:75], v[28:29], v[100:101]
	v_pk_fma_f32 v[106:107], v[6:7], v[30:31], v[106:107]
	v_pk_fma_f32 v[110:111], v[70:71], v[28:29], v[110:111]
	v_pk_fma_f32 v[114:115], v[2:3], v[30:31], v[114:115]
	v_pk_fma_f32 v[118:119], v[66:67], v[28:29], v[118:119]
	v_pk_fma_f32 v[80:81], v[26:27], v[30:31], v[80:81]
	v_pk_fma_f32 v[46:47], v[46:47], v[28:29], v[52:53]
	v_pk_fma_f32 v[52:53], v[40:41], v[104:105], v[54:55]
	v_pk_fma_f32 v[54:55], v[42:43], v[30:31], v[32:33]
	global_load_dwordx4 v[28:31], v[60:61], off offset:16
	global_load_dwordx4 v[40:43], v[60:61], off
	v_lshl_add_u64 v[60:61], v[60:61], 0, s[0:1]
	v_pk_fma_f32 v[44:45], v[44:45], v[62:63], v[34:35]
	ds_read_b128 v[32:35], v134 offset:28672
	v_pk_fma_f32 v[102:103], v[72:73], v[62:63], v[102:103]
	v_pk_fma_f32 v[82:83], v[4:5], v[104:105], v[82:83]
	v_pk_fma_f32 v[108:109], v[68:69], v[62:63], v[108:109]
	v_pk_fma_f32 v[112:113], v[0:1], v[104:105], v[112:113]
	v_pk_fma_f32 v[116:117], v[64:65], v[62:63], v[116:117]
	v_pk_fma_f32 v[120:121], v[24:25], v[104:105], v[120:121]
	s_waitcnt lgkmcnt(0)
	v_lshlrev_b32_e32 v62, 16, v32
	v_and_b32_e32 v63, 0xffff0000, v32
	v_lshlrev_b32_e32 v32, 16, v33
	v_and_b32_e32 v33, 0xffff0000, v33
	v_lshlrev_b32_e32 v104, 16, v34
	v_and_b32_e32 v105, 0xffff0000, v34
	v_lshlrev_b32_e32 v34, 16, v35
	v_and_b32_e32 v35, 0xffff0000, v35
	s_waitcnt vmcnt(8)
	v_pk_fma_f32 v[102:103], v[76:77], v[62:63], v[102:103]
	v_pk_fma_f32 v[108:109], v[72:73], v[62:63], v[108:109]
	v_pk_fma_f32 v[116:117], v[68:69], v[62:63], v[116:117]
	v_pk_fma_f32 v[62:63], v[64:65], v[62:63], v[44:45]
	v_pk_fma_f32 v[64:65], v[66:67], v[32:33], v[46:47]
	v_pk_fma_f32 v[52:53], v[24:25], v[104:105], v[52:53]
	v_pk_fma_f32 v[54:55], v[26:27], v[34:35], v[54:55]
	global_load_dwordx4 v[24:27], v[60:61], off offset:16
	global_load_dwordx4 v[44:47], v[60:61], off
	v_lshl_add_u64 v[60:61], v[60:61], 0, s[0:1]
	v_pk_fma_f32 v[100:101], v[78:79], v[32:33], v[100:101]
	v_pk_fma_f32 v[106:107], v[10:11], v[34:35], v[106:107]
	v_pk_fma_f32 v[110:111], v[74:75], v[32:33], v[110:111]
	v_pk_fma_f32 v[114:115], v[6:7], v[34:35], v[114:115]
	v_pk_fma_f32 v[118:119], v[70:71], v[32:33], v[118:119]
	v_pk_fma_f32 v[80:81], v[2:3], v[34:35], v[80:81]
	ds_read_b128 v[32:35], v134 offset:30720
	v_pk_fma_f32 v[82:83], v[8:9], v[104:105], v[82:83]
	v_pk_fma_f32 v[112:113], v[4:5], v[104:105], v[112:113]
	v_pk_fma_f32 v[120:121], v[0:1], v[104:105], v[120:121]
	s_waitcnt lgkmcnt(0)
	v_lshlrev_b32_e32 v66, 16, v32
	v_and_b32_e32 v67, 0xffff0000, v32
	v_lshlrev_b32_e32 v104, 16, v34
	v_and_b32_e32 v105, 0xffff0000, v34
	v_lshlrev_b32_e32 v34, 16, v35
	v_and_b32_e32 v35, 0xffff0000, v35
	s_waitcnt vmcnt(8)
	v_pk_fma_f32 v[102:103], v[36:37], v[66:67], v[102:103]
	v_pk_fma_f32 v[108:109], v[76:77], v[66:67], v[108:109]
	v_pk_fma_f32 v[116:117], v[72:73], v[66:67], v[116:117]
	v_pk_fma_f32 v[62:63], v[68:69], v[66:67], v[62:63]
	v_pk_fma_f32 v[66:67], v[0:1], v[104:105], v[52:53]
	v_pk_fma_f32 v[68:69], v[2:3], v[34:35], v[54:55]
	global_load_dwordx4 v[0:3], v[60:61], off offset:16
	global_load_dwordx4 v[52:55], v[60:61], off
	v_lshlrev_b32_e32 v32, 16, v33
	v_and_b32_e32 v33, 0xffff0000, v33
	v_pk_fma_f32 v[64:65], v[70:71], v[32:33], v[64:65]
	v_lshl_add_u64 v[70:71], v[60:61], 0, s[0:1]
	v_pk_fma_f32 v[100:101], v[38:39], v[32:33], v[100:101]
	v_pk_fma_f32 v[106:107], v[14:15], v[34:35], v[106:107]
	v_pk_fma_f32 v[110:111], v[78:79], v[32:33], v[110:111]
	v_pk_fma_f32 v[114:115], v[10:11], v[34:35], v[114:115]
	v_pk_fma_f32 v[118:119], v[74:75], v[32:33], v[118:119]
	v_pk_fma_f32 v[80:81], v[6:7], v[34:35], v[80:81]
	ds_read_b128 v[32:35], v134 offset:32768
	v_pk_fma_f32 v[82:83], v[12:13], v[104:105], v[82:83]
	v_pk_fma_f32 v[112:113], v[8:9], v[104:105], v[112:113]
	v_pk_fma_f32 v[120:121], v[4:5], v[104:105], v[120:121]
	s_waitcnt lgkmcnt(0)
; #define LAS __attribute__((address_space(3)))
; __device__ __forceinline__ void conv_phase(LAS unsigned char* lds, const bf16_t* U, bf16_t* C, const float* wdw, const float* bdw, const float* lng, const float* lnb,
;                                            int first, int stride, int end, int tid, int wave, int lane) {
;     ...
;             for (int r = 0; r < TT / NWAVES + CW - 1; ++r) {
;                 if (r + 4 < CW) { wt[(r + 4) & 7][0] = wq[0]; wt[(r + 4) & 7][1] = wq[1]; wq += D / 4; asm volatile("" : "+v"(wq)); }
;                 const u32x4 xv = *(const LAS u32x4*)(lds + (4 * wave + r) * 2048 + p * 1024 + lane * 16);
;                 f32x2 x[4];
; #pragma unroll
;                 for (int i = 0; i < 4; ++i) x[i] = (f32x2){__uint_as_float(xv[i] << 16), __uint_as_float(xv[i] & 0xffff0000u)};
; #pragma unroll
;                 for (int j = 0; j < 4; ++j) { const int w = r - j;
;                     if (w >= 0 && w < CW) {
; #pragma unroll
;                         for (int c = 0; c < 4; ++c) { const f32x4 wv = wt[w & 7][c >> 1]; const f32x2 w2 = (c & 1) ? (f32x2){wv.z, wv.w} : (f32x2){wv.x, wv.y}; acc[p][j][c] = __builtin_elementwise_fma(w2, x[c], acc[p][j][c]); } } }
;                 asm volatile("" ::: "memory");
;             }
	v_lshlrev_b32_e32 v60, 16, v32
	v_and_b32_e32 v61, 0xffff0000, v32
	v_lshlrev_b32_e32 v104, 16, v34
	v_and_b32_e32 v105, 0xffff0000, v34
	v_lshlrev_b32_e32 v34, 16, v35
	v_and_b32_e32 v35, 0xffff0000, v35
	v_lshlrev_b32_e32 v32, 16, v33
	v_and_b32_e32 v33, 0xffff0000, v33
	s_waitcnt vmcnt(8)
	v_pk_fma_f32 v[102:103], v[56:57], v[60:61], v[102:103]
	v_pk_fma_f32 v[108:109], v[36:37], v[60:61], v[108:109]
	v_pk_fma_f32 v[116:117], v[76:77], v[60:61], v[116:117]
	v_pk_fma_f32 v[72:73], v[72:73], v[60:61], v[62:63]
	v_pk_fma_f32 v[66:67], v[4:5], v[104:105], v[66:67]
	v_pk_fma_f32 v[68:69], v[6:7], v[34:35], v[68:69]
	global_load_dwordx4 v[4:7], v[70:71], off offset:16
	global_load_dwordx4 v[60:63], v[70:71], off
	v_lshl_add_u64 v[70:71], v[70:71], 0, s[0:1]
	v_pk_fma_f32 v[100:101], v[58:59], v[32:33], v[100:101]
	v_pk_fma_f32 v[106:107], v[18:19], v[34:35], v[106:107]
	v_pk_fma_f32 v[110:111], v[38:39], v[32:33], v[110:111]
	v_pk_fma_f32 v[114:115], v[14:15], v[34:35], v[114:115]
	v_pk_fma_f32 v[118:119], v[78:79], v[32:33], v[118:119]
	v_pk_fma_f32 v[80:81], v[10:11], v[34:35], v[80:81]
	v_pk_fma_f32 v[64:65], v[74:75], v[32:33], v[64:65]
	ds_read_b128 v[32:35], v134 offset:34816
	v_pk_fma_f32 v[82:83], v[16:17], v[104:105], v[82:83]
	v_pk_fma_f32 v[112:113], v[12:13], v[104:105], v[112:113]
	v_pk_fma_f32 v[120:121], v[8:9], v[104:105], v[120:121]
	s_waitcnt lgkmcnt(0)
	v_lshlrev_b32_e32 v74, 16, v32
	v_and_b32_e32 v75, 0xffff0000, v32
	v_lshlrev_b32_e32 v32, 16, v33
	v_and_b32_e32 v33, 0xffff0000, v33
	v_lshlrev_b32_e32 v104, 16, v34
	v_and_b32_e32 v105, 0xffff0000, v34
	v_lshlrev_b32_e32 v34, 16, v35
	v_and_b32_e32 v35, 0xffff0000, v35
	s_waitcnt vmcnt(8)
	v_pk_fma_f32 v[102:103], v[48:49], v[74:75], v[102:103]
	v_pk_fma_f32 v[108:109], v[56:57], v[74:75], v[108:109]
	v_pk_fma_f32 v[116:117], v[36:37], v[74:75], v[116:117]
	v_pk_fma_f32 v[72:73], v[76:77], v[74:75], v[72:73]
	v_pk_fma_f32 v[74:75], v[78:79], v[32:33], v[64:65]
	v_lshl_add_u64 v[78:79], v[70:71], 0, s[0:1]
	v_pk_fma_f32 v[100:101], v[50:51], v[32:33], v[100:101]
	v_pk_fma_f32 v[106:107], v[22:23], v[34:35], v[106:107]
	v_pk_fma_f32 v[110:111], v[58:59], v[32:33], v[110:111]
	v_pk_fma_f32 v[114:115], v[18:19], v[34:35], v[114:115]
	v_pk_fma_f32 v[118:119], v[38:39], v[32:33], v[118:119]
	v_pk_fma_f32 v[80:81], v[14:15], v[34:35], v[80:81]
	v_pk_fma_f32 v[76:77], v[8:9], v[104:105], v[66:67]
	v_pk_fma_f32 v[68:69], v[10:11], v[34:35], v[68:69]
	global_load_dwordx4 v[32:35], v[70:71], off offset:16
	global_load_dwordx4 v[64:67], v[70:71], off
	ds_read_b128 v[8:11], v134 offset:36864
	v_pk_fma_f32 v[82:83], v[20:21], v[104:105], v[82:83]
	v_pk_fma_f32 v[112:113], v[16:17], v[104:105], v[112:113]
	v_pk_fma_f32 v[120:121], v[12:13], v[104:105], v[120:121]
	s_waitcnt lgkmcnt(0)
	v_lshlrev_b32_e32 v70, 16, v8
	v_and_b32_e32 v71, 0xffff0000, v8
	v_lshlrev_b32_e32 v8, 16, v9
	v_and_b32_e32 v9, 0xffff0000, v9
	v_lshlrev_b32_e32 v104, 16, v10
	v_and_b32_e32 v105, 0xffff0000, v10
	v_lshlrev_b32_e32 v10, 16, v11
	v_and_b32_e32 v11, 0xffff0000, v11
	s_waitcnt vmcnt(8)
	v_pk_fma_f32 v[102:103], v[40:41], v[70:71], v[102:103]
	v_pk_fma_f32 v[108:109], v[48:49], v[70:71], v[108:109]
	v_pk_fma_f32 v[116:117], v[56:57], v[70:71], v[116:117]
	v_pk_fma_f32 v[72:73], v[36:37], v[70:71], v[72:73]
	v_pk_fma_f32 v[74:75], v[38:39], v[8:9], v[74:75]
	v_pk_fma_f32 v[14:15], v[14:15], v[10:11], v[68:69]
	global_load_dwordx4 v[36:39], v[78:79], off offset:16
	global_load_dwordx4 v[68:71], v[78:79], off
	v_pk_fma_f32 v[12:13], v[12:13], v[104:105], v[76:77]
	v_lshl_add_u64 v[76:77], v[78:79], 0, s[0:1]
	v_pk_fma_f32 v[100:101], v[42:43], v[8:9], v[100:101]
	v_pk_fma_f32 v[106:107], v[30:31], v[10:11], v[106:107]
	v_pk_fma_f32 v[110:111], v[50:51], v[8:9], v[110:111]
	v_pk_fma_f32 v[114:115], v[22:23], v[10:11], v[114:115]
	v_pk_fma_f32 v[118:119], v[58:59], v[8:9], v[118:119]
	v_pk_fma_f32 v[80:81], v[18:19], v[10:11], v[80:81]
	ds_read_b128 v[8:11], v134 offset:38912
	v_pk_fma_f32 v[82:83], v[28:29], v[104:105], v[82:83]
	v_pk_fma_f32 v[112:113], v[20:21], v[104:105], v[112:113]
	v_pk_fma_f32 v[120:121], v[16:17], v[104:105], v[120:121]
	s_waitcnt lgkmcnt(0)
	v_lshlrev_b32_e32 v78, 16, v8
	v_and_b32_e32 v79, 0xffff0000, v8
	v_lshlrev_b32_e32 v8, 16, v9
	v_and_b32_e32 v9, 0xffff0000, v9
	v_lshlrev_b32_e32 v104, 16, v10
	v_and_b32_e32 v105, 0xffff0000, v10
	v_lshlrev_b32_e32 v10, 16, v11
	v_and_b32_e32 v11, 0xffff0000, v11
	s_waitcnt vmcnt(8)
	v_pk_fma_f32 v[102:103], v[44:45], v[78:79], v[102:103]
	v_pk_fma_f32 v[108:109], v[40:41], v[78:79], v[108:109]
	v_pk_fma_f32 v[116:117], v[48:49], v[78:79], v[116:117]
	v_pk_fma_f32 v[78:79], v[56:57], v[78:79], v[72:73]
	v_pk_fma_f32 v[122:123], v[58:59], v[8:9], v[74:75]
	v_pk_fma_f32 v[12:13], v[16:17], v[104:105], v[12:13]
	global_load_dwordx4 v[56:59], v[76:77], off offset:16
	global_load_dwordx4 v[72:75], v[76:77], off
	v_lshl_add_u64 v[16:17], v[76:77], 0, s[0:1]
	v_pk_fma_f32 v[100:101], v[46:47], v[8:9], v[100:101]
	v_pk_fma_f32 v[106:107], v[26:27], v[10:11], v[106:107]
	v_pk_fma_f32 v[110:111], v[42:43], v[8:9], v[110:111]
	v_pk_fma_f32 v[114:115], v[30:31], v[10:11], v[114:115]
	v_pk_fma_f32 v[118:119], v[50:51], v[8:9], v[118:119]
	v_pk_fma_f32 v[80:81], v[22:23], v[10:11], v[80:81]
	v_pk_fma_f32 v[14:15], v[18:19], v[10:11], v[14:15]
	ds_read_b128 v[8:11], v134 offset:40960
	v_pk_fma_f32 v[82:83], v[24:25], v[104:105], v[82:83]
	v_pk_fma_f32 v[112:113], v[28:29], v[104:105], v[112:113]
	v_pk_fma_f32 v[120:121], v[20:21], v[104:105], v[120:121]
	s_waitcnt lgkmcnt(0)
; #define LAS __attribute__((address_space(3)))
; __device__ __forceinline__ void conv_phase(LAS unsigned char* lds, const bf16_t* U, bf16_t* C, const float* wdw, const float* bdw, const float* lng, const float* lnb,
;                                            int first, int stride, int end, int tid, int wave, int lane) {
;     ...
;             for (int r = 0; r < TT / NWAVES + CW - 1; ++r) {
;                 if (r + 4 < CW) { wt[(r + 4) & 7][0] = wq[0]; wt[(r + 4) & 7][1] = wq[1]; wq += D / 4; asm volatile("" : "+v"(wq)); }
;                 const u32x4 xv = *(const LAS u32x4*)(lds + (4 * wave + r) * 2048 + p * 1024 + lane * 16);
;                 f32x2 x[4];
; #pragma unroll
;                 for (int i = 0; i < 4; ++i) x[i] = (f32x2){__uint_as_float(xv[i] << 16), __uint_as_float(xv[i] & 0xffff0000u)};
; #pragma unroll
;                 for (int j = 0; j < 4; ++j) { const int w = r - j;
;                     if (w >= 0 && w < CW) {
; #pragma unroll
;                         for (int c = 0; c < 4; ++c) { const f32x4 wv = wt[w & 7][c >> 1]; const f32x2 w2 = (c & 1) ? (f32x2){wv.z, wv.w} : (f32x2){wv.x, wv.y}; acc[p][j][c] = __builtin_elementwise_fma(w2, x[c], acc[p][j][c]); } } }
;                 asm volatile("" ::: "memory");
;             }
	v_lshlrev_b32_e32 v18, 16, v8
	v_and_b32_e32 v19, 0xffff0000, v8
	v_lshlrev_b32_e32 v8, 16, v9
	v_and_b32_e32 v9, 0xffff0000, v9
	v_lshlrev_b32_e32 v76, 16, v10
	v_and_b32_e32 v77, 0xffff0000, v10
	v_lshlrev_b32_e32 v10, 16, v11
	v_and_b32_e32 v11, 0xffff0000, v11
	s_waitcnt vmcnt(8)
	v_pk_fma_f32 v[102:103], v[52:53], v[18:19], v[102:103]
	v_pk_fma_f32 v[82:83], v[0:1], v[76:77], v[82:83]
	v_pk_fma_f32 v[104:105], v[2:3], v[10:11], v[106:107]
	v_pk_fma_f32 v[106:107], v[44:45], v[18:19], v[108:109]
	v_pk_fma_f32 v[108:109], v[46:47], v[8:9], v[110:111]
	v_pk_fma_f32 v[110:111], v[24:25], v[76:77], v[112:113]
	v_pk_fma_f32 v[112:113], v[26:27], v[10:11], v[114:115]
	v_pk_fma_f32 v[114:115], v[40:41], v[18:19], v[116:117]
	v_pk_fma_f32 v[116:117], v[42:43], v[8:9], v[118:119]
	v_pk_fma_f32 v[118:119], v[28:29], v[76:77], v[120:121]
	v_pk_fma_f32 v[18:19], v[48:49], v[18:19], v[78:79]
	v_pk_fma_f32 v[120:121], v[50:51], v[8:9], v[122:123]
	v_pk_fma_f32 v[12:13], v[20:21], v[76:77], v[12:13]
	global_load_dwordx4 v[48:51], v[16:17], off offset:16
	global_load_dwordx4 v[76:79], v[16:17], off
	v_lshl_add_u64 v[16:17], v[16:17], 0, s[0:1]
	v_pk_fma_f32 v[100:101], v[54:55], v[8:9], v[100:101]
	v_pk_fma_f32 v[80:81], v[30:31], v[10:11], v[80:81]
	v_pk_fma_f32 v[14:15], v[22:23], v[10:11], v[14:15]
	ds_read_b128 v[8:11], v134 offset:43008
	s_waitcnt lgkmcnt(0)
	v_lshlrev_b32_e32 v20, 16, v8
	v_and_b32_e32 v21, 0xffff0000, v8
	v_lshlrev_b32_e32 v8, 16, v9
	v_and_b32_e32 v9, 0xffff0000, v9
	v_lshlrev_b32_e32 v22, 16, v10
	v_and_b32_e32 v23, 0xffff0000, v10
	v_lshlrev_b32_e32 v10, 16, v11
	v_and_b32_e32 v11, 0xffff0000, v11
	s_waitcnt vmcnt(8)
	v_pk_fma_f32 v[102:103], v[60:61], v[20:21], v[102:103]
	v_pk_fma_f32 v[106:107], v[52:53], v[20:21], v[106:107]
	v_pk_fma_f32 v[114:115], v[44:45], v[20:21], v[114:115]
	v_pk_fma_f32 v[18:19], v[40:41], v[20:21], v[18:19]
	v_pk_fma_f32 v[20:21], v[42:43], v[8:9], v[120:121]
	v_pk_fma_f32 v[12:13], v[28:29], v[22:23], v[12:13]
	v_pk_fma_f32 v[14:15], v[30:31], v[10:11], v[14:15]
	global_load_dwordx4 v[28:31], v[16:17], off offset:16
	global_load_dwordx4 v[40:43], v[16:17], off
	v_lshl_add_u64 v[16:17], v[16:17], 0, s[0:1]
	v_pk_fma_f32 v[100:101], v[62:63], v[8:9], v[100:101]
	v_pk_fma_f32 v[104:105], v[6:7], v[10:11], v[104:105]
	v_pk_fma_f32 v[108:109], v[54:55], v[8:9], v[108:109]
	v_pk_fma_f32 v[112:113], v[2:3], v[10:11], v[112:113]
	v_pk_fma_f32 v[116:117], v[46:47], v[8:9], v[116:117]
	v_pk_fma_f32 v[80:81], v[26:27], v[10:11], v[80:81]
	ds_read_b128 v[8:11], v134 offset:45056
	v_pk_fma_f32 v[82:83], v[4:5], v[22:23], v[82:83]
	v_pk_fma_f32 v[110:111], v[0:1], v[22:23], v[110:111]
	v_pk_fma_f32 v[118:119], v[24:25], v[22:23], v[118:119]
	s_waitcnt lgkmcnt(0)
	v_lshlrev_b32_e32 v120, 16, v10
	v_and_b32_e32 v121, 0xffff0000, v10
	v_lshlrev_b32_e32 v22, 16, v8
	v_and_b32_e32 v23, 0xffff0000, v8
	v_lshlrev_b32_e32 v8, 16, v9
	v_and_b32_e32 v9, 0xffff0000, v9
	v_lshlrev_b32_e32 v10, 16, v11
	v_and_b32_e32 v11, 0xffff0000, v11
	s_waitcnt vmcnt(9)
	v_pk_fma_f32 v[82:83], v[32:33], v[120:121], v[82:83]
	v_pk_fma_f32 v[110:111], v[4:5], v[120:121], v[110:111]
	v_pk_fma_f32 v[118:119], v[0:1], v[120:121], v[118:119]
	v_pk_fma_f32 v[12:13], v[24:25], v[120:121], v[12:13]
	v_lshl_add_u64 v[120:121], v[16:17], 0, s[0:1]
	s_waitcnt vmcnt(8)
	v_pk_fma_f32 v[100:101], v[66:67], v[8:9], v[100:101]
	v_pk_fma_f32 v[104:105], v[34:35], v[10:11], v[104:105]
	v_pk_fma_f32 v[108:109], v[62:63], v[8:9], v[108:109]
	v_pk_fma_f32 v[112:113], v[6:7], v[10:11], v[112:113]
	v_pk_fma_f32 v[116:117], v[54:55], v[8:9], v[116:117]
	v_pk_fma_f32 v[80:81], v[2:3], v[10:11], v[80:81]
	v_pk_fma_f32 v[18:19], v[44:45], v[22:23], v[18:19]
	v_pk_fma_f32 v[20:21], v[46:47], v[8:9], v[20:21]
	v_pk_fma_f32 v[14:15], v[26:27], v[10:11], v[14:15]
	global_load_dwordx4 v[24:27], v[16:17], off offset:16
	global_load_dwordx4 v[44:47], v[16:17], off
	ds_read_b128 v[8:11], v134 offset:47104
	v_pk_fma_f32 v[102:103], v[64:65], v[22:23], v[102:103]
	v_pk_fma_f32 v[106:107], v[60:61], v[22:23], v[106:107]
	v_pk_fma_f32 v[114:115], v[52:53], v[22:23], v[114:115]
	s_waitcnt lgkmcnt(0)
	v_lshlrev_b32_e32 v16, 16, v8
	v_and_b32_e32 v17, 0xffff0000, v8
	v_lshlrev_b32_e32 v8, 16, v9
	v_and_b32_e32 v9, 0xffff0000, v9
	v_lshlrev_b32_e32 v22, 16, v10
	v_and_b32_e32 v23, 0xffff0000, v10
	s_waitcnt vmcnt(8)
	v_pk_fma_f32 v[102:103], v[68:69], v[16:17], v[102:103]
	v_pk_fma_f32 v[100:101], v[70:71], v[8:9], v[100:101]
	v_pk_fma_f32 v[82:83], v[36:37], v[22:23], v[82:83]
	v_pk_fma_f32 v[106:107], v[64:65], v[16:17], v[106:107]
	v_pk_fma_f32 v[108:109], v[66:67], v[8:9], v[108:109]
	v_pk_fma_f32 v[110:111], v[32:33], v[22:23], v[110:111]
	v_pk_fma_f32 v[114:115], v[60:61], v[16:17], v[114:115]
	v_pk_fma_f32 v[116:117], v[62:63], v[8:9], v[116:117]
	v_pk_fma_f32 v[118:119], v[4:5], v[22:23], v[118:119]
	v_pk_fma_f32 v[52:53], v[52:53], v[16:17], v[18:19]
	v_pk_fma_f32 v[8:9], v[54:55], v[8:9], v[20:21]
	v_pk_fma_f32 v[12:13], v[0:1], v[22:23], v[12:13]
	global_load_dwordx4 v[16:19], v[120:121], off offset:16
	global_load_dwordx4 v[20:23], v[120:121], off
	v_lshlrev_b32_e32 v10, 16, v11
	v_and_b32_e32 v11, 0xffff0000, v11
	v_lshl_add_u64 v[54:55], v[120:121], 0, s[0:1]
	v_pk_fma_f32 v[104:105], v[38:39], v[10:11], v[104:105]
	v_pk_fma_f32 v[112:113], v[34:35], v[10:11], v[112:113]
	v_pk_fma_f32 v[80:81], v[6:7], v[10:11], v[80:81]
	v_pk_fma_f32 v[10:11], v[2:3], v[10:11], v[14:15]
	ds_read_b128 v[0:3], v134 offset:49152
	s_waitcnt lgkmcnt(0)
; #define LAS __attribute__((address_space(3)))
; __device__ __forceinline__ void conv_phase(LAS unsigned char* lds, const bf16_t* U, bf16_t* C, const float* wdw, const float* bdw, const float* lng, const float* lnb,
;                                            int first, int stride, int end, int tid, int wave, int lane) {
;     ...
;             for (int r = 0; r < TT / NWAVES + CW - 1; ++r) {
;                 if (r + 4 < CW) { wt[(r + 4) & 7][0] = wq[0]; wt[(r + 4) & 7][1] = wq[1]; wq += D / 4; asm volatile("" : "+v"(wq)); }
;                 const u32x4 xv = *(const LAS u32x4*)(lds + (4 * wave + r) * 2048 + p * 1024 + lane * 16);
;                 f32x2 x[4];
; #pragma unroll
;                 for (int i = 0; i < 4; ++i) x[i] = (f32x2){__uint_as_float(xv[i] << 16), __uint_as_float(xv[i] & 0xffff0000u)};
; #pragma unroll
;                 for (int j = 0; j < 4; ++j) { const int w = r - j;
;                     if (w >= 0 && w < CW) {
; #pragma unroll
;                         for (int c = 0; c < 4; ++c) { const f32x4 wv = wt[w & 7][c >> 1]; const f32x2 w2 = (c & 1) ? (f32x2){wv.z, wv.w} : (f32x2){wv.x, wv.y}; acc[p][j][c] = __builtin_elementwise_fma(w2, x[c], acc[p][j][c]); } } }
;                 asm volatile("" ::: "memory");
;             }
	v_lshlrev_b32_e32 v14, 16, v0
	v_and_b32_e32 v15, 0xffff0000, v0
	v_lshlrev_b32_e32 v0, 16, v1
	v_and_b32_e32 v1, 0xffff0000, v1
	v_lshlrev_b32_e32 v120, 16, v2
	v_and_b32_e32 v121, 0xffff0000, v2
	v_lshlrev_b32_e32 v2, 16, v3
	v_and_b32_e32 v3, 0xffff0000, v3
	s_waitcnt vmcnt(8)
	v_pk_fma_f32 v[102:103], v[72:73], v[14:15], v[102:103]
	v_pk_fma_f32 v[106:107], v[68:69], v[14:15], v[106:107]
	v_pk_fma_f32 v[114:115], v[64:65], v[14:15], v[114:115]
	v_pk_fma_f32 v[52:53], v[60:61], v[14:15], v[52:53]
	v_pk_fma_f32 v[60:61], v[62:63], v[0:1], v[8:9]
	v_pk_fma_f32 v[4:5], v[4:5], v[120:121], v[12:13]
	v_pk_fma_f32 v[6:7], v[6:7], v[2:3], v[10:11]
	global_load_dwordx4 v[8:11], v[54:55], off offset:16
	global_load_dwordx4 v[12:15], v[54:55], off
	v_lshl_add_u64 v[54:55], v[54:55], 0, s[0:1]
	v_pk_fma_f32 v[100:101], v[74:75], v[0:1], v[100:101]
	v_pk_fma_f32 v[104:105], v[58:59], v[2:3], v[104:105]
	v_pk_fma_f32 v[108:109], v[70:71], v[0:1], v[108:109]
	v_pk_fma_f32 v[112:113], v[38:39], v[2:3], v[112:113]
	v_pk_fma_f32 v[116:117], v[66:67], v[0:1], v[116:117]
	v_pk_fma_f32 v[80:81], v[34:35], v[2:3], v[80:81]
	ds_read_b128 v[0:3], v134 offset:51200
	v_pk_fma_f32 v[82:83], v[56:57], v[120:121], v[82:83]
	v_pk_fma_f32 v[110:111], v[36:37], v[120:121], v[110:111]
	v_pk_fma_f32 v[118:119], v[32:33], v[120:121], v[118:119]
	s_waitcnt lgkmcnt(0)
	v_lshlrev_b32_e32 v62, 16, v0
	v_and_b32_e32 v63, 0xffff0000, v0
	v_lshlrev_b32_e32 v0, 16, v1
	v_and_b32_e32 v1, 0xffff0000, v1
	v_lshlrev_b32_e32 v120, 16, v2
	v_and_b32_e32 v121, 0xffff0000, v2
	v_lshlrev_b32_e32 v2, 16, v3
	v_and_b32_e32 v3, 0xffff0000, v3
	s_waitcnt vmcnt(8)
	v_pk_fma_f32 v[102:103], v[76:77], v[62:63], v[102:103]
	v_pk_fma_f32 v[100:101], v[78:79], v[0:1], v[100:101]
	v_pk_fma_f32 v[104:105], v[50:51], v[2:3], v[104:105]
	v_pk_fma_f32 v[106:107], v[72:73], v[62:63], v[106:107]
	v_pk_fma_f32 v[108:109], v[74:75], v[0:1], v[108:109]
	v_pk_fma_f32 v[112:113], v[58:59], v[2:3], v[112:113]
	v_pk_fma_f32 v[114:115], v[68:69], v[62:63], v[114:115]
	v_pk_fma_f32 v[116:117], v[70:71], v[0:1], v[116:117]
	v_pk_fma_f32 v[80:81], v[38:39], v[2:3], v[80:81]
	v_pk_fma_f32 v[52:53], v[64:65], v[62:63], v[52:53]
	v_pk_fma_f32 v[60:61], v[66:67], v[0:1], v[60:61]
	v_pk_fma_f32 v[62:63], v[32:33], v[120:121], v[4:5]
	v_pk_fma_f32 v[64:65], v[34:35], v[2:3], v[6:7]
	global_load_dwordx4 v[4:7], v[54:55], off offset:16
	global_load_dwordx4 v[0:3], v[54:55], off
	v_lshl_add_u64 v[32:33], v[54:55], 0, s[0:1]
	ds_read_b128 v[32:35], v134 offset:53248
	v_pk_fma_f32 v[82:83], v[48:49], v[120:121], v[82:83]
	v_pk_fma_f32 v[110:111], v[56:57], v[120:121], v[110:111]
	v_pk_fma_f32 v[118:119], v[36:37], v[120:121], v[118:119]
	s_waitcnt lgkmcnt(0)
	v_lshlrev_b32_e32 v54, 16, v32
	v_and_b32_e32 v55, 0xffff0000, v32
	v_lshlrev_b32_e32 v32, 16, v33
	v_and_b32_e32 v33, 0xffff0000, v33
	v_lshlrev_b32_e32 v66, 16, v34
	v_and_b32_e32 v67, 0xffff0000, v34
	v_lshlrev_b32_e32 v34, 16, v35
	v_and_b32_e32 v35, 0xffff0000, v35
	s_waitcnt vmcnt(8)
	v_pk_fma_f32 v[102:103], v[40:41], v[54:55], v[102:103]
	v_pk_fma_f32 v[100:101], v[42:43], v[32:33], v[100:101]
	v_pk_fma_f32 v[104:105], v[30:31], v[34:35], v[104:105]
	v_pk_fma_f32 v[106:107], v[76:77], v[54:55], v[106:107]
	v_pk_fma_f32 v[108:109], v[78:79], v[32:33], v[108:109]
	v_pk_fma_f32 v[112:113], v[50:51], v[34:35], v[112:113]
	v_pk_fma_f32 v[114:115], v[72:73], v[54:55], v[114:115]
	v_pk_fma_f32 v[116:117], v[74:75], v[32:33], v[116:117]
	v_pk_fma_f32 v[80:81], v[58:59], v[34:35], v[80:81]
	v_pk_fma_f32 v[52:53], v[68:69], v[54:55], v[52:53]
	v_pk_fma_f32 v[54:55], v[70:71], v[32:33], v[60:61]
	v_pk_fma_f32 v[38:39], v[38:39], v[34:35], v[64:65]
	ds_read_b128 v[32:35], v134 offset:55296
	v_pk_fma_f32 v[36:37], v[36:37], v[66:67], v[62:63]
	v_pk_fma_f32 v[82:83], v[28:29], v[66:67], v[82:83]
	v_pk_fma_f32 v[110:111], v[48:49], v[66:67], v[110:111]
	s_waitcnt lgkmcnt(0)
	v_lshlrev_b32_e32 v60, 16, v32
	v_and_b32_e32 v61, 0xffff0000, v32
	v_lshlrev_b32_e32 v32, 16, v33
	v_and_b32_e32 v33, 0xffff0000, v33
	v_lshlrev_b32_e32 v62, 16, v34
	v_and_b32_e32 v63, 0xffff0000, v34
	v_lshlrev_b32_e32 v34, 16, v35
	v_and_b32_e32 v35, 0xffff0000, v35
	v_pk_fma_f32 v[118:119], v[56:57], v[66:67], v[118:119]
	s_waitcnt vmcnt(6)
	v_pk_fma_f32 v[66:67], v[46:47], v[32:33], v[100:101]
	v_pk_fma_f32 v[70:71], v[26:27], v[34:35], v[104:105]
	v_pk_fma_f32 v[100:101], v[42:43], v[32:33], v[108:109]
	v_pk_fma_f32 v[104:105], v[30:31], v[34:35], v[112:113]
	v_pk_fma_f32 v[108:109], v[78:79], v[32:33], v[116:117]
	v_pk_fma_f32 v[80:81], v[50:51], v[34:35], v[80:81]
	v_pk_fma_f32 v[54:55], v[74:75], v[32:33], v[54:55]
	v_pk_fma_f32 v[38:39], v[58:59], v[34:35], v[38:39]
	ds_read_b128 v[32:35], v134 offset:57344
	v_pk_fma_f32 v[36:37], v[56:57], v[62:63], v[36:37]
	v_pk_fma_f32 v[64:65], v[44:45], v[60:61], v[102:103]
	v_pk_fma_f32 v[68:69], v[24:25], v[62:63], v[82:83]
	s_waitcnt lgkmcnt(0)
	v_lshlrev_b32_e32 v56, 16, v32
	v_and_b32_e32 v57, 0xffff0000, v32
	v_lshlrev_b32_e32 v32, 16, v33
	v_and_b32_e32 v33, 0xffff0000, v33
	v_lshlrev_b32_e32 v58, 16, v34
	v_and_b32_e32 v59, 0xffff0000, v34
	v_lshlrev_b32_e32 v34, 16, v35
	v_and_b32_e32 v35, 0xffff0000, v35
	v_pk_fma_f32 v[102:103], v[28:29], v[62:63], v[110:111]
	v_pk_fma_f32 v[110:111], v[48:49], v[62:63], v[118:119]
	s_waitcnt vmcnt(4)
; #define LAS __attribute__((address_space(3)))
; __device__ __forceinline__ void conv_phase(LAS unsigned char* lds, const bf16_t* U, bf16_t* C, const float* wdw, const float* bdw, const float* lng, const float* lnb,
;                                            int first, int stride, int end, int tid, int wave, int lane) {
;     ...
;             for (int r = 0; r < TT / NWAVES + CW - 1; ++r) {
;                 if (r + 4 < CW) { wt[(r + 4) & 7][0] = wq[0]; wt[(r + 4) & 7][1] = wq[1]; wq += D / 4; asm volatile("" : "+v"(wq)); }
;                 const u32x4 xv = *(const LAS u32x4*)(lds + (4 * wave + r) * 2048 + p * 1024 + lane * 16);
;                 f32x2 x[4];
; #pragma unroll
;                 for (int i = 0; i < 4; ++i) x[i] = (f32x2){__uint_as_float(xv[i] << 16), __uint_as_float(xv[i] & 0xffff0000u)};
; #pragma unroll
;                 for (int j = 0; j < 4; ++j) { const int w = r - j;
;                     if (w >= 0 && w < CW) {
; #pragma unroll
;                         for (int c = 0; c < 4; ++c) { const f32x4 wv = wt[w & 7][c >> 1]; const f32x2 w2 = (c & 1) ? (f32x2){wv.z, wv.w} : (f32x2){wv.x, wv.y}; acc[p][j][c] = __builtin_elementwise_fma(w2, x[c], acc[p][j][c]); } } }
;                 asm volatile("" ::: "memory");
;             }
;             const f32x4 b0 = *(const f32x4*)(bdw + p * 512 + lane * 8), b1 = *(const f32x4*)(bdw + p * 512 + lane * 8 + 4);
; #pragma unroll
;             for (int j = 0; j < 4; ++j) { acc[p][j][0] += (f32x2){b0.x, b0.y}; acc[p][j][1] += (f32x2){b0.z, b0.w}; acc[p][j][2] += (f32x2){b1.x, b1.y}; acc[p][j][3] += (f32x2){b1.z, b1.w}; }
	v_pk_fma_f32 v[62:63], v[22:23], v[32:33], v[66:67]
	v_pk_fma_f32 v[66:67], v[18:19], v[34:35], v[70:71]
	v_pk_fma_f32 v[70:71], v[46:47], v[32:33], v[100:101]
	v_pk_fma_f32 v[74:75], v[26:27], v[34:35], v[104:105]
	v_pk_fma_f32 v[100:101], v[42:43], v[32:33], v[108:109]
	v_pk_fma_f32 v[80:81], v[30:31], v[34:35], v[80:81]
	v_pk_fma_f32 v[54:55], v[78:79], v[32:33], v[54:55]
	v_pk_fma_f32 v[38:39], v[50:51], v[34:35], v[38:39]
	ds_read_b128 v[32:35], v134 offset:59392
	v_pk_fma_f32 v[36:37], v[48:49], v[58:59], v[36:37]
	v_pk_fma_f32 v[52:53], v[72:73], v[60:61], v[52:53]
	v_pk_fma_f32 v[72:73], v[24:25], v[58:59], v[102:103]
	s_waitcnt lgkmcnt(0)
	v_lshlrev_b32_e32 v50, 16, v34
	v_and_b32_e32 v51, 0xffff0000, v34
	v_lshlrev_b32_e32 v34, 16, v35
	v_and_b32_e32 v35, 0xffff0000, v35
	v_pk_fma_f32 v[102:103], v[28:29], v[58:59], v[110:111]
	v_pk_fma_f32 v[36:37], v[28:29], v[50:51], v[36:37]
	v_pk_fma_f32 v[38:39], v[30:31], v[34:35], v[38:39]
	ds_read_b128 v[28:31], v134 offset:61440
	v_pk_fma_f32 v[82:83], v[40:41], v[60:61], v[106:107]
	v_pk_fma_f32 v[106:107], v[76:77], v[60:61], v[114:115]
	v_pk_fma_f32 v[60:61], v[20:21], v[56:57], v[64:65]
	v_pk_fma_f32 v[64:65], v[16:17], v[58:59], v[68:69]
	v_pk_fma_f32 v[68:69], v[44:45], v[56:57], v[82:83]
	v_pk_fma_f32 v[82:83], v[40:41], v[56:57], v[106:107]
	v_pk_fma_f32 v[52:53], v[76:77], v[56:57], v[52:53]
	v_lshlrev_b32_e32 v48, 16, v32
	v_and_b32_e32 v49, 0xffff0000, v32
	v_lshlrev_b32_e32 v32, 16, v33
	v_and_b32_e32 v33, 0xffff0000, v33
	s_waitcnt vmcnt(2)
	v_pk_fma_f32 v[56:57], v[12:13], v[48:49], v[60:61]
	v_pk_fma_f32 v[60:61], v[8:9], v[50:51], v[64:65]
	v_pk_fma_f32 v[64:65], v[20:21], v[48:49], v[68:69]
	v_pk_fma_f32 v[68:69], v[16:17], v[50:51], v[72:73]
	v_pk_fma_f32 v[72:73], v[44:45], v[48:49], v[82:83]
	v_pk_fma_f32 v[76:77], v[24:25], v[50:51], v[102:103]
	v_pk_fma_f32 v[40:41], v[40:41], v[48:49], v[52:53]
	v_pk_fma_f32 v[42:43], v[42:43], v[32:33], v[54:55]
	s_waitcnt lgkmcnt(0)
	v_lshlrev_b32_e32 v48, 16, v28
	v_and_b32_e32 v49, 0xffff0000, v28
	v_lshlrev_b32_e32 v50, 16, v29
	v_and_b32_e32 v51, 0xffff0000, v29
	v_lshlrev_b32_e32 v52, 16, v30
	v_and_b32_e32 v53, 0xffff0000, v30
	v_lshlrev_b32_e32 v54, 16, v31
	v_and_b32_e32 v55, 0xffff0000, v31
	v_pk_fma_f32 v[58:59], v[14:15], v[32:33], v[62:63]
	v_pk_fma_f32 v[62:63], v[10:11], v[34:35], v[66:67]
	v_pk_fma_f32 v[66:67], v[22:23], v[32:33], v[70:71]
	v_pk_fma_f32 v[70:71], v[18:19], v[34:35], v[74:75]
	v_pk_fma_f32 v[74:75], v[46:47], v[32:33], v[100:101]
	v_pk_fma_f32 v[78:79], v[26:27], v[34:35], v[80:81]
	v_pk_fma_f32 v[40:41], v[44:45], v[48:49], v[40:41]
	v_pk_fma_f32 v[42:43], v[46:47], v[50:51], v[42:43]
	v_pk_fma_f32 v[44:45], v[24:25], v[52:53], v[36:37]
	v_pk_fma_f32 v[46:47], v[26:27], v[54:55], v[38:39]
	ds_read_b128 v[24:27], v134 offset:63488
	s_waitcnt vmcnt(0)
	v_pk_fma_f32 v[28:29], v[0:1], v[48:49], v[56:57]
	v_pk_fma_f32 v[30:31], v[2:3], v[50:51], v[58:59]
	v_pk_fma_f32 v[32:33], v[4:5], v[52:53], v[60:61]
	v_pk_fma_f32 v[34:35], v[6:7], v[54:55], v[62:63]
	v_pk_fma_f32 v[56:57], v[12:13], v[48:49], v[64:65]
	v_pk_fma_f32 v[58:59], v[14:15], v[50:51], v[66:67]
	v_pk_fma_f32 v[60:61], v[8:9], v[52:53], v[68:69]
	v_pk_fma_f32 v[62:63], v[10:11], v[54:55], v[70:71]
	v_pk_fma_f32 v[64:65], v[20:21], v[48:49], v[72:73]
	v_pk_fma_f32 v[66:67], v[22:23], v[50:51], v[74:75]
	v_pk_fma_f32 v[68:69], v[16:17], v[52:53], v[76:77]
	v_pk_fma_f32 v[70:71], v[18:19], v[54:55], v[78:79]
	s_waitcnt lgkmcnt(0)
	v_lshlrev_b32_e32 v48, 16, v24
	v_and_b32_e32 v49, 0xffff0000, v24
	v_lshlrev_b32_e32 v50, 16, v25
	v_and_b32_e32 v51, 0xffff0000, v25
	v_lshlrev_b32_e32 v52, 16, v26
	v_and_b32_e32 v53, 0xffff0000, v26
	v_lshlrev_b32_e32 v54, 16, v27
	v_and_b32_e32 v55, 0xffff0000, v27
	v_pk_fma_f32 v[20:21], v[20:21], v[48:49], v[40:41]
	v_pk_fma_f32 v[22:23], v[22:23], v[50:51], v[42:43]
	v_pk_fma_f32 v[40:41], v[16:17], v[52:53], v[44:45]
	v_pk_fma_f32 v[42:43], v[18:19], v[54:55], v[46:47]
	ds_read_b128 v[16:19], v136
	v_pk_fma_f32 v[26:27], v[2:3], v[50:51], v[58:59]
	v_pk_fma_f32 v[38:39], v[6:7], v[54:55], v[62:63]
	v_pk_fma_f32 v[58:59], v[14:15], v[50:51], v[66:67]
	v_pk_fma_f32 v[62:63], v[10:11], v[54:55], v[70:71]
	s_waitcnt lgkmcnt(0)
	v_lshlrev_b32_e32 v44, 16, v16
	v_and_b32_e32 v45, 0xffff0000, v16
	v_lshlrev_b32_e32 v16, 16, v17
	v_and_b32_e32 v17, 0xffff0000, v17
	v_lshlrev_b32_e32 v46, 16, v18
	v_and_b32_e32 v47, 0xffff0000, v18
	v_lshlrev_b32_e32 v18, 16, v19
	v_and_b32_e32 v19, 0xffff0000, v19
	v_pk_fma_f32 v[36:37], v[4:5], v[52:53], v[60:61]
	v_pk_fma_f32 v[60:61], v[8:9], v[52:53], v[68:69]
	v_pk_fma_f32 v[50:51], v[2:3], v[16:17], v[58:59]
	v_pk_fma_f32 v[54:55], v[6:7], v[18:19], v[62:63]
	v_pk_fma_f32 v[14:15], v[14:15], v[16:17], v[22:23]
	v_pk_fma_f32 v[16:17], v[8:9], v[46:47], v[40:41]
	v_pk_fma_f32 v[18:19], v[10:11], v[18:19], v[42:43]
	ds_read_b128 v[8:11], v137
	v_pk_fma_f32 v[24:25], v[0:1], v[48:49], v[56:57]
	v_pk_fma_f32 v[56:57], v[12:13], v[48:49], v[64:65]
	v_pk_fma_f32 v[12:13], v[12:13], v[44:45], v[20:21]
	s_waitcnt lgkmcnt(0)
	v_lshlrev_b32_e32 v20, 16, v8
	v_and_b32_e32 v21, 0xffff0000, v8
	v_lshlrev_b32_e32 v8, 16, v9
	v_and_b32_e32 v9, 0xffff0000, v9
	v_lshlrev_b32_e32 v22, 16, v10
	v_and_b32_e32 v23, 0xffff0000, v10
	v_lshlrev_b32_e32 v10, 16, v11
	v_and_b32_e32 v11, 0xffff0000, v11
	v_pk_fma_f32 v[48:49], v[0:1], v[44:45], v[56:57]
	v_pk_fma_f32 v[52:53], v[4:5], v[46:47], v[60:61]
	v_pk_fma_f32 v[10:11], v[6:7], v[10:11], v[18:19]
	v_pk_fma_f32 v[16:17], v[4:5], v[22:23], v[16:17]
	v_pk_fma_f32 v[8:9], v[2:3], v[8:9], v[14:15]
	v_pk_fma_f32 v[12:13], v[0:1], v[20:21], v[12:13]
	global_load_dwordx4 v[0:3], v[86:87], off offset:16
	global_load_dwordx4 v[4:7], v[86:87], off
	s_waitcnt vmcnt(1)
; #define LAS __attribute__((address_space(3)))
; __device__ __forceinline__ void conv_phase(LAS unsigned char* lds, const bf16_t* U, bf16_t* C, const float* wdw, const float* bdw, const float* lng, const float* lnb,
;                                            int first, int stride, int end, int tid, int wave, int lane) {
;     ...
;         for (int p = 0; p < 2; ++p) {
; #pragma unroll
;             for (int j = 0; j < 4; ++j)
; #pragma unroll
;                 for (int c = 0; c < 4; ++c) acc[p][j][c] = (f32x2){0.f, 0.f};
;             f32x4 wt[8][2];
;             typedef const __attribute__((address_space(1))) f32x4 gf32x4;
;             const gf32x4* wq = (const gf32x4*)(wdw + p * 512 + lane * 8);
; #pragma unroll
;             for (int t = 0; t < 4; ++t) { wt[t][0] = wq[0]; wt[t][1] = wq[1]; wq += D / 4; asm volatile("" : "+v"(wq)); }
; #pragma unroll
;             for (int r = 0; r < TT / NWAVES + CW - 1; ++r) {
;                 if (r + 4 < CW) { wt[(r + 4) & 7][0] = wq[0]; wt[(r + 4) & 7][1] = wq[1]; wq += D / 4; asm volatile("" : "+v"(wq)); }
;                 const u32x4 xv = *(const LAS u32x4*)(lds + (4 * wave + r) * 2048 + p * 1024 + lane * 16);
;                 f32x2 x[4];
; #pragma unroll
;                 for (int i = 0; i < 4; ++i) x[i] = (f32x2){__uint_as_float(xv[i] << 16), __uint_as_float(xv[i] & 0xffff0000u)};
; #pragma unroll
;                 for (int j = 0; j < 4; ++j) { const int w = r - j;
;                     if (w >= 0 && w < CW) {
; #pragma unroll
;                         for (int c = 0; c < 4; ++c) { const f32x4 wv = wt[w & 7][c >> 1]; const f32x2 w2 = (c & 1) ? (f32x2){wv.z, wv.w} : (f32x2){wv.x, wv.y}; acc[p][j][c] = __builtin_elementwise_fma(w2, x[c], acc[p][j][c]); } } }
;                 asm volatile("" ::: "memory");
;             }
;             const f32x4 b0 = *(const f32x4*)(bdw + p * 512 + lane * 8), b1 = *(const f32x4*)(bdw + p * 512 + lane * 8 + 4);
; #pragma unroll
;             for (int j = 0; j < 4; ++j) { acc[p][j][0] += (f32x2){b0.x, b0.y}; acc[p][j][1] += (f32x2){b0.z, b0.w}; acc[p][j][2] += (f32x2){b1.x, b1.y}; acc[p][j][3] += (f32x2){b1.z, b1.w}; }
	v_pk_add_f32 v[118:119], v[36:37], v[0:1]
	s_waitcnt vmcnt(0)
	v_pk_add_f32 v[128:129], v[28:29], v[4:5]
	v_pk_add_f32 v[130:131], v[30:31], v[6:7]
	v_pk_add_f32 v[120:121], v[24:25], v[4:5]
	v_pk_add_f32 v[122:123], v[26:27], v[6:7]
	v_pk_add_f32 v[116:117], v[38:39], v[2:3]
	v_pk_add_f32 v[112:113], v[4:5], v[48:49]
	v_pk_add_f32 v[114:115], v[6:7], v[50:51]
	v_pk_add_f32 v[104:105], v[4:5], v[12:13]
	v_pk_add_f32 v[106:107], v[6:7], v[8:9]
	global_load_dwordx4 v[4:7], v[84:85], off offset:2064
	global_load_dwordx4 v[36:39], v[84:85], off offset:2048
	v_pk_add_f32 v[126:127], v[32:33], v[0:1]
	v_pk_add_f32 v[110:111], v[0:1], v[52:53]
	v_pk_add_f32 v[102:103], v[0:1], v[16:17]
	v_mov_b64_e32 v[0:1], v[98:99]
	v_pk_add_f32 v[100:101], v[2:3], v[10:11]
	global_load_dwordx4 v[8:11], v[0:1], off offset:16
	global_load_dwordx4 v[12:15], v[0:1], off
	v_lshl_add_u64 v[0:1], v[0:1], 0, s[0:1]
	global_load_dwordx4 v[44:47], v[0:1], off offset:16
	global_load_dwordx4 v[64:67], v[0:1], off
	v_lshl_add_u64 v[0:1], v[0:1], 0, s[0:1]
	global_load_dwordx4 v[16:19], v[0:1], off offset:16
	global_load_dwordx4 v[48:51], v[0:1], off
	v_lshl_add_u64 v[0:1], v[0:1], 0, s[0:1]
	v_pk_add_f32 v[108:109], v[2:3], v[54:55]
	global_load_dwordx4 v[20:23], v[0:1], off offset:16
	global_load_dwordx4 v[52:55], v[0:1], off
	v_lshl_add_u64 v[28:29], v[0:1], 0, s[0:1]
	v_pk_add_f32 v[124:125], v[34:35], v[2:3]
	ds_read_b128 v[0:3], v134 offset:1024
	v_lshl_add_u64 v[42:43], v[28:29], 0, s[0:1]
	s_waitcnt lgkmcnt(0)
	v_lshlrev_b32_e32 v24, 16, v3
	v_and_b32_e32 v25, 0xffff0000, v3
	v_lshlrev_b32_e32 v26, 16, v2
	v_and_b32_e32 v27, 0xffff0000, v2
	v_lshlrev_b32_e32 v2, 16, v1
	v_and_b32_e32 v3, 0xffff0000, v1
	v_lshlrev_b32_e32 v30, 16, v0
	v_and_b32_e32 v31, 0xffff0000, v0
	s_waitcnt vmcnt(9)
	v_pk_fma_f32 v[34:35], v[4:5], v[26:27], 0 op_sel_hi:[1,1,0]
	v_pk_fma_f32 v[40:41], v[6:7], v[24:25], 0 op_sel_hi:[1,1,0]
	global_load_dwordx4 v[24:27], v[28:29], off offset:16
	global_load_dwordx4 v[56:59], v[28:29], off
	s_waitcnt vmcnt(10)
	v_pk_fma_f32 v[32:33], v[38:39], v[2:3], 0 op_sel_hi:[1,1,0]
	ds_read_b128 v[0:3], v134 offset:3072
	v_pk_fma_f32 v[30:31], v[36:37], v[30:31], 0 op_sel_hi:[1,1,0]
	s_waitcnt lgkmcnt(0)
	v_lshlrev_b32_e32 v28, 16, v0
	v_and_b32_e32 v29, 0xffff0000, v0
	v_lshlrev_b32_e32 v60, 16, v2
	v_and_b32_e32 v61, 0xffff0000, v2
	v_lshlrev_b32_e32 v0, 16, v1
	v_and_b32_e32 v1, 0xffff0000, v1
	v_lshlrev_b32_e32 v2, 16, v3
	v_and_b32_e32 v3, 0xffff0000, v3
	s_waitcnt vmcnt(8)
	v_pk_fma_f32 v[68:69], v[12:13], v[28:29], v[30:31]
	v_pk_fma_f32 v[34:35], v[8:9], v[60:61], v[34:35]
	v_pk_fma_f32 v[70:71], v[36:37], v[28:29], 0 op_sel_hi:[1,1,0]
	v_pk_fma_f32 v[74:75], v[4:5], v[60:61], 0 op_sel_hi:[1,1,0]
	global_load_dwordx4 v[28:31], v[42:43], off offset:16
	global_load_dwordx4 v[60:63], v[42:43], off
	v_lshl_add_u64 v[42:43], v[42:43], 0, s[0:1]
	v_pk_fma_f32 v[32:33], v[14:15], v[0:1], v[32:33]
	v_pk_fma_f32 v[40:41], v[10:11], v[2:3], v[40:41]
	v_pk_fma_f32 v[72:73], v[38:39], v[0:1], 0 op_sel_hi:[1,1,0]
	v_pk_fma_f32 v[76:77], v[6:7], v[2:3], 0 op_sel_hi:[1,1,0]
	ds_read_b128 v[0:3], v134 offset:5120
	v_lshl_add_u64 v[150:151], v[42:43], 0, s[0:1]
	s_waitcnt lgkmcnt(0)
	v_lshlrev_b32_e32 v78, 16, v0
	v_and_b32_e32 v79, 0xffff0000, v0
	v_lshlrev_b32_e32 v0, 16, v1
	v_and_b32_e32 v1, 0xffff0000, v1
	v_lshlrev_b32_e32 v80, 16, v2
	v_and_b32_e32 v81, 0xffff0000, v2
	v_lshlrev_b32_e32 v2, 16, v3
	v_and_b32_e32 v3, 0xffff0000, v3
	s_waitcnt vmcnt(8)
	v_pk_fma_f32 v[82:83], v[66:67], v[0:1], v[32:33]
	v_pk_fma_f32 v[142:143], v[44:45], v[80:81], v[34:35]
	v_pk_fma_f32 v[144:145], v[46:47], v[2:3], v[40:41]
	v_pk_fma_f32 v[72:73], v[14:15], v[0:1], v[72:73]
	v_pk_fma_f32 v[76:77], v[10:11], v[2:3], v[76:77]
	v_pk_fma_f32 v[146:147], v[38:39], v[0:1], 0 op_sel_hi:[1,1,0]
	v_pk_fma_f32 v[148:149], v[6:7], v[2:3], 0 op_sel_hi:[1,1,0]
	global_load_dwordx4 v[0:3], v[42:43], off offset:16
	global_load_dwordx4 v[32:35], v[42:43], off
	ds_read_b128 v[40:43], v134 offset:7168
	v_pk_fma_f32 v[68:69], v[64:65], v[78:79], v[68:69]
	v_pk_fma_f32 v[70:71], v[12:13], v[78:79], v[70:71]
	v_pk_fma_f32 v[74:75], v[8:9], v[80:81], v[74:75]
	v_pk_fma_f32 v[78:79], v[36:37], v[78:79], 0 op_sel_hi:[1,1,0]
	v_pk_fma_f32 v[80:81], v[4:5], v[80:81], 0 op_sel_hi:[1,1,0]
	s_waitcnt lgkmcnt(0)
	v_lshlrev_b32_e32 v152, 16, v40
	v_and_b32_e32 v153, 0xffff0000, v40
	v_lshlrev_b32_e32 v40, 16, v41
	v_and_b32_e32 v41, 0xffff0000, v41
	v_lshlrev_b32_e32 v154, 16, v42
	v_and_b32_e32 v155, 0xffff0000, v42
	v_lshlrev_b32_e32 v42, 16, v43
	v_and_b32_e32 v43, 0xffff0000, v43
	s_waitcnt vmcnt(8)
	v_pk_fma_f32 v[68:69], v[48:49], v[152:153], v[68:69]
	v_pk_fma_f32 v[142:143], v[16:17], v[154:155], v[142:143]
	v_pk_fma_f32 v[70:71], v[64:65], v[152:153], v[70:71]
	v_pk_fma_f32 v[74:75], v[44:45], v[154:155], v[74:75]
	v_pk_fma_f32 v[78:79], v[12:13], v[152:153], v[78:79]
	v_pk_fma_f32 v[80:81], v[8:9], v[154:155], v[80:81]
	v_pk_fma_f32 v[152:153], v[36:37], v[152:153], 0 op_sel_hi:[1,1,0]
	v_pk_fma_f32 v[156:157], v[38:39], v[40:41], 0 op_sel_hi:[1,1,0]
	v_pk_fma_f32 v[154:155], v[4:5], v[154:155], 0 op_sel_hi:[1,1,0]
	v_pk_fma_f32 v[158:159], v[6:7], v[42:43], 0 op_sel_hi:[1,1,0]
	global_load_dwordx4 v[4:7], v[150:151], off offset:16
	global_load_dwordx4 v[36:39], v[150:151], off
	v_lshl_add_u64 v[150:151], v[150:151], 0, s[0:1]
	v_pk_fma_f32 v[82:83], v[50:51], v[40:41], v[82:83]
	v_pk_fma_f32 v[144:145], v[18:19], v[42:43], v[144:145]
	v_pk_fma_f32 v[72:73], v[66:67], v[40:41], v[72:73]
	v_pk_fma_f32 v[76:77], v[46:47], v[42:43], v[76:77]
	v_pk_fma_f32 v[146:147], v[14:15], v[40:41], v[146:147]
	v_pk_fma_f32 v[148:149], v[10:11], v[42:43], v[148:149]
	ds_read_b128 v[40:43], v134 offset:9216
	s_waitcnt lgkmcnt(0)
; #define LAS __attribute__((address_space(3)))
; __device__ __forceinline__ void conv_phase(LAS unsigned char* lds, const bf16_t* U, bf16_t* C, const float* wdw, const float* bdw, const float* lng, const float* lnb,
;                                            int first, int stride, int end, int tid, int wave, int lane) {
;     ...
;             for (int r = 0; r < TT / NWAVES + CW - 1; ++r) {
;                 if (r + 4 < CW) { wt[(r + 4) & 7][0] = wq[0]; wt[(r + 4) & 7][1] = wq[1]; wq += D / 4; asm volatile("" : "+v"(wq)); }
;                 const u32x4 xv = *(const LAS u32x4*)(lds + (4 * wave + r) * 2048 + p * 1024 + lane * 16);
;                 f32x2 x[4];
; #pragma unroll
;                 for (int i = 0; i < 4; ++i) x[i] = (f32x2){__uint_as_float(xv[i] << 16), __uint_as_float(xv[i] & 0xffff0000u)};
; #pragma unroll
;                 for (int j = 0; j < 4; ++j) { const int w = r - j;
;                     if (w >= 0 && w < CW) {
; #pragma unroll
;                         for (int c = 0; c < 4; ++c) { const f32x4 wv = wt[w & 7][c >> 1]; const f32x2 w2 = (c & 1) ? (f32x2){wv.z, wv.w} : (f32x2){wv.x, wv.y}; acc[p][j][c] = __builtin_elementwise_fma(w2, x[c], acc[p][j][c]); } } }
;                 asm volatile("" ::: "memory");
;             }
	v_lshlrev_b32_e32 v160, 16, v40
	v_and_b32_e32 v161, 0xffff0000, v40
	v_lshlrev_b32_e32 v40, 16, v41
	v_and_b32_e32 v41, 0xffff0000, v41
	v_lshlrev_b32_e32 v162, 16, v42
	v_and_b32_e32 v163, 0xffff0000, v42
	v_lshlrev_b32_e32 v42, 16, v43
	v_and_b32_e32 v43, 0xffff0000, v43
	s_waitcnt vmcnt(8)
	v_pk_fma_f32 v[82:83], v[54:55], v[40:41], v[82:83]
	v_pk_fma_f32 v[144:145], v[22:23], v[42:43], v[144:145]
	v_pk_fma_f32 v[72:73], v[50:51], v[40:41], v[72:73]
	v_pk_fma_f32 v[76:77], v[18:19], v[42:43], v[76:77]
	v_pk_fma_f32 v[146:147], v[66:67], v[40:41], v[146:147]
	v_pk_fma_f32 v[148:149], v[46:47], v[42:43], v[148:149]
	v_pk_fma_f32 v[156:157], v[14:15], v[40:41], v[156:157]
	v_pk_fma_f32 v[154:155], v[8:9], v[162:163], v[154:155]
	v_pk_fma_f32 v[158:159], v[10:11], v[42:43], v[158:159]
	global_load_dwordx4 v[8:11], v[150:151], off offset:16
	global_load_dwordx4 v[40:43], v[150:151], off
	v_lshl_add_u64 v[150:151], v[150:151], 0, s[0:1]
	v_pk_fma_f32 v[152:153], v[12:13], v[160:161], v[152:153]
	ds_read_b128 v[12:15], v134 offset:11264
	v_pk_fma_f32 v[68:69], v[52:53], v[160:161], v[68:69]
	v_pk_fma_f32 v[142:143], v[20:21], v[162:163], v[142:143]
	v_pk_fma_f32 v[70:71], v[48:49], v[160:161], v[70:71]
	v_pk_fma_f32 v[74:75], v[16:17], v[162:163], v[74:75]
	v_pk_fma_f32 v[78:79], v[64:65], v[160:161], v[78:79]
	v_pk_fma_f32 v[80:81], v[44:45], v[162:163], v[80:81]
	s_waitcnt lgkmcnt(0)
	v_lshlrev_b32_e32 v160, 16, v12
	v_and_b32_e32 v161, 0xffff0000, v12
	v_lshlrev_b32_e32 v12, 16, v13
	v_and_b32_e32 v13, 0xffff0000, v13
	v_lshlrev_b32_e32 v162, 16, v14
	v_and_b32_e32 v163, 0xffff0000, v14
	v_lshlrev_b32_e32 v14, 16, v15
	v_and_b32_e32 v15, 0xffff0000, v15
	s_waitcnt vmcnt(8)
	v_pk_fma_f32 v[82:83], v[58:59], v[12:13], v[82:83]
	v_pk_fma_f32 v[144:145], v[26:27], v[14:15], v[144:145]
	v_pk_fma_f32 v[72:73], v[54:55], v[12:13], v[72:73]
	v_pk_fma_f32 v[76:77], v[22:23], v[14:15], v[76:77]
	v_pk_fma_f32 v[146:147], v[50:51], v[12:13], v[146:147]
	v_pk_fma_f32 v[148:149], v[18:19], v[14:15], v[148:149]
	v_pk_fma_f32 v[156:157], v[66:67], v[12:13], v[156:157]
	v_pk_fma_f32 v[154:155], v[44:45], v[162:163], v[154:155]
	v_pk_fma_f32 v[158:159], v[46:47], v[14:15], v[158:159]
	global_load_dwordx4 v[12:15], v[150:151], off offset:16
	global_load_dwordx4 v[44:47], v[150:151], off
	v_lshl_add_u64 v[150:151], v[150:151], 0, s[0:1]
	v_pk_fma_f32 v[152:153], v[64:65], v[160:161], v[152:153]
	ds_read_b128 v[64:67], v134 offset:13312
	v_pk_fma_f32 v[68:69], v[56:57], v[160:161], v[68:69]
	v_pk_fma_f32 v[142:143], v[24:25], v[162:163], v[142:143]
	v_pk_fma_f32 v[70:71], v[52:53], v[160:161], v[70:71]
	v_pk_fma_f32 v[74:75], v[20:21], v[162:163], v[74:75]
	v_pk_fma_f32 v[78:79], v[48:49], v[160:161], v[78:79]
	v_pk_fma_f32 v[80:81], v[16:17], v[162:163], v[80:81]
	s_waitcnt lgkmcnt(0)
	v_lshlrev_b32_e32 v160, 16, v64
	v_and_b32_e32 v161, 0xffff0000, v64
	v_lshlrev_b32_e32 v64, 16, v65
	v_and_b32_e32 v65, 0xffff0000, v65
	v_lshlrev_b32_e32 v162, 16, v66
	v_and_b32_e32 v163, 0xffff0000, v66
	v_lshlrev_b32_e32 v66, 16, v67
	v_and_b32_e32 v67, 0xffff0000, v67
	v_pk_fma_f32 v[152:153], v[48:49], v[160:161], v[152:153]
	v_pk_fma_f32 v[156:157], v[50:51], v[64:65], v[156:157]
	v_pk_fma_f32 v[154:155], v[16:17], v[162:163], v[154:155]
	v_pk_fma_f32 v[158:159], v[18:19], v[66:67], v[158:159]
	global_load_dwordx4 v[16:19], v[150:151], off offset:16
	global_load_dwordx4 v[48:51], v[150:151], off
	v_lshl_add_u64 v[150:151], v[150:151], 0, s[0:1]
	s_waitcnt vmcnt(10)
	v_pk_fma_f32 v[82:83], v[62:63], v[64:65], v[82:83]
	v_pk_fma_f32 v[144:145], v[30:31], v[66:67], v[144:145]
	v_pk_fma_f32 v[72:73], v[58:59], v[64:65], v[72:73]
	v_pk_fma_f32 v[76:77], v[26:27], v[66:67], v[76:77]
	v_pk_fma_f32 v[146:147], v[54:55], v[64:65], v[146:147]
	v_pk_fma_f32 v[148:149], v[22:23], v[66:67], v[148:149]
	ds_read_b128 v[64:67], v134 offset:15360
	v_pk_fma_f32 v[68:69], v[60:61], v[160:161], v[68:69]
	v_pk_fma_f32 v[142:143], v[28:29], v[162:163], v[142:143]
	v_pk_fma_f32 v[70:71], v[56:57], v[160:161], v[70:71]
	v_pk_fma_f32 v[74:75], v[24:25], v[162:163], v[74:75]
	v_pk_fma_f32 v[78:79], v[52:53], v[160:161], v[78:79]
	v_pk_fma_f32 v[80:81], v[20:21], v[162:163], v[80:81]
	s_waitcnt lgkmcnt(0)
	v_lshlrev_b32_e32 v160, 16, v64
	v_and_b32_e32 v161, 0xffff0000, v64
	v_lshlrev_b32_e32 v64, 16, v65
	v_and_b32_e32 v65, 0xffff0000, v65
	v_lshlrev_b32_e32 v162, 16, v66
	v_and_b32_e32 v163, 0xffff0000, v66
	v_lshlrev_b32_e32 v66, 16, v67
	v_and_b32_e32 v67, 0xffff0000, v67
	v_pk_fma_f32 v[152:153], v[52:53], v[160:161], v[152:153]
	v_pk_fma_f32 v[156:157], v[54:55], v[64:65], v[156:157]
	v_pk_fma_f32 v[154:155], v[20:21], v[162:163], v[154:155]
	v_pk_fma_f32 v[158:159], v[22:23], v[66:67], v[158:159]
	global_load_dwordx4 v[20:23], v[150:151], off offset:16
	global_load_dwordx4 v[52:55], v[150:151], off
	v_lshl_add_u64 v[150:151], v[150:151], 0, s[0:1]
	s_waitcnt vmcnt(10)
	v_pk_fma_f32 v[82:83], v[34:35], v[64:65], v[82:83]
	v_pk_fma_f32 v[144:145], v[2:3], v[66:67], v[144:145]
	v_pk_fma_f32 v[72:73], v[62:63], v[64:65], v[72:73]
	v_pk_fma_f32 v[76:77], v[30:31], v[66:67], v[76:77]
	v_pk_fma_f32 v[146:147], v[58:59], v[64:65], v[146:147]
	v_pk_fma_f32 v[148:149], v[26:27], v[66:67], v[148:149]
	ds_read_b128 v[64:67], v134 offset:17408
	v_pk_fma_f32 v[68:69], v[32:33], v[160:161], v[68:69]
	v_pk_fma_f32 v[142:143], v[0:1], v[162:163], v[142:143]
	v_pk_fma_f32 v[70:71], v[60:61], v[160:161], v[70:71]
	v_pk_fma_f32 v[74:75], v[28:29], v[162:163], v[74:75]
	v_pk_fma_f32 v[78:79], v[56:57], v[160:161], v[78:79]
	v_pk_fma_f32 v[80:81], v[24:25], v[162:163], v[80:81]
	s_waitcnt lgkmcnt(0)
; #define LAS __attribute__((address_space(3)))
; __device__ __forceinline__ void conv_phase(LAS unsigned char* lds, const bf16_t* U, bf16_t* C, const float* wdw, const float* bdw, const float* lng, const float* lnb,
;                                            int first, int stride, int end, int tid, int wave, int lane) {
;     ...
;             for (int r = 0; r < TT / NWAVES + CW - 1; ++r) {
;                 if (r + 4 < CW) { wt[(r + 4) & 7][0] = wq[0]; wt[(r + 4) & 7][1] = wq[1]; wq += D / 4; asm volatile("" : "+v"(wq)); }
;                 const u32x4 xv = *(const LAS u32x4*)(lds + (4 * wave + r) * 2048 + p * 1024 + lane * 16);
;                 f32x2 x[4];
; #pragma unroll
;                 for (int i = 0; i < 4; ++i) x[i] = (f32x2){__uint_as_float(xv[i] << 16), __uint_as_float(xv[i] & 0xffff0000u)};
; #pragma unroll
;                 for (int j = 0; j < 4; ++j) { const int w = r - j;
;                     if (w >= 0 && w < CW) {
; #pragma unroll
;                         for (int c = 0; c < 4; ++c) { const f32x4 wv = wt[w & 7][c >> 1]; const f32x2 w2 = (c & 1) ? (f32x2){wv.z, wv.w} : (f32x2){wv.x, wv.y}; acc[p][j][c] = __builtin_elementwise_fma(w2, x[c], acc[p][j][c]); } } }
;                 asm volatile("" ::: "memory");
;             }
	v_lshlrev_b32_e32 v160, 16, v64
	v_and_b32_e32 v161, 0xffff0000, v64
	v_lshlrev_b32_e32 v64, 16, v65
	v_and_b32_e32 v65, 0xffff0000, v65
	v_lshlrev_b32_e32 v162, 16, v66
	v_and_b32_e32 v163, 0xffff0000, v66
	v_lshlrev_b32_e32 v66, 16, v67
	v_and_b32_e32 v67, 0xffff0000, v67
	v_pk_fma_f32 v[152:153], v[56:57], v[160:161], v[152:153]
	v_pk_fma_f32 v[156:157], v[58:59], v[64:65], v[156:157]
	v_pk_fma_f32 v[154:155], v[24:25], v[162:163], v[154:155]
	v_pk_fma_f32 v[158:159], v[26:27], v[66:67], v[158:159]
	global_load_dwordx4 v[24:27], v[150:151], off offset:16
	global_load_dwordx4 v[56:59], v[150:151], off
	v_lshl_add_u64 v[150:151], v[150:151], 0, s[0:1]
	s_waitcnt vmcnt(10)
	v_pk_fma_f32 v[82:83], v[38:39], v[64:65], v[82:83]
	v_pk_fma_f32 v[144:145], v[6:7], v[66:67], v[144:145]
	v_pk_fma_f32 v[72:73], v[34:35], v[64:65], v[72:73]
	v_pk_fma_f32 v[76:77], v[2:3], v[66:67], v[76:77]
	v_pk_fma_f32 v[146:147], v[62:63], v[64:65], v[146:147]
	v_pk_fma_f32 v[148:149], v[30:31], v[66:67], v[148:149]
	ds_read_b128 v[64:67], v134 offset:19456
	v_pk_fma_f32 v[68:69], v[36:37], v[160:161], v[68:69]
	v_pk_fma_f32 v[142:143], v[4:5], v[162:163], v[142:143]
	v_pk_fma_f32 v[70:71], v[32:33], v[160:161], v[70:71]
	v_pk_fma_f32 v[74:75], v[0:1], v[162:163], v[74:75]
	v_pk_fma_f32 v[78:79], v[60:61], v[160:161], v[78:79]
	v_pk_fma_f32 v[80:81], v[28:29], v[162:163], v[80:81]
	s_waitcnt lgkmcnt(0)
	v_lshlrev_b32_e32 v160, 16, v64
	v_and_b32_e32 v161, 0xffff0000, v64
	v_lshlrev_b32_e32 v64, 16, v65
	v_and_b32_e32 v65, 0xffff0000, v65
	v_lshlrev_b32_e32 v162, 16, v66
	v_and_b32_e32 v163, 0xffff0000, v66
	v_lshlrev_b32_e32 v66, 16, v67
	v_and_b32_e32 v67, 0xffff0000, v67
	v_pk_fma_f32 v[152:153], v[60:61], v[160:161], v[152:153]
	v_pk_fma_f32 v[156:157], v[62:63], v[64:65], v[156:157]
	v_pk_fma_f32 v[154:155], v[28:29], v[162:163], v[154:155]
	v_pk_fma_f32 v[158:159], v[30:31], v[66:67], v[158:159]
	global_load_dwordx4 v[28:31], v[150:151], off offset:16
	global_load_dwordx4 v[60:63], v[150:151], off
	v_lshl_add_u64 v[150:151], v[150:151], 0, s[0:1]
	s_waitcnt vmcnt(10)
	v_pk_fma_f32 v[82:83], v[42:43], v[64:65], v[82:83]
	v_pk_fma_f32 v[144:145], v[10:11], v[66:67], v[144:145]
	v_pk_fma_f32 v[72:73], v[38:39], v[64:65], v[72:73]
	v_pk_fma_f32 v[76:77], v[6:7], v[66:67], v[76:77]
	v_pk_fma_f32 v[146:147], v[34:35], v[64:65], v[146:147]
	v_pk_fma_f32 v[148:149], v[2:3], v[66:67], v[148:149]
	ds_read_b128 v[64:67], v134 offset:21504
	v_pk_fma_f32 v[68:69], v[40:41], v[160:161], v[68:69]
	v_pk_fma_f32 v[142:143], v[8:9], v[162:163], v[142:143]
	v_pk_fma_f32 v[70:71], v[36:37], v[160:161], v[70:71]
	v_pk_fma_f32 v[74:75], v[4:5], v[162:163], v[74:75]
	v_pk_fma_f32 v[78:79], v[32:33], v[160:161], v[78:79]
	v_pk_fma_f32 v[80:81], v[0:1], v[162:163], v[80:81]
	s_waitcnt lgkmcnt(0)
	v_lshlrev_b32_e32 v160, 16, v64
	v_and_b32_e32 v161, 0xffff0000, v64
	v_lshlrev_b32_e32 v64, 16, v65
	v_and_b32_e32 v65, 0xffff0000, v65
	v_lshlrev_b32_e32 v162, 16, v66
	v_and_b32_e32 v163, 0xffff0000, v66
	v_lshlrev_b32_e32 v66, 16, v67
	v_and_b32_e32 v67, 0xffff0000, v67
	v_pk_fma_f32 v[152:153], v[32:33], v[160:161], v[152:153]
	v_pk_fma_f32 v[156:157], v[34:35], v[64:65], v[156:157]
	v_pk_fma_f32 v[154:155], v[0:1], v[162:163], v[154:155]
	v_pk_fma_f32 v[158:159], v[2:3], v[66:67], v[158:159]
	global_load_dwordx4 v[0:3], v[150:151], off offset:16
	global_load_dwordx4 v[32:35], v[150:151], off
	v_lshl_add_u64 v[150:151], v[150:151], 0, s[0:1]
	s_waitcnt vmcnt(10)
	v_pk_fma_f32 v[82:83], v[46:47], v[64:65], v[82:83]
	v_pk_fma_f32 v[144:145], v[14:15], v[66:67], v[144:145]
	v_pk_fma_f32 v[72:73], v[42:43], v[64:65], v[72:73]
	v_pk_fma_f32 v[76:77], v[10:11], v[66:67], v[76:77]
	v_pk_fma_f32 v[146:147], v[38:39], v[64:65], v[146:147]
	v_pk_fma_f32 v[148:149], v[6:7], v[66:67], v[148:149]
	ds_read_b128 v[64:67], v134 offset:23552
	v_pk_fma_f32 v[68:69], v[44:45], v[160:161], v[68:69]
	v_pk_fma_f32 v[142:143], v[12:13], v[162:163], v[142:143]
	v_pk_fma_f32 v[70:71], v[40:41], v[160:161], v[70:71]
	v_pk_fma_f32 v[74:75], v[8:9], v[162:163], v[74:75]
	v_pk_fma_f32 v[78:79], v[36:37], v[160:161], v[78:79]
	v_pk_fma_f32 v[80:81], v[4:5], v[162:163], v[80:81]
	s_waitcnt lgkmcnt(0)
	v_lshlrev_b32_e32 v160, 16, v64
	v_and_b32_e32 v161, 0xffff0000, v64
	v_lshlrev_b32_e32 v64, 16, v65
	v_and_b32_e32 v65, 0xffff0000, v65
	v_lshlrev_b32_e32 v162, 16, v66
	v_and_b32_e32 v163, 0xffff0000, v66
	v_lshlrev_b32_e32 v66, 16, v67
	v_and_b32_e32 v67, 0xffff0000, v67
	v_pk_fma_f32 v[152:153], v[36:37], v[160:161], v[152:153]
	v_pk_fma_f32 v[156:157], v[38:39], v[64:65], v[156:157]
	v_pk_fma_f32 v[154:155], v[4:5], v[162:163], v[154:155]
	v_pk_fma_f32 v[158:159], v[6:7], v[66:67], v[158:159]
	global_load_dwordx4 v[4:7], v[150:151], off offset:16
	global_load_dwordx4 v[36:39], v[150:151], off
	v_lshl_add_u64 v[150:151], v[150:151], 0, s[0:1]
	s_waitcnt vmcnt(10)
	v_pk_fma_f32 v[82:83], v[50:51], v[64:65], v[82:83]
	v_pk_fma_f32 v[144:145], v[18:19], v[66:67], v[144:145]
	v_pk_fma_f32 v[72:73], v[46:47], v[64:65], v[72:73]
	v_pk_fma_f32 v[76:77], v[14:15], v[66:67], v[76:77]
	v_pk_fma_f32 v[146:147], v[42:43], v[64:65], v[146:147]
	v_pk_fma_f32 v[148:149], v[10:11], v[66:67], v[148:149]
	ds_read_b128 v[64:67], v134 offset:25600
	v_pk_fma_f32 v[68:69], v[48:49], v[160:161], v[68:69]
	v_pk_fma_f32 v[142:143], v[16:17], v[162:163], v[142:143]
	v_pk_fma_f32 v[70:71], v[44:45], v[160:161], v[70:71]
	v_pk_fma_f32 v[74:75], v[12:13], v[162:163], v[74:75]
	v_pk_fma_f32 v[78:79], v[40:41], v[160:161], v[78:79]
	v_pk_fma_f32 v[80:81], v[8:9], v[162:163], v[80:81]
	s_waitcnt lgkmcnt(0)
; #define LAS __attribute__((address_space(3)))
; __device__ __forceinline__ void conv_phase(LAS unsigned char* lds, const bf16_t* U, bf16_t* C, const float* wdw, const float* bdw, const float* lng, const float* lnb,
;                                            int first, int stride, int end, int tid, int wave, int lane) {
;     ...
;             for (int r = 0; r < TT / NWAVES + CW - 1; ++r) {
;                 if (r + 4 < CW) { wt[(r + 4) & 7][0] = wq[0]; wt[(r + 4) & 7][1] = wq[1]; wq += D / 4; asm volatile("" : "+v"(wq)); }
;                 const u32x4 xv = *(const LAS u32x4*)(lds + (4 * wave + r) * 2048 + p * 1024 + lane * 16);
;                 f32x2 x[4];
; #pragma unroll
;                 for (int i = 0; i < 4; ++i) x[i] = (f32x2){__uint_as_float(xv[i] << 16), __uint_as_float(xv[i] & 0xffff0000u)};
; #pragma unroll
;                 for (int j = 0; j < 4; ++j) { const int w = r - j;
;                     if (w >= 0 && w < CW) {
; #pragma unroll
;                         for (int c = 0; c < 4; ++c) { const f32x4 wv = wt[w & 7][c >> 1]; const f32x2 w2 = (c & 1) ? (f32x2){wv.z, wv.w} : (f32x2){wv.x, wv.y}; acc[p][j][c] = __builtin_elementwise_fma(w2, x[c], acc[p][j][c]); } } }
;                 asm volatile("" ::: "memory");
;             }
	v_lshlrev_b32_e32 v160, 16, v64
	v_and_b32_e32 v161, 0xffff0000, v64
	v_lshlrev_b32_e32 v64, 16, v65
	v_and_b32_e32 v65, 0xffff0000, v65
	v_lshlrev_b32_e32 v162, 16, v66
	v_and_b32_e32 v163, 0xffff0000, v66
	v_lshlrev_b32_e32 v66, 16, v67
	v_and_b32_e32 v67, 0xffff0000, v67
	v_pk_fma_f32 v[152:153], v[40:41], v[160:161], v[152:153]
	v_pk_fma_f32 v[156:157], v[42:43], v[64:65], v[156:157]
	v_pk_fma_f32 v[154:155], v[8:9], v[162:163], v[154:155]
	v_pk_fma_f32 v[158:159], v[10:11], v[66:67], v[158:159]
	global_load_dwordx4 v[8:11], v[150:151], off offset:16
	global_load_dwordx4 v[40:43], v[150:151], off
	v_lshl_add_u64 v[150:151], v[150:151], 0, s[0:1]
	s_waitcnt vmcnt(10)
	v_pk_fma_f32 v[82:83], v[54:55], v[64:65], v[82:83]
	v_pk_fma_f32 v[144:145], v[22:23], v[66:67], v[144:145]
	v_pk_fma_f32 v[72:73], v[50:51], v[64:65], v[72:73]
	v_pk_fma_f32 v[76:77], v[18:19], v[66:67], v[76:77]
	v_pk_fma_f32 v[146:147], v[46:47], v[64:65], v[146:147]
	v_pk_fma_f32 v[148:149], v[14:15], v[66:67], v[148:149]
	ds_read_b128 v[64:67], v134 offset:27648
	v_pk_fma_f32 v[68:69], v[52:53], v[160:161], v[68:69]
	v_pk_fma_f32 v[142:143], v[20:21], v[162:163], v[142:143]
	v_pk_fma_f32 v[70:71], v[48:49], v[160:161], v[70:71]
	v_pk_fma_f32 v[74:75], v[16:17], v[162:163], v[74:75]
	v_pk_fma_f32 v[78:79], v[44:45], v[160:161], v[78:79]
	v_pk_fma_f32 v[80:81], v[12:13], v[162:163], v[80:81]
	s_waitcnt lgkmcnt(0)
	v_lshlrev_b32_e32 v160, 16, v64
	v_and_b32_e32 v161, 0xffff0000, v64
	v_lshlrev_b32_e32 v64, 16, v65
	v_and_b32_e32 v65, 0xffff0000, v65
	v_lshlrev_b32_e32 v162, 16, v66
	v_and_b32_e32 v163, 0xffff0000, v66
	v_lshlrev_b32_e32 v66, 16, v67
	v_and_b32_e32 v67, 0xffff0000, v67
	v_pk_fma_f32 v[152:153], v[44:45], v[160:161], v[152:153]
	v_pk_fma_f32 v[156:157], v[46:47], v[64:65], v[156:157]
	v_pk_fma_f32 v[154:155], v[12:13], v[162:163], v[154:155]
	v_pk_fma_f32 v[158:159], v[14:15], v[66:67], v[158:159]
	global_load_dwordx4 v[12:15], v[150:151], off offset:16
	global_load_dwordx4 v[44:47], v[150:151], off
	v_lshl_add_u64 v[150:151], v[150:151], 0, s[0:1]
	s_waitcnt vmcnt(10)
	v_pk_fma_f32 v[82:83], v[58:59], v[64:65], v[82:83]
	v_pk_fma_f32 v[144:145], v[26:27], v[66:67], v[144:145]
	v_pk_fma_f32 v[72:73], v[54:55], v[64:65], v[72:73]
	v_pk_fma_f32 v[76:77], v[22:23], v[66:67], v[76:77]
	v_pk_fma_f32 v[146:147], v[50:51], v[64:65], v[146:147]
	v_pk_fma_f32 v[148:149], v[18:19], v[66:67], v[148:149]
	ds_read_b128 v[64:67], v134 offset:29696
	v_pk_fma_f32 v[68:69], v[56:57], v[160:161], v[68:69]
	v_pk_fma_f32 v[142:143], v[24:25], v[162:163], v[142:143]
	v_pk_fma_f32 v[70:71], v[52:53], v[160:161], v[70:71]
	v_pk_fma_f32 v[74:75], v[20:21], v[162:163], v[74:75]
	v_pk_fma_f32 v[78:79], v[48:49], v[160:161], v[78:79]
	v_pk_fma_f32 v[80:81], v[16:17], v[162:163], v[80:81]
	s_waitcnt lgkmcnt(0)
	v_lshlrev_b32_e32 v160, 16, v64
	v_and_b32_e32 v161, 0xffff0000, v64
	v_lshlrev_b32_e32 v64, 16, v65
	v_and_b32_e32 v65, 0xffff0000, v65
	v_lshlrev_b32_e32 v162, 16, v66
	v_and_b32_e32 v163, 0xffff0000, v66
	v_lshlrev_b32_e32 v66, 16, v67
	v_and_b32_e32 v67, 0xffff0000, v67
	v_pk_fma_f32 v[152:153], v[48:49], v[160:161], v[152:153]
	v_pk_fma_f32 v[156:157], v[50:51], v[64:65], v[156:157]
	v_pk_fma_f32 v[154:155], v[16:17], v[162:163], v[154:155]
	v_pk_fma_f32 v[158:159], v[18:19], v[66:67], v[158:159]
	global_load_dwordx4 v[16:19], v[150:151], off offset:16
	global_load_dwordx4 v[48:51], v[150:151], off
	v_lshl_add_u64 v[150:151], v[150:151], 0, s[0:1]
	s_waitcnt vmcnt(10)
	v_pk_fma_f32 v[82:83], v[62:63], v[64:65], v[82:83]
	v_pk_fma_f32 v[144:145], v[30:31], v[66:67], v[144:145]
	v_pk_fma_f32 v[72:73], v[58:59], v[64:65], v[72:73]
	v_pk_fma_f32 v[76:77], v[26:27], v[66:67], v[76:77]
	v_pk_fma_f32 v[146:147], v[54:55], v[64:65], v[146:147]
	v_pk_fma_f32 v[148:149], v[22:23], v[66:67], v[148:149]
	ds_read_b128 v[64:67], v134 offset:31744
	v_pk_fma_f32 v[68:69], v[60:61], v[160:161], v[68:69]
	v_pk_fma_f32 v[142:143], v[28:29], v[162:163], v[142:143]
	v_pk_fma_f32 v[70:71], v[56:57], v[160:161], v[70:71]
	v_pk_fma_f32 v[74:75], v[24:25], v[162:163], v[74:75]
	v_pk_fma_f32 v[78:79], v[52:53], v[160:161], v[78:79]
	v_pk_fma_f32 v[80:81], v[20:21], v[162:163], v[80:81]
	s_waitcnt lgkmcnt(0)
	v_lshlrev_b32_e32 v160, 16, v64
	v_and_b32_e32 v161, 0xffff0000, v64
	v_lshlrev_b32_e32 v64, 16, v65
	v_and_b32_e32 v65, 0xffff0000, v65
	v_lshlrev_b32_e32 v162, 16, v66
	v_and_b32_e32 v163, 0xffff0000, v66
	v_lshlrev_b32_e32 v66, 16, v67
	v_and_b32_e32 v67, 0xffff0000, v67
	v_pk_fma_f32 v[152:153], v[52:53], v[160:161], v[152:153]
	v_pk_fma_f32 v[156:157], v[54:55], v[64:65], v[156:157]
	v_pk_fma_f32 v[154:155], v[20:21], v[162:163], v[154:155]
	v_pk_fma_f32 v[158:159], v[22:23], v[66:67], v[158:159]
	global_load_dwordx4 v[20:23], v[150:151], off offset:16
	global_load_dwordx4 v[52:55], v[150:151], off
	v_lshl_add_u64 v[150:151], v[150:151], 0, s[0:1]
	s_waitcnt vmcnt(10)
	v_pk_fma_f32 v[82:83], v[34:35], v[64:65], v[82:83]
	v_pk_fma_f32 v[144:145], v[2:3], v[66:67], v[144:145]
	v_pk_fma_f32 v[72:73], v[62:63], v[64:65], v[72:73]
	v_pk_fma_f32 v[76:77], v[30:31], v[66:67], v[76:77]
	v_pk_fma_f32 v[146:147], v[58:59], v[64:65], v[146:147]
	v_pk_fma_f32 v[148:149], v[26:27], v[66:67], v[148:149]
	ds_read_b128 v[64:67], v134 offset:33792
	v_pk_fma_f32 v[68:69], v[32:33], v[160:161], v[68:69]
	v_pk_fma_f32 v[142:143], v[0:1], v[162:163], v[142:143]
	v_pk_fma_f32 v[70:71], v[60:61], v[160:161], v[70:71]
	v_pk_fma_f32 v[74:75], v[28:29], v[162:163], v[74:75]
	v_pk_fma_f32 v[78:79], v[56:57], v[160:161], v[78:79]
	v_pk_fma_f32 v[80:81], v[24:25], v[162:163], v[80:81]
	s_waitcnt lgkmcnt(0)
; #define LAS __attribute__((address_space(3)))
; __device__ __forceinline__ void conv_phase(LAS unsigned char* lds, const bf16_t* U, bf16_t* C, const float* wdw, const float* bdw, const float* lng, const float* lnb,
;                                            int first, int stride, int end, int tid, int wave, int lane) {
;     ...
;             for (int r = 0; r < TT / NWAVES + CW - 1; ++r) {
;                 if (r + 4 < CW) { wt[(r + 4) & 7][0] = wq[0]; wt[(r + 4) & 7][1] = wq[1]; wq += D / 4; asm volatile("" : "+v"(wq)); }
;                 const u32x4 xv = *(const LAS u32x4*)(lds + (4 * wave + r) * 2048 + p * 1024 + lane * 16);
;                 f32x2 x[4];
; #pragma unroll
;                 for (int i = 0; i < 4; ++i) x[i] = (f32x2){__uint_as_float(xv[i] << 16), __uint_as_float(xv[i] & 0xffff0000u)};
; #pragma unroll
;                 for (int j = 0; j < 4; ++j) { const int w = r - j;
;                     if (w >= 0 && w < CW) {
; #pragma unroll
;                         for (int c = 0; c < 4; ++c) { const f32x4 wv = wt[w & 7][c >> 1]; const f32x2 w2 = (c & 1) ? (f32x2){wv.z, wv.w} : (f32x2){wv.x, wv.y}; acc[p][j][c] = __builtin_elementwise_fma(w2, x[c], acc[p][j][c]); } } }
;                 asm volatile("" ::: "memory");
;             }
	v_lshlrev_b32_e32 v160, 16, v64
	v_and_b32_e32 v161, 0xffff0000, v64
	v_lshlrev_b32_e32 v64, 16, v65
	v_and_b32_e32 v65, 0xffff0000, v65
	v_lshlrev_b32_e32 v162, 16, v66
	v_and_b32_e32 v163, 0xffff0000, v66
	v_lshlrev_b32_e32 v66, 16, v67
	v_and_b32_e32 v67, 0xffff0000, v67
	v_pk_fma_f32 v[152:153], v[56:57], v[160:161], v[152:153]
	v_pk_fma_f32 v[156:157], v[58:59], v[64:65], v[156:157]
	v_pk_fma_f32 v[154:155], v[24:25], v[162:163], v[154:155]
	v_pk_fma_f32 v[158:159], v[26:27], v[66:67], v[158:159]
	global_load_dwordx4 v[24:27], v[150:151], off offset:16
	global_load_dwordx4 v[56:59], v[150:151], off
	v_lshl_add_u64 v[150:151], v[150:151], 0, s[0:1]
	s_waitcnt vmcnt(10)
	v_pk_fma_f32 v[82:83], v[38:39], v[64:65], v[82:83]
	v_pk_fma_f32 v[144:145], v[6:7], v[66:67], v[144:145]
	v_pk_fma_f32 v[72:73], v[34:35], v[64:65], v[72:73]
	v_pk_fma_f32 v[76:77], v[2:3], v[66:67], v[76:77]
	v_pk_fma_f32 v[146:147], v[62:63], v[64:65], v[146:147]
	v_pk_fma_f32 v[148:149], v[30:31], v[66:67], v[148:149]
	ds_read_b128 v[64:67], v134 offset:35840
	v_pk_fma_f32 v[68:69], v[36:37], v[160:161], v[68:69]
	v_pk_fma_f32 v[142:143], v[4:5], v[162:163], v[142:143]
	v_pk_fma_f32 v[70:71], v[32:33], v[160:161], v[70:71]
	v_pk_fma_f32 v[74:75], v[0:1], v[162:163], v[74:75]
	v_pk_fma_f32 v[78:79], v[60:61], v[160:161], v[78:79]
	v_pk_fma_f32 v[80:81], v[28:29], v[162:163], v[80:81]
	s_waitcnt lgkmcnt(0)
	v_lshlrev_b32_e32 v160, 16, v64
	v_and_b32_e32 v161, 0xffff0000, v64
	v_lshlrev_b32_e32 v64, 16, v65
	v_and_b32_e32 v65, 0xffff0000, v65
	v_lshlrev_b32_e32 v162, 16, v66
	v_and_b32_e32 v163, 0xffff0000, v66
	v_lshlrev_b32_e32 v66, 16, v67
	v_and_b32_e32 v67, 0xffff0000, v67
	v_pk_fma_f32 v[152:153], v[60:61], v[160:161], v[152:153]
	v_pk_fma_f32 v[156:157], v[62:63], v[64:65], v[156:157]
	v_pk_fma_f32 v[154:155], v[28:29], v[162:163], v[154:155]
	v_pk_fma_f32 v[158:159], v[30:31], v[66:67], v[158:159]
	global_load_dwordx4 v[28:31], v[150:151], off offset:16
	global_load_dwordx4 v[60:63], v[150:151], off
	v_lshl_add_u64 v[150:151], v[150:151], 0, s[0:1]
	s_waitcnt vmcnt(10)
	v_pk_fma_f32 v[82:83], v[42:43], v[64:65], v[82:83]
	v_pk_fma_f32 v[144:145], v[10:11], v[66:67], v[144:145]
	v_pk_fma_f32 v[72:73], v[38:39], v[64:65], v[72:73]
	v_pk_fma_f32 v[76:77], v[6:7], v[66:67], v[76:77]
	v_pk_fma_f32 v[146:147], v[34:35], v[64:65], v[146:147]
	v_pk_fma_f32 v[148:149], v[2:3], v[66:67], v[148:149]
	ds_read_b128 v[64:67], v134 offset:37888
	v_pk_fma_f32 v[68:69], v[40:41], v[160:161], v[68:69]
	v_pk_fma_f32 v[142:143], v[8:9], v[162:163], v[142:143]
	v_pk_fma_f32 v[70:71], v[36:37], v[160:161], v[70:71]
	v_pk_fma_f32 v[74:75], v[4:5], v[162:163], v[74:75]
	v_pk_fma_f32 v[78:79], v[32:33], v[160:161], v[78:79]
	v_pk_fma_f32 v[80:81], v[0:1], v[162:163], v[80:81]
	s_waitcnt lgkmcnt(0)
	v_lshlrev_b32_e32 v160, 16, v64
	v_and_b32_e32 v161, 0xffff0000, v64
	v_lshlrev_b32_e32 v64, 16, v65
	v_and_b32_e32 v65, 0xffff0000, v65
	v_lshlrev_b32_e32 v162, 16, v66
	v_and_b32_e32 v163, 0xffff0000, v66
	v_lshlrev_b32_e32 v66, 16, v67
	v_and_b32_e32 v67, 0xffff0000, v67
	s_waitcnt vmcnt(8)
	v_pk_fma_f32 v[82:83], v[46:47], v[64:65], v[82:83]
	v_pk_fma_f32 v[144:145], v[14:15], v[66:67], v[144:145]
	v_pk_fma_f32 v[72:73], v[42:43], v[64:65], v[72:73]
	v_pk_fma_f32 v[76:77], v[10:11], v[66:67], v[76:77]
	v_pk_fma_f32 v[146:147], v[38:39], v[64:65], v[146:147]
	v_pk_fma_f32 v[148:149], v[6:7], v[66:67], v[148:149]
	v_pk_fma_f32 v[152:153], v[32:33], v[160:161], v[152:153]
	v_pk_fma_f32 v[156:157], v[34:35], v[64:65], v[156:157]
	v_pk_fma_f32 v[158:159], v[2:3], v[66:67], v[158:159]
	global_load_dwordx4 v[32:35], v[150:151], off offset:16
	global_load_dwordx4 v[64:67], v[150:151], off
	v_lshl_add_u64 v[150:151], v[150:151], 0, s[0:1]
	v_pk_fma_f32 v[154:155], v[0:1], v[162:163], v[154:155]
	ds_read_b128 v[0:3], v134 offset:39936
	v_pk_fma_f32 v[68:69], v[44:45], v[160:161], v[68:69]
	v_pk_fma_f32 v[70:71], v[40:41], v[160:161], v[70:71]
	v_pk_fma_f32 v[78:79], v[36:37], v[160:161], v[78:79]
	s_waitcnt lgkmcnt(0)
	v_lshlrev_b32_e32 v160, 16, v0
	v_and_b32_e32 v161, 0xffff0000, v0
	v_lshlrev_b32_e32 v0, 16, v1
	v_and_b32_e32 v1, 0xffff0000, v1
	v_pk_fma_f32 v[142:143], v[12:13], v[162:163], v[142:143]
	v_pk_fma_f32 v[74:75], v[8:9], v[162:163], v[74:75]
	v_pk_fma_f32 v[80:81], v[4:5], v[162:163], v[80:81]
	v_lshlrev_b32_e32 v162, 16, v2
	v_and_b32_e32 v163, 0xffff0000, v2
	v_lshlrev_b32_e32 v2, 16, v3
	v_and_b32_e32 v3, 0xffff0000, v3
	s_waitcnt vmcnt(8)
	v_pk_fma_f32 v[164:165], v[48:49], v[160:161], v[68:69]
	v_pk_fma_f32 v[166:167], v[44:45], v[160:161], v[70:71]
	v_pk_fma_f32 v[152:153], v[36:37], v[160:161], v[152:153]
	v_pk_fma_f32 v[156:157], v[38:39], v[0:1], v[156:157]
	global_load_dwordx4 v[36:39], v[150:151], off offset:16
	global_load_dwordx4 v[68:71], v[150:151], off
	v_lshl_add_u64 v[150:151], v[150:151], 0, s[0:1]
	v_pk_fma_f32 v[82:83], v[50:51], v[0:1], v[82:83]
	v_pk_fma_f32 v[144:145], v[18:19], v[2:3], v[144:145]
	v_pk_fma_f32 v[72:73], v[46:47], v[0:1], v[72:73]
	v_pk_fma_f32 v[76:77], v[14:15], v[2:3], v[76:77]
	v_pk_fma_f32 v[146:147], v[42:43], v[0:1], v[146:147]
	v_pk_fma_f32 v[148:149], v[10:11], v[2:3], v[148:149]
	v_pk_fma_f32 v[6:7], v[6:7], v[2:3], v[158:159]
	ds_read_b128 v[0:3], v134 offset:41984
	v_pk_fma_f32 v[74:75], v[12:13], v[162:163], v[74:75]
	v_pk_fma_f32 v[78:79], v[40:41], v[160:161], v[78:79]
	v_pk_fma_f32 v[4:5], v[4:5], v[162:163], v[154:155]
	s_waitcnt lgkmcnt(0)
	v_lshlrev_b32_e32 v154, 16, v0
	v_and_b32_e32 v155, 0xffff0000, v0
	v_lshlrev_b32_e32 v0, 16, v1
	v_and_b32_e32 v1, 0xffff0000, v1
	v_lshlrev_b32_e32 v158, 16, v2
	v_and_b32_e32 v159, 0xffff0000, v2
	v_pk_fma_f32 v[142:143], v[16:17], v[162:163], v[142:143]
	v_pk_fma_f32 v[80:81], v[8:9], v[162:163], v[80:81]
	s_waitcnt vmcnt(8)
; #define LAS __attribute__((address_space(3)))
; __device__ __forceinline__ void conv_phase(LAS unsigned char* lds, const bf16_t* U, bf16_t* C, const float* wdw, const float* bdw, const float* lng, const float* lnb,
;                                            int first, int stride, int end, int tid, int wave, int lane) {
;     ...
;             for (int r = 0; r < TT / NWAVES + CW - 1; ++r) {
;                 if (r + 4 < CW) { wt[(r + 4) & 7][0] = wq[0]; wt[(r + 4) & 7][1] = wq[1]; wq += D / 4; asm volatile("" : "+v"(wq)); }
;                 const u32x4 xv = *(const LAS u32x4*)(lds + (4 * wave + r) * 2048 + p * 1024 + lane * 16);
;                 f32x2 x[4];
; #pragma unroll
;                 for (int i = 0; i < 4; ++i) x[i] = (f32x2){__uint_as_float(xv[i] << 16), __uint_as_float(xv[i] & 0xffff0000u)};
; #pragma unroll
;                 for (int j = 0; j < 4; ++j) { const int w = r - j;
;                     if (w >= 0 && w < CW) {
; #pragma unroll
;                         for (int c = 0; c < 4; ++c) { const f32x4 wv = wt[w & 7][c >> 1]; const f32x2 w2 = (c & 1) ? (f32x2){wv.z, wv.w} : (f32x2){wv.x, wv.y}; acc[p][j][c] = __builtin_elementwise_fma(w2, x[c], acc[p][j][c]); } } }
;                 asm volatile("" ::: "memory");
;             }
	v_pk_fma_f32 v[160:161], v[52:53], v[154:155], v[164:165]
	v_pk_fma_f32 v[162:163], v[48:49], v[154:155], v[166:167]
	v_pk_fma_f32 v[164:165], v[50:51], v[0:1], v[72:73]
	v_pk_fma_f32 v[166:167], v[16:17], v[158:159], v[74:75]
	v_pk_fma_f32 v[78:79], v[44:45], v[154:155], v[78:79]
	v_pk_fma_f32 v[152:153], v[40:41], v[154:155], v[152:153]
	v_pk_fma_f32 v[154:155], v[42:43], v[0:1], v[156:157]
	global_load_dwordx4 v[40:43], v[150:151], off offset:16
	global_load_dwordx4 v[72:75], v[150:151], off
	v_lshlrev_b32_e32 v2, 16, v3
	v_and_b32_e32 v3, 0xffff0000, v3
	v_pk_fma_f32 v[4:5], v[8:9], v[158:159], v[4:5]
	v_lshl_add_u64 v[8:9], v[150:151], 0, s[0:1]
	v_pk_fma_f32 v[82:83], v[54:55], v[0:1], v[82:83]
	v_pk_fma_f32 v[144:145], v[22:23], v[2:3], v[144:145]
	v_pk_fma_f32 v[76:77], v[18:19], v[2:3], v[76:77]
	v_pk_fma_f32 v[146:147], v[46:47], v[0:1], v[146:147]
	v_pk_fma_f32 v[148:149], v[14:15], v[2:3], v[148:149]
	v_pk_fma_f32 v[6:7], v[10:11], v[2:3], v[6:7]
	ds_read_b128 v[0:3], v134 offset:44032
	v_pk_fma_f32 v[142:143], v[20:21], v[158:159], v[142:143]
	v_pk_fma_f32 v[80:81], v[12:13], v[158:159], v[80:81]
	s_waitcnt lgkmcnt(0)
	v_lshlrev_b32_e32 v10, 16, v0
	v_and_b32_e32 v11, 0xffff0000, v0
	v_lshlrev_b32_e32 v0, 16, v1
	v_and_b32_e32 v1, 0xffff0000, v1
	v_lshlrev_b32_e32 v150, 16, v2
	v_and_b32_e32 v151, 0xffff0000, v2
	v_lshlrev_b32_e32 v2, 16, v3
	v_and_b32_e32 v3, 0xffff0000, v3
	s_waitcnt vmcnt(8)
	v_pk_fma_f32 v[156:157], v[56:57], v[10:11], v[160:161]
	v_pk_fma_f32 v[158:159], v[52:53], v[10:11], v[162:163]
	v_pk_fma_f32 v[160:161], v[54:55], v[0:1], v[164:165]
	v_pk_fma_f32 v[162:163], v[20:21], v[150:151], v[166:167]
	v_pk_fma_f32 v[164:165], v[22:23], v[2:3], v[76:77]
	v_pk_fma_f32 v[166:167], v[48:49], v[10:11], v[78:79]
	v_pk_fma_f32 v[10:11], v[44:45], v[10:11], v[152:153]
	v_pk_fma_f32 v[152:153], v[46:47], v[0:1], v[154:155]
	global_load_dwordx4 v[44:47], v[8:9], off offset:16
	global_load_dwordx4 v[76:79], v[8:9], off
	v_lshl_add_u64 v[8:9], v[8:9], 0, s[0:1]
	v_pk_fma_f32 v[82:83], v[58:59], v[0:1], v[82:83]
	v_pk_fma_f32 v[144:145], v[26:27], v[2:3], v[144:145]
	v_pk_fma_f32 v[146:147], v[50:51], v[0:1], v[146:147]
	v_pk_fma_f32 v[148:149], v[18:19], v[2:3], v[148:149]
	v_pk_fma_f32 v[6:7], v[14:15], v[2:3], v[6:7]
	ds_read_b128 v[0:3], v134 offset:46080
	v_pk_fma_f32 v[80:81], v[16:17], v[150:151], v[80:81]
	v_pk_fma_f32 v[4:5], v[12:13], v[150:151], v[4:5]
	v_pk_fma_f32 v[142:143], v[24:25], v[150:151], v[142:143]
	s_waitcnt lgkmcnt(0)
	v_lshlrev_b32_e32 v12, 16, v0
	v_and_b32_e32 v13, 0xffff0000, v0
	v_lshlrev_b32_e32 v0, 16, v1
	v_and_b32_e32 v1, 0xffff0000, v1
	v_lshlrev_b32_e32 v14, 16, v2
	v_and_b32_e32 v15, 0xffff0000, v2
	v_lshlrev_b32_e32 v2, 16, v3
	v_and_b32_e32 v3, 0xffff0000, v3
	s_waitcnt vmcnt(8)
	v_pk_fma_f32 v[150:151], v[60:61], v[12:13], v[156:157]
	v_pk_fma_f32 v[154:155], v[62:63], v[0:1], v[82:83]
	v_pk_fma_f32 v[156:157], v[56:57], v[12:13], v[158:159]
	v_pk_fma_f32 v[158:159], v[58:59], v[0:1], v[160:161]
	v_pk_fma_f32 v[160:161], v[24:25], v[14:15], v[162:163]
	v_pk_fma_f32 v[162:163], v[26:27], v[2:3], v[164:165]
	v_pk_fma_f32 v[164:165], v[52:53], v[12:13], v[166:167]
	v_pk_fma_f32 v[166:167], v[20:21], v[14:15], v[80:81]
	v_pk_fma_f32 v[10:11], v[48:49], v[12:13], v[10:11]
	v_pk_fma_f32 v[12:13], v[50:51], v[0:1], v[152:153]
	global_load_dwordx4 v[48:51], v[8:9], off offset:16
	global_load_dwordx4 v[80:83], v[8:9], off
	v_lshl_add_u64 v[8:9], v[8:9], 0, s[0:1]
	v_pk_fma_f32 v[144:145], v[30:31], v[2:3], v[144:145]
	v_pk_fma_f32 v[146:147], v[54:55], v[0:1], v[146:147]
	v_pk_fma_f32 v[148:149], v[22:23], v[2:3], v[148:149]
	v_pk_fma_f32 v[6:7], v[18:19], v[2:3], v[6:7]
	ds_read_b128 v[0:3], v134 offset:48128
	v_pk_fma_f32 v[142:143], v[28:29], v[14:15], v[142:143]
	v_pk_fma_f32 v[4:5], v[16:17], v[14:15], v[4:5]
	s_waitcnt lgkmcnt(0)
	v_lshlrev_b32_e32 v14, 16, v0
	v_and_b32_e32 v15, 0xffff0000, v0
	v_lshlrev_b32_e32 v0, 16, v1
	v_and_b32_e32 v1, 0xffff0000, v1
	v_lshlrev_b32_e32 v16, 16, v2
	v_and_b32_e32 v17, 0xffff0000, v2
	v_lshlrev_b32_e32 v2, 16, v3
	v_and_b32_e32 v3, 0xffff0000, v3
	v_pk_fma_f32 v[10:11], v[52:53], v[14:15], v[10:11]
	v_lshl_add_u64 v[52:53], v[8:9], 0, s[0:1]
	s_waitcnt vmcnt(8)
	v_pk_fma_f32 v[152:153], v[66:67], v[0:1], v[154:155]
	v_pk_fma_f32 v[142:143], v[32:33], v[16:17], v[142:143]
	v_pk_fma_f32 v[144:145], v[34:35], v[2:3], v[144:145]
	v_pk_fma_f32 v[154:155], v[60:61], v[14:15], v[156:157]
	v_pk_fma_f32 v[156:157], v[62:63], v[0:1], v[158:159]
	v_pk_fma_f32 v[158:159], v[28:29], v[16:17], v[160:161]
	v_pk_fma_f32 v[160:161], v[30:31], v[2:3], v[162:163]
	v_pk_fma_f32 v[162:163], v[56:57], v[14:15], v[164:165]
	v_pk_fma_f32 v[146:147], v[58:59], v[0:1], v[146:147]
	v_pk_fma_f32 v[164:165], v[24:25], v[16:17], v[166:167]
	v_pk_fma_f32 v[148:149], v[26:27], v[2:3], v[148:149]
	v_pk_fma_f32 v[12:13], v[54:55], v[0:1], v[12:13]
	v_pk_fma_f32 v[4:5], v[20:21], v[16:17], v[4:5]
	v_pk_fma_f32 v[6:7], v[22:23], v[2:3], v[6:7]
	global_load_dwordx4 v[16:19], v[8:9], off offset:16
	global_load_dwordx4 v[20:23], v[8:9], off
	ds_read_b128 v[0:3], v134 offset:50176
	v_pk_fma_f32 v[150:151], v[64:65], v[14:15], v[150:151]
	s_waitcnt lgkmcnt(0)
	v_lshlrev_b32_e32 v14, 16, v2
	v_and_b32_e32 v15, 0xffff0000, v2
	v_lshlrev_b32_e32 v8, 16, v0
	v_and_b32_e32 v9, 0xffff0000, v0
	v_lshlrev_b32_e32 v0, 16, v1
	v_and_b32_e32 v1, 0xffff0000, v1
	v_lshlrev_b32_e32 v2, 16, v3
	v_and_b32_e32 v3, 0xffff0000, v3
	v_pk_fma_f32 v[4:5], v[24:25], v[14:15], v[4:5]
	v_lshl_add_u64 v[24:25], v[52:53], 0, s[0:1]
	s_waitcnt vmcnt(8)
; #define LAS __attribute__((address_space(3)))
; __device__ __forceinline__ void conv_phase(LAS unsigned char* lds, const bf16_t* U, bf16_t* C, const float* wdw, const float* bdw, const float* lng, const float* lnb,
;                                            int first, int stride, int end, int tid, int wave, int lane) {
;     ...
;             for (int r = 0; r < TT / NWAVES + CW - 1; ++r) {
;                 if (r + 4 < CW) { wt[(r + 4) & 7][0] = wq[0]; wt[(r + 4) & 7][1] = wq[1]; wq += D / 4; asm volatile("" : "+v"(wq)); }
;                 const u32x4 xv = *(const LAS u32x4*)(lds + (4 * wave + r) * 2048 + p * 1024 + lane * 16);
;                 f32x2 x[4];
; #pragma unroll
;                 for (int i = 0; i < 4; ++i) x[i] = (f32x2){__uint_as_float(xv[i] << 16), __uint_as_float(xv[i] & 0xffff0000u)};
; #pragma unroll
;                 for (int j = 0; j < 4; ++j) { const int w = r - j;
;                     if (w >= 0 && w < CW) {
; #pragma unroll
;                         for (int c = 0; c < 4; ++c) { const f32x4 wv = wt[w & 7][c >> 1]; const f32x2 w2 = (c & 1) ? (f32x2){wv.z, wv.w} : (f32x2){wv.x, wv.y}; acc[p][j][c] = __builtin_elementwise_fma(w2, x[c], acc[p][j][c]); } } }
;                 asm volatile("" ::: "memory");
;             }
	v_pk_fma_f32 v[54:55], v[68:69], v[8:9], v[150:151]
	v_pk_fma_f32 v[150:151], v[70:71], v[0:1], v[152:153]
	v_pk_fma_f32 v[142:143], v[36:37], v[14:15], v[142:143]
	v_pk_fma_f32 v[144:145], v[38:39], v[2:3], v[144:145]
	v_pk_fma_f32 v[152:153], v[64:65], v[8:9], v[154:155]
	v_pk_fma_f32 v[154:155], v[66:67], v[0:1], v[156:157]
	v_pk_fma_f32 v[156:157], v[32:33], v[14:15], v[158:159]
	v_pk_fma_f32 v[158:159], v[34:35], v[2:3], v[160:161]
	v_pk_fma_f32 v[160:161], v[60:61], v[8:9], v[162:163]
	v_pk_fma_f32 v[146:147], v[62:63], v[0:1], v[146:147]
	v_pk_fma_f32 v[162:163], v[28:29], v[14:15], v[164:165]
	v_pk_fma_f32 v[148:149], v[30:31], v[2:3], v[148:149]
	v_pk_fma_f32 v[56:57], v[56:57], v[8:9], v[10:11]
	v_pk_fma_f32 v[58:59], v[58:59], v[0:1], v[12:13]
	v_pk_fma_f32 v[6:7], v[26:27], v[2:3], v[6:7]
	global_load_dwordx4 v[8:11], v[52:53], off offset:16
	global_load_dwordx4 v[12:15], v[52:53], off
	ds_read_b128 v[0:3], v134 offset:52224
	s_waitcnt lgkmcnt(0)
	v_lshlrev_b32_e32 v26, 16, v0
	v_and_b32_e32 v27, 0xffff0000, v0
	v_lshlrev_b32_e32 v0, 16, v1
	v_and_b32_e32 v1, 0xffff0000, v1
	v_lshlrev_b32_e32 v52, 16, v2
	v_and_b32_e32 v53, 0xffff0000, v2
	v_lshlrev_b32_e32 v2, 16, v3
	v_and_b32_e32 v3, 0xffff0000, v3
	s_waitcnt vmcnt(8)
	v_pk_fma_f32 v[150:151], v[74:75], v[0:1], v[150:151]
	v_pk_fma_f32 v[144:145], v[42:43], v[2:3], v[144:145]
	v_pk_fma_f32 v[154:155], v[70:71], v[0:1], v[154:155]
	v_pk_fma_f32 v[158:159], v[38:39], v[2:3], v[158:159]
	v_pk_fma_f32 v[146:147], v[66:67], v[0:1], v[146:147]
	v_pk_fma_f32 v[148:149], v[34:35], v[2:3], v[148:149]
	v_pk_fma_f32 v[58:59], v[62:63], v[0:1], v[58:59]
	v_pk_fma_f32 v[28:29], v[28:29], v[52:53], v[4:5]
	v_pk_fma_f32 v[30:31], v[30:31], v[2:3], v[6:7]
	global_load_dwordx4 v[4:7], v[24:25], off offset:16
	global_load_dwordx4 v[0:3], v[24:25], off
	v_lshl_add_u64 v[24:25], v[24:25], 0, s[0:1]
	v_pk_fma_f32 v[54:55], v[72:73], v[26:27], v[54:55]
	v_pk_fma_f32 v[152:153], v[68:69], v[26:27], v[152:153]
	v_pk_fma_f32 v[160:161], v[64:65], v[26:27], v[160:161]
	v_pk_fma_f32 v[56:57], v[60:61], v[26:27], v[56:57]
	ds_read_b128 v[24:27], v134 offset:54272
	v_pk_fma_f32 v[142:143], v[40:41], v[52:53], v[142:143]
	v_pk_fma_f32 v[156:157], v[36:37], v[52:53], v[156:157]
	v_pk_fma_f32 v[162:163], v[32:33], v[52:53], v[162:163]
	s_waitcnt lgkmcnt(0)
	v_lshlrev_b32_e32 v52, 16, v24
	v_and_b32_e32 v53, 0xffff0000, v24
	v_lshlrev_b32_e32 v24, 16, v25
	v_and_b32_e32 v25, 0xffff0000, v25
	v_lshlrev_b32_e32 v60, 16, v26
	v_and_b32_e32 v61, 0xffff0000, v26
	v_lshlrev_b32_e32 v26, 16, v27
	v_and_b32_e32 v27, 0xffff0000, v27
	s_waitcnt vmcnt(8)
	v_pk_fma_f32 v[54:55], v[76:77], v[52:53], v[54:55]
	v_pk_fma_f32 v[62:63], v[78:79], v[24:25], v[150:151]
	v_pk_fma_f32 v[144:145], v[46:47], v[26:27], v[144:145]
	v_pk_fma_f32 v[150:151], v[72:73], v[52:53], v[152:153]
	v_pk_fma_f32 v[152:153], v[74:75], v[24:25], v[154:155]
	v_pk_fma_f32 v[154:155], v[40:41], v[60:61], v[156:157]
	v_pk_fma_f32 v[156:157], v[42:43], v[26:27], v[158:159]
	v_pk_fma_f32 v[158:159], v[68:69], v[52:53], v[160:161]
	v_pk_fma_f32 v[146:147], v[70:71], v[24:25], v[146:147]
	v_pk_fma_f32 v[148:149], v[38:39], v[26:27], v[148:149]
	v_pk_fma_f32 v[52:53], v[64:65], v[52:53], v[56:57]
	v_pk_fma_f32 v[56:57], v[66:67], v[24:25], v[58:59]
	v_pk_fma_f32 v[30:31], v[34:35], v[26:27], v[30:31]
	ds_read_b128 v[24:27], v134 offset:56320
	v_pk_fma_f32 v[28:29], v[32:33], v[60:61], v[28:29]
	v_pk_fma_f32 v[142:143], v[44:45], v[60:61], v[142:143]
	v_pk_fma_f32 v[160:161], v[36:37], v[60:61], v[162:163]
	s_waitcnt lgkmcnt(0)
	v_lshlrev_b32_e32 v32, 16, v24
	v_and_b32_e32 v33, 0xffff0000, v24
	v_lshlrev_b32_e32 v24, 16, v25
	v_and_b32_e32 v25, 0xffff0000, v25
	v_lshlrev_b32_e32 v34, 16, v26
	v_and_b32_e32 v35, 0xffff0000, v26
	v_lshlrev_b32_e32 v26, 16, v27
	v_and_b32_e32 v27, 0xffff0000, v27
	s_waitcnt vmcnt(6)
	v_pk_fma_f32 v[54:55], v[80:81], v[32:33], v[54:55]
	v_pk_fma_f32 v[58:59], v[82:83], v[24:25], v[62:63]
	v_pk_fma_f32 v[62:63], v[50:51], v[26:27], v[144:145]
	v_pk_fma_f32 v[64:65], v[76:77], v[32:33], v[150:151]
	v_pk_fma_f32 v[66:67], v[78:79], v[24:25], v[152:153]
	v_pk_fma_f32 v[144:145], v[46:47], v[26:27], v[156:157]
	v_pk_fma_f32 v[150:151], v[72:73], v[32:33], v[158:159]
	v_pk_fma_f32 v[146:147], v[74:75], v[24:25], v[146:147]
	v_pk_fma_f32 v[148:149], v[42:43], v[26:27], v[148:149]
	v_pk_fma_f32 v[32:33], v[68:69], v[32:33], v[52:53]
	v_pk_fma_f32 v[52:53], v[70:71], v[24:25], v[56:57]
	v_pk_fma_f32 v[30:31], v[38:39], v[26:27], v[30:31]
	ds_read_b128 v[24:27], v134 offset:58368
	v_pk_fma_f32 v[60:61], v[48:49], v[34:35], v[142:143]
	v_pk_fma_f32 v[142:143], v[44:45], v[34:35], v[154:155]
	v_pk_fma_f32 v[152:153], v[40:41], v[34:35], v[160:161]
	v_pk_fma_f32 v[28:29], v[36:37], v[34:35], v[28:29]
	s_waitcnt lgkmcnt(0)
	v_lshlrev_b32_e32 v34, 16, v24
	v_and_b32_e32 v35, 0xffff0000, v24
	v_lshlrev_b32_e32 v24, 16, v25
	v_and_b32_e32 v25, 0xffff0000, v25
	v_lshlrev_b32_e32 v36, 16, v26
	v_and_b32_e32 v37, 0xffff0000, v26
	v_lshlrev_b32_e32 v26, 16, v27
	v_and_b32_e32 v27, 0xffff0000, v27
	s_waitcnt vmcnt(4)
	v_pk_fma_f32 v[38:39], v[20:21], v[34:35], v[54:55]
	v_pk_fma_f32 v[54:55], v[22:23], v[24:25], v[58:59]
	v_pk_fma_f32 v[56:57], v[16:17], v[36:37], v[60:61]
	v_pk_fma_f32 v[58:59], v[18:19], v[26:27], v[62:63]
	v_pk_fma_f32 v[60:61], v[80:81], v[34:35], v[64:65]
	v_pk_fma_f32 v[62:63], v[82:83], v[24:25], v[66:67]
	v_pk_fma_f32 v[66:67], v[50:51], v[26:27], v[144:145]
	v_pk_fma_f32 v[68:69], v[76:77], v[34:35], v[150:151]
	v_pk_fma_f32 v[70:71], v[78:79], v[24:25], v[146:147]
	v_pk_fma_f32 v[144:145], v[46:47], v[26:27], v[148:149]
	v_pk_fma_f32 v[32:33], v[72:73], v[34:35], v[32:33]
	v_pk_fma_f32 v[34:35], v[74:75], v[24:25], v[52:53]
	v_pk_fma_f32 v[30:31], v[42:43], v[26:27], v[30:31]
	ds_read_b128 v[24:27], v134 offset:60416
	v_pk_fma_f32 v[64:65], v[48:49], v[36:37], v[142:143]
	v_pk_fma_f32 v[142:143], v[44:45], v[36:37], v[152:153]
	v_pk_fma_f32 v[28:29], v[40:41], v[36:37], v[28:29]
	s_waitcnt lgkmcnt(0)
; #define LAS __attribute__((address_space(3)))
; __device__ __forceinline__ void conv_phase(LAS unsigned char* lds, const bf16_t* U, bf16_t* C, const float* wdw, const float* bdw, const float* lng, const float* lnb,
;                                            int first, int stride, int end, int tid, int wave, int lane) {
;     ...
;             for (int r = 0; r < TT / NWAVES + CW - 1; ++r) {
;                 if (r + 4 < CW) { wt[(r + 4) & 7][0] = wq[0]; wt[(r + 4) & 7][1] = wq[1]; wq += D / 4; asm volatile("" : "+v"(wq)); }
;                 const u32x4 xv = *(const LAS u32x4*)(lds + (4 * wave + r) * 2048 + p * 1024 + lane * 16);
;                 f32x2 x[4];
; #pragma unroll
;                 for (int i = 0; i < 4; ++i) x[i] = (f32x2){__uint_as_float(xv[i] << 16), __uint_as_float(xv[i] & 0xffff0000u)};
; #pragma unroll
;                 for (int j = 0; j < 4; ++j) { const int w = r - j;
;                     if (w >= 0 && w < CW) {
; #pragma unroll
;                         for (int c = 0; c < 4; ++c) { const f32x4 wv = wt[w & 7][c >> 1]; const f32x2 w2 = (c & 1) ? (f32x2){wv.z, wv.w} : (f32x2){wv.x, wv.y}; acc[p][j][c] = __builtin_elementwise_fma(w2, x[c], acc[p][j][c]); } } }
;                 asm volatile("" ::: "memory");
;             }
;             const f32x4 b0 = *(const f32x4*)(bdw + p * 512 + lane * 8), b1 = *(const f32x4*)(bdw + p * 512 + lane * 8 + 4);
; #pragma unroll
;             for (int j = 0; j < 4; ++j) { acc[p][j][0] += (f32x2){b0.x, b0.y}; acc[p][j][1] += (f32x2){b0.z, b0.w}; acc[p][j][2] += (f32x2){b1.x, b1.y}; acc[p][j][3] += (f32x2){b1.z, b1.w}; }
	v_lshlrev_b32_e32 v36, 16, v24
	v_and_b32_e32 v37, 0xffff0000, v24
	v_lshlrev_b32_e32 v24, 16, v25
	v_and_b32_e32 v25, 0xffff0000, v25
	v_lshlrev_b32_e32 v40, 16, v26
	v_and_b32_e32 v41, 0xffff0000, v26
	v_lshlrev_b32_e32 v26, 16, v27
	v_and_b32_e32 v27, 0xffff0000, v27
	s_waitcnt vmcnt(2)
	v_pk_fma_f32 v[38:39], v[12:13], v[36:37], v[38:39]
	v_pk_fma_f32 v[42:43], v[14:15], v[24:25], v[54:55]
	v_pk_fma_f32 v[52:53], v[8:9], v[40:41], v[56:57]
	v_pk_fma_f32 v[54:55], v[10:11], v[26:27], v[58:59]
	v_pk_fma_f32 v[56:57], v[20:21], v[36:37], v[60:61]
	v_pk_fma_f32 v[58:59], v[22:23], v[24:25], v[62:63]
	v_pk_fma_f32 v[60:61], v[16:17], v[40:41], v[64:65]
	v_pk_fma_f32 v[62:63], v[18:19], v[26:27], v[66:67]
	v_pk_fma_f32 v[64:65], v[80:81], v[36:37], v[68:69]
	v_pk_fma_f32 v[66:67], v[82:83], v[24:25], v[70:71]
	v_pk_fma_f32 v[68:69], v[48:49], v[40:41], v[142:143]
	v_pk_fma_f32 v[70:71], v[50:51], v[26:27], v[144:145]
	v_pk_fma_f32 v[32:33], v[76:77], v[36:37], v[32:33]
	v_pk_fma_f32 v[34:35], v[78:79], v[24:25], v[34:35]
	v_pk_fma_f32 v[36:37], v[44:45], v[40:41], v[28:29]
	v_pk_fma_f32 v[40:41], v[46:47], v[26:27], v[30:31]
	ds_read_b128 v[24:27], v134 offset:62464
	s_waitcnt lgkmcnt(0)
	v_lshlrev_b32_e32 v44, 16, v24
	v_and_b32_e32 v45, 0xffff0000, v24
	v_lshlrev_b32_e32 v46, 16, v25
	v_and_b32_e32 v47, 0xffff0000, v25
	v_lshlrev_b32_e32 v72, 16, v26
	v_and_b32_e32 v73, 0xffff0000, v26
	v_lshlrev_b32_e32 v74, 16, v27
	v_and_b32_e32 v75, 0xffff0000, v27
	s_waitcnt vmcnt(0)
	v_pk_fma_f32 v[24:25], v[0:1], v[44:45], v[38:39]
	v_pk_fma_f32 v[26:27], v[2:3], v[46:47], v[42:43]
	v_pk_fma_f32 v[38:39], v[12:13], v[44:45], v[56:57]
	v_pk_fma_f32 v[42:43], v[14:15], v[46:47], v[58:59]
	v_pk_fma_f32 v[56:57], v[20:21], v[44:45], v[64:65]
	v_pk_fma_f32 v[58:59], v[22:23], v[46:47], v[66:67]
	v_pk_fma_f32 v[44:45], v[80:81], v[44:45], v[32:33]
	v_pk_fma_f32 v[46:47], v[82:83], v[46:47], v[34:35]
	ds_read_b128 v[32:35], v134 offset:64512
	v_pk_fma_f32 v[28:29], v[4:5], v[72:73], v[52:53]
	v_pk_fma_f32 v[52:53], v[8:9], v[72:73], v[60:61]
	v_pk_fma_f32 v[60:61], v[16:17], v[72:73], v[68:69]
	v_pk_fma_f32 v[48:49], v[48:49], v[72:73], v[36:37]
	v_pk_fma_f32 v[40:41], v[50:51], v[74:75], v[40:41]
	s_waitcnt lgkmcnt(0)
	v_lshlrev_b32_e32 v66, 16, v34
	v_and_b32_e32 v67, 0xffff0000, v34
	v_lshlrev_b32_e32 v68, 16, v35
	v_and_b32_e32 v69, 0xffff0000, v35
	v_pk_fma_f32 v[30:31], v[6:7], v[74:75], v[54:55]
	v_pk_fma_f32 v[54:55], v[10:11], v[74:75], v[62:63]
	v_pk_fma_f32 v[62:63], v[18:19], v[74:75], v[70:71]
	v_pk_fma_f32 v[48:49], v[16:17], v[66:67], v[48:49]
	v_pk_fma_f32 v[40:41], v[18:19], v[68:69], v[40:41]
	ds_read_b128 v[16:19], v138
	v_lshlrev_b32_e32 v50, 16, v32
	v_and_b32_e32 v51, 0xffff0000, v32
	v_lshlrev_b32_e32 v64, 16, v33
	v_and_b32_e32 v65, 0xffff0000, v33
	v_pk_fma_f32 v[32:33], v[0:1], v[50:51], v[38:39]
	v_pk_fma_f32 v[34:35], v[2:3], v[64:65], v[42:43]
	v_pk_fma_f32 v[38:39], v[6:7], v[68:69], v[54:55]
	v_pk_fma_f32 v[42:43], v[12:13], v[50:51], v[56:57]
	v_pk_fma_f32 v[54:55], v[8:9], v[66:67], v[60:61]
	v_pk_fma_f32 v[56:57], v[10:11], v[68:69], v[62:63]
	v_pk_fma_f32 v[44:45], v[20:21], v[50:51], v[44:45]
	s_waitcnt lgkmcnt(0)
	v_lshlrev_b32_e32 v50, 16, v16
	v_and_b32_e32 v51, 0xffff0000, v16
	v_lshlrev_b32_e32 v60, 16, v18
	v_and_b32_e32 v61, 0xffff0000, v18
	v_lshlrev_b32_e32 v62, 16, v19
	v_and_b32_e32 v63, 0xffff0000, v19
	v_pk_fma_f32 v[36:37], v[4:5], v[66:67], v[52:53]
	v_pk_fma_f32 v[52:53], v[14:15], v[64:65], v[58:59]
	v_lshlrev_b32_e32 v58, 16, v17
	v_and_b32_e32 v59, 0xffff0000, v17
	v_pk_fma_f32 v[16:17], v[0:1], v[50:51], v[42:43]
	v_pk_fma_f32 v[42:43], v[8:9], v[60:61], v[48:49]
	v_pk_fma_f32 v[40:41], v[10:11], v[62:63], v[40:41]
	ds_read_b128 v[8:11], v139
	v_pk_fma_f32 v[46:47], v[22:23], v[64:65], v[46:47]
	v_pk_fma_f32 v[12:13], v[12:13], v[50:51], v[44:45]
	v_pk_fma_f32 v[14:15], v[14:15], v[58:59], v[46:47]
	s_waitcnt lgkmcnt(0)
	v_lshlrev_b32_e32 v46, 16, v8
	v_and_b32_e32 v47, 0xffff0000, v8
	v_lshlrev_b32_e32 v8, 16, v9
	v_and_b32_e32 v9, 0xffff0000, v9
	v_lshlrev_b32_e32 v44, 16, v10
	v_and_b32_e32 v45, 0xffff0000, v10
	v_lshlrev_b32_e32 v10, 16, v11
	v_and_b32_e32 v11, 0xffff0000, v11
	v_pk_fma_f32 v[18:19], v[2:3], v[58:59], v[52:53]
	v_pk_fma_f32 v[20:21], v[4:5], v[60:61], v[54:55]
	v_pk_fma_f32 v[22:23], v[6:7], v[62:63], v[56:57]
	v_pk_fma_f32 v[40:41], v[6:7], v[10:11], v[40:41]
	v_pk_fma_f32 v[42:43], v[4:5], v[44:45], v[42:43]
	v_pk_fma_f32 v[44:45], v[2:3], v[8:9], v[14:15]
	v_pk_fma_f32 v[8:9], v[0:1], v[46:47], v[12:13]
	global_load_dwordx4 v[0:3], v[86:87], off offset:2064
	global_load_dwordx4 v[4:7], v[86:87], off offset:2048
	s_waitcnt vmcnt(1)
	v_pk_add_f32 v[50:51], v[28:29], v[0:1]
	s_waitcnt vmcnt(0)
; __device__ __forceinline__ float wave_sum(float v) {
; #pragma unroll
;     for (int o = 1; o < 64; o <<= 1) v += __shfl_xor(v, o);
;     return v;
; }
; __device__ __forceinline__ void conv_phase(LAS unsigned char* lds, const bf16_t* U, bf16_t* C, const float* wdw, const float* bdw, const float* lng, const float* lnb,
;                                            int first, int stride, int end, int tid, int wave, int lane) {
;     ...
;         float mean[4], rstd[4];
; #pragma unroll
;         for (int j = 0; j < 4; ++j) { f32x2 s2 = (f32x2){0.f, 0.f};
; #pragma unroll
;             for (int p = 0; p < 2; ++p)
; #pragma unroll
;                 for (int c = 0; c < 4; ++c) s2 += acc[p][j][c];
;             mean[j] = wave_sum(s2.x + s2.y) * (1.f / D); f32x2 q2 = (f32x2){0.f, 0.f};
; #pragma unroll
;             for (int p = 0; p < 2; ++p)
; #pragma unroll
;                 for (int c = 0; c < 4; ++c) { const f32x2 d = acc[p][j][c] - mean[j]; q2 += d * d; }
;             rstd[j] = rsqrtf(wave_sum(q2.x + q2.y) * (1.f / D) + LN_EPS); }
	v_pk_add_f32 v[46:47], v[24:25], v[4:5]
	v_pk_add_f32 v[48:49], v[26:27], v[6:7]
	v_pk_add_f32 v[52:53], v[30:31], v[2:3]
	v_pk_add_f32 v[32:33], v[32:33], v[4:5]
	v_pk_add_f32 v[30:31], v[34:35], v[6:7]
	v_pk_add_f32 v[24:25], v[36:37], v[0:1]
	v_pk_add_f32 v[26:27], v[38:39], v[2:3]
	v_pk_add_f32 v[34:35], v[4:5], v[16:17]
	v_pk_add_f32 v[12:13], v[0:1], v[20:21]
	v_pk_add_f32 v[10:11], v[2:3], v[22:23]
	v_pk_add_f32 v[8:9], v[4:5], v[8:9]
	v_pk_add_f32 v[4:5], v[0:1], v[42:43]
	v_pk_add_f32 v[0:1], v[2:3], v[40:41]
	v_cndmask_b32_e64 v2, v224, v226, s[40:41]
	v_cmp_lt_i32_e64 s[40:41], v227, v225
	v_lshlrev_b32_e32 v41, 2, v2
	v_pk_add_f32 v[14:15], v[6:7], v[18:19]
	v_cndmask_b32_e64 v2, v224, v227, s[40:41]
	v_cmp_lt_i32_e64 s[40:41], v228, v225
	v_pk_add_f32 v[6:7], v[6:7], v[44:45]
	v_lshlrev_b32_e32 v44, 2, v2
	v_cndmask_b32_e64 v2, v224, v228, s[40:41]
	v_cmp_lt_i32_e64 s[40:41], v229, v225
	v_lshlrev_b32_e32 v45, 2, v2
	s_nop 0
	v_cndmask_b32_e64 v2, v224, v229, s[40:41]
	v_cmp_lt_i32_e64 s[40:41], v230, v225
	v_lshlrev_b32_e32 v54, 2, v2
	s_nop 0
	v_cndmask_b32_e64 v2, v224, v230, s[40:41]
	v_cmp_lt_i32_e64 s[40:41], v231, v225
	v_lshlrev_b32_e32 v55, 2, v2
	s_nop 0
	v_cndmask_b32_e64 v2, v224, v231, s[40:41]
	v_lshlrev_b32_e32 v76, 2, v2
	v_pk_add_f32 v[2:3], v[128:129], 0 op_sel_hi:[1,0]
	s_nop 0
	v_pk_add_f32 v[2:3], v[130:131], v[2:3]
	s_nop 0
	v_pk_add_f32 v[2:3], v[126:127], v[2:3]
	s_nop 0
	v_pk_add_f32 v[2:3], v[124:125], v[2:3]
	s_nop 0
	v_pk_add_f32 v[2:3], v[2:3], v[46:47]
	s_nop 0
	v_pk_add_f32 v[2:3], v[48:49], v[2:3]
	s_nop 0
	v_pk_add_f32 v[2:3], v[50:51], v[2:3]
	s_nop 0
	v_pk_add_f32 v[2:3], v[52:53], v[2:3]
	s_nop 0
	v_add_f32_e32 v2, v2, v3
	s_nop 1
	v_add_f32_dpp v2, v2, v2 quad_perm:[1,0,3,2] row_mask:0xf bank_mask:0xf
	s_nop 1
	v_add_f32_dpp v2, v2, v2 quad_perm:[2,3,0,1] row_mask:0xf bank_mask:0xf
	s_nop 1
	v_add_f32_dpp v2, v2, v2 row_half_mirror row_mask:0xf bank_mask:0xf
	s_nop 1
	v_add_f32_dpp v2, v2, v2 row_mirror row_mask:0xf bank_mask:0xf
	ds_bpermute_b32 v3, v55, v2
	s_waitcnt lgkmcnt(0)
	v_add_f32_e32 v2, v2, v3
	ds_bpermute_b32 v3, v76, v2
	s_waitcnt lgkmcnt(0)
	v_add_f32_e32 v2, v2, v3
	v_mul_f32_e32 v2, 0x3a800000, v2
	v_pk_add_f32 v[62:63], v[130:131], v[2:3] op_sel_hi:[1,0] neg_lo:[0,1] neg_hi:[0,1]
	v_pk_add_f32 v[66:67], v[128:129], v[2:3] op_sel_hi:[1,0] neg_lo:[0,1] neg_hi:[0,1]
	v_pk_mul_f32 v[16:17], v[62:63], v[62:63]
	v_pk_add_f32 v[58:59], v[126:127], v[2:3] op_sel_hi:[1,0] neg_lo:[0,1] neg_hi:[0,1]
	v_pk_fma_f32 v[16:17], v[66:67], v[66:67], v[16:17]
	v_pk_add_f32 v[56:57], v[124:125], v[2:3] op_sel_hi:[1,0] neg_lo:[0,1] neg_hi:[0,1]
	v_pk_fma_f32 v[16:17], v[58:59], v[58:59], v[16:17]
	v_pk_add_f32 v[28:29], v[46:47], v[2:3] op_sel_hi:[1,0] neg_lo:[0,1] neg_hi:[0,1]
	v_pk_fma_f32 v[16:17], v[56:57], v[56:57], v[16:17]
	v_pk_add_f32 v[22:23], v[48:49], v[2:3] op_sel_hi:[1,0] neg_lo:[0,1] neg_hi:[0,1]
	v_pk_fma_f32 v[16:17], v[28:29], v[28:29], v[16:17]
	v_pk_add_f32 v[18:19], v[50:51], v[2:3] op_sel_hi:[1,0] neg_lo:[0,1] neg_hi:[0,1]
	v_pk_fma_f32 v[16:17], v[22:23], v[22:23], v[16:17]
	s_nop 0
	v_pk_fma_f32 v[20:21], v[18:19], v[18:19], v[16:17]
	v_pk_add_f32 v[16:17], v[52:53], v[2:3] op_sel_hi:[1,0] neg_lo:[0,1] neg_hi:[0,1]
	s_nop 0
	v_pk_fma_f32 v[2:3], v[16:17], v[16:17], v[20:21]
	v_pk_add_f32 v[20:21], v[120:121], 0 op_sel_hi:[1,0]
	s_nop 0
	v_pk_add_f32 v[20:21], v[122:123], v[20:21]
	s_nop 0
	v_pk_add_f32 v[20:21], v[118:119], v[20:21]
	s_nop 0
	v_pk_add_f32 v[20:21], v[116:117], v[20:21]
	s_nop 0
	v_pk_add_f32 v[20:21], v[20:21], v[32:33]
	s_nop 0
	v_pk_add_f32 v[20:21], v[30:31], v[20:21]
	s_nop 0
	v_pk_add_f32 v[20:21], v[24:25], v[20:21]
	s_nop 0
	v_pk_add_f32 v[20:21], v[26:27], v[20:21]
	s_nop 0
	v_add_f32_e32 v20, v20, v21
	s_nop 1
	v_add_f32_dpp v20, v20, v20 quad_perm:[1,0,3,2] row_mask:0xf bank_mask:0xf
	s_nop 1
	v_add_f32_dpp v20, v20, v20 quad_perm:[2,3,0,1] row_mask:0xf bank_mask:0xf
	s_nop 1
	v_add_f32_dpp v20, v20, v20 row_half_mirror row_mask:0xf bank_mask:0xf
	s_nop 1
	v_add_f32_dpp v20, v20, v20 row_mirror row_mask:0xf bank_mask:0xf
	ds_bpermute_b32 v21, v55, v20
	s_waitcnt lgkmcnt(0)
	v_add_f32_e32 v20, v20, v21
	ds_bpermute_b32 v21, v76, v20
	s_waitcnt lgkmcnt(0)
	v_add_f32_e32 v20, v20, v21
	v_mul_f32_e32 v20, 0x3a800000, v20
	v_pk_add_f32 v[68:69], v[122:123], v[20:21] op_sel_hi:[1,0] neg_lo:[0,1] neg_hi:[0,1]
	v_pk_add_f32 v[70:71], v[120:121], v[20:21] op_sel_hi:[1,0] neg_lo:[0,1] neg_hi:[0,1]
	v_pk_mul_f32 v[36:37], v[68:69], v[68:69]
	v_pk_add_f32 v[64:65], v[118:119], v[20:21] op_sel_hi:[1,0] neg_lo:[0,1] neg_hi:[0,1]
	v_pk_fma_f32 v[36:37], v[70:71], v[70:71], v[36:37]
	v_pk_add_f32 v[60:61], v[116:117], v[20:21] op_sel_hi:[1,0] neg_lo:[0,1] neg_hi:[0,1]
	v_pk_fma_f32 v[36:37], v[64:65], v[64:65], v[36:37]
	v_pk_add_f32 v[32:33], v[32:33], v[20:21] op_sel_hi:[1,0] neg_lo:[0,1] neg_hi:[0,1]
	v_pk_fma_f32 v[36:37], v[60:61], v[60:61], v[36:37]
	v_pk_add_f32 v[30:31], v[30:31], v[20:21] op_sel_hi:[1,0] neg_lo:[0,1] neg_hi:[0,1]
	v_pk_fma_f32 v[36:37], v[32:33], v[32:33], v[36:37]
	v_pk_add_f32 v[24:25], v[24:25], v[20:21] op_sel_hi:[1,0] neg_lo:[0,1] neg_hi:[0,1]
	v_pk_fma_f32 v[36:37], v[30:31], v[30:31], v[36:37]
	v_pk_add_f32 v[20:21], v[26:27], v[20:21] op_sel_hi:[1,0] neg_lo:[0,1] neg_hi:[0,1]
	v_pk_fma_f32 v[36:37], v[24:25], v[24:25], v[36:37]
	s_nop 0
	v_pk_fma_f32 v[26:27], v[20:21], v[20:21], v[36:37]
	v_mov_b32_e32 v37, v2
	v_mov_b32_e32 v36, v26
	v_mov_b32_e32 v2, v27
	v_pk_add_f32 v[2:3], v[36:37], v[2:3]
	s_nop 1
	v_add_f32_dpp v2, v2, v2 quad_perm:[1,0,3,2] row_mask:0xf bank_mask:0xf
	v_add_f32_dpp v3, v3, v3 quad_perm:[1,0,3,2] row_mask:0xf bank_mask:0xf
	s_nop 1
	v_add_f32_dpp v2, v2, v2 quad_perm:[2,3,0,1] row_mask:0xf bank_mask:0xf
	v_add_f32_dpp v3, v3, v3 quad_perm:[2,3,0,1] row_mask:0xf bank_mask:0xf
	s_nop 1
	v_add_f32_dpp v2, v2, v2 row_half_mirror row_mask:0xf bank_mask:0xf
	v_add_f32_dpp v3, v3, v3 row_half_mirror row_mask:0xf bank_mask:0xf
	s_nop 1
	v_add_f32_dpp v2, v2, v2 row_mirror row_mask:0xf bank_mask:0xf
	v_add_f32_dpp v3, v3, v3 row_mirror row_mask:0xf bank_mask:0xf
	ds_bpermute_b32 v27, v55, v3
	ds_bpermute_b32 v26, v55, v2
	s_waitcnt lgkmcnt(0)
; __device__ __forceinline__ float wave_sum(float v) {
; #pragma unroll
;     for (int o = 1; o < 64; o <<= 1) v += __shfl_xor(v, o);
;     return v;
; }
; __device__ __forceinline__ void conv_phase(LAS unsigned char* lds, const bf16_t* U, bf16_t* C, const float* wdw, const float* bdw, const float* lng, const float* lnb,
;                                            int first, int stride, int end, int tid, int wave, int lane) {
;     ...
;         float mean[4], rstd[4];
; #pragma unroll
;         for (int j = 0; j < 4; ++j) { f32x2 s2 = (f32x2){0.f, 0.f};
; #pragma unroll
;             for (int p = 0; p < 2; ++p)
; #pragma unroll
;                 for (int c = 0; c < 4; ++c) s2 += acc[p][j][c];
;             mean[j] = wave_sum(s2.x + s2.y) * (1.f / D); f32x2 q2 = (f32x2){0.f, 0.f};
; #pragma unroll
;             for (int p = 0; p < 2; ++p)
; #pragma unroll
;                 for (int c = 0; c < 4; ++c) { const f32x2 d = acc[p][j][c] - mean[j]; q2 += d * d; }
;             rstd[j] = rsqrtf(wave_sum(q2.x + q2.y) * (1.f / D) + LN_EPS); }
	v_pk_add_f32 v[2:3], v[2:3], v[26:27]
	ds_bpermute_b32 v27, v76, v3
	ds_bpermute_b32 v26, v76, v2
	s_waitcnt lgkmcnt(0)
	v_pk_add_f32 v[26:27], v[2:3], v[26:27]
	v_mov_b64_e32 v[2:3], s[4:5]
	s_mov_b32 s4, 0x3a800000
	v_pk_fma_f32 v[26:27], v[26:27], s[4:5], v[2:3] op_sel_hi:[1,0,0]
	s_nop 0
	v_mul_f32_e32 v36, 0x4b800000, v27
	v_cmp_gt_f32_e64 s[42:43], s7, v27
	v_cmp_gt_f32_e64 s[40:41], s7, v26
	s_nop 0
	v_cndmask_b32_e64 v27, v27, v36, s[42:43]
	v_rsq_f32_e32 v27, v27
	s_nop 0
	v_mul_f32_e32 v36, 0x45800000, v27
	v_cndmask_b32_e64 v40, v27, v36, s[42:43]
	v_pk_add_f32 v[36:37], v[112:113], 0 op_sel_hi:[1,0]
	v_mul_f32_e32 v27, 0x4b800000, v26
	v_pk_add_f32 v[36:37], v[114:115], v[36:37]
	v_cndmask_b32_e64 v26, v26, v27, s[40:41]
	v_pk_add_f32 v[36:37], v[110:111], v[36:37]
	v_rsq_f32_e32 v26, v26
	v_pk_add_f32 v[36:37], v[108:109], v[36:37]
	v_mul_f32_e32 v27, 0x45800000, v26
	v_pk_add_f32 v[36:37], v[36:37], v[34:35]
	v_cndmask_b32_e64 v26, v26, v27, s[40:41]
	v_pk_add_f32 v[36:37], v[14:15], v[36:37]
	s_nop 0
	v_pk_add_f32 v[36:37], v[12:13], v[36:37]
	s_nop 0
	v_pk_add_f32 v[36:37], v[10:11], v[36:37]
	s_nop 0
	v_add_f32_e32 v27, v36, v37
	s_nop 1
	v_add_f32_dpp v27, v27, v27 quad_perm:[1,0,3,2] row_mask:0xf bank_mask:0xf
	s_nop 1
	v_add_f32_dpp v27, v27, v27 quad_perm:[2,3,0,1] row_mask:0xf bank_mask:0xf
	s_nop 1
	v_add_f32_dpp v27, v27, v27 row_half_mirror row_mask:0xf bank_mask:0xf
	s_nop 1
	v_add_f32_dpp v27, v27, v27 row_mirror row_mask:0xf bank_mask:0xf
	ds_bpermute_b32 v36, v55, v27
	s_waitcnt lgkmcnt(0)
	v_add_f32_e32 v27, v27, v36
	ds_bpermute_b32 v36, v76, v27
	s_waitcnt lgkmcnt(0)
	v_add_f32_e32 v27, v27, v36
	v_mul_f32_e32 v36, 0x3a800000, v27
	v_pk_add_f32 v[82:83], v[114:115], v[36:37] op_sel_hi:[1,0] neg_lo:[0,1] neg_hi:[0,1]
	v_pk_add_f32 v[112:113], v[112:113], v[36:37] op_sel_hi:[1,0] neg_lo:[0,1] neg_hi:[0,1]
	v_pk_mul_f32 v[38:39], v[82:83], v[82:83]
	v_pk_add_f32 v[78:79], v[110:111], v[36:37] op_sel_hi:[1,0] neg_lo:[0,1] neg_hi:[0,1]
	v_pk_fma_f32 v[38:39], v[112:113], v[112:113], v[38:39]
	v_pk_add_f32 v[72:73], v[108:109], v[36:37] op_sel_hi:[1,0] neg_lo:[0,1] neg_hi:[0,1]
	v_pk_fma_f32 v[38:39], v[78:79], v[78:79], v[38:39]
	v_pk_add_f32 v[50:51], v[34:35], v[36:37] op_sel_hi:[1,0] neg_lo:[0,1] neg_hi:[0,1]
	v_pk_fma_f32 v[38:39], v[72:73], v[72:73], v[38:39]
	v_pk_add_f32 v[46:47], v[14:15], v[36:37] op_sel_hi:[1,0] neg_lo:[0,1] neg_hi:[0,1]
	v_pk_fma_f32 v[34:35], v[50:51], v[50:51], v[38:39]
	v_pk_add_f32 v[38:39], v[12:13], v[36:37] op_sel_hi:[1,0] neg_lo:[0,1] neg_hi:[0,1]
	v_pk_fma_f32 v[14:15], v[46:47], v[46:47], v[34:35]
	v_pk_add_f32 v[34:35], v[10:11], v[36:37] op_sel_hi:[1,0] neg_lo:[0,1] neg_hi:[0,1]
	v_pk_fma_f32 v[12:13], v[38:39], v[38:39], v[14:15]
	s_nop 0
	v_pk_fma_f32 v[10:11], v[34:35], v[34:35], v[12:13]
	v_pk_add_f32 v[12:13], v[104:105], 0 op_sel_hi:[1,0]
	s_nop 0
	v_pk_add_f32 v[12:13], v[106:107], v[12:13]
	s_nop 0
	v_pk_add_f32 v[12:13], v[102:103], v[12:13]
	s_nop 0
	v_pk_add_f32 v[12:13], v[100:101], v[12:13]
	s_nop 0
	v_pk_add_f32 v[12:13], v[12:13], v[8:9]
	s_nop 0
	v_pk_add_f32 v[12:13], v[6:7], v[12:13]
	s_nop 0
	v_pk_add_f32 v[12:13], v[4:5], v[12:13]
	s_nop 0
	v_pk_add_f32 v[12:13], v[0:1], v[12:13]
	s_nop 0
	v_add_f32_e32 v12, v12, v13
	s_nop 1
	v_add_f32_dpp v12, v12, v12 quad_perm:[1,0,3,2] row_mask:0xf bank_mask:0xf
	s_nop 1
	v_add_f32_dpp v12, v12, v12 quad_perm:[2,3,0,1] row_mask:0xf bank_mask:0xf
	s_nop 1
	v_add_f32_dpp v12, v12, v12 row_half_mirror row_mask:0xf bank_mask:0xf
	s_nop 1
	v_add_f32_dpp v12, v12, v12 row_mirror row_mask:0xf bank_mask:0xf
	ds_bpermute_b32 v13, v55, v12
	s_waitcnt lgkmcnt(0)
	v_add_f32_e32 v12, v12, v13
	ds_bpermute_b32 v13, v76, v12
	s_waitcnt lgkmcnt(0)
	v_add_f32_e32 v12, v12, v13
	v_mul_f32_e32 v12, 0x3a800000, v12
	v_pk_add_f32 v[108:109], v[104:105], v[12:13] op_sel_hi:[1,0] neg_lo:[0,1] neg_hi:[0,1]
	v_pk_add_f32 v[104:105], v[106:107], v[12:13] op_sel_hi:[1,0] neg_lo:[0,1] neg_hi:[0,1]
	v_pk_add_f32 v[80:81], v[102:103], v[12:13] op_sel_hi:[1,0] neg_lo:[0,1] neg_hi:[0,1]
	v_pk_mul_f32 v[14:15], v[104:105], v[104:105]
	v_pk_add_f32 v[74:75], v[100:101], v[12:13] op_sel_hi:[1,0] neg_lo:[0,1] neg_hi:[0,1]
	v_pk_fma_f32 v[14:15], v[108:109], v[108:109], v[14:15]
	v_pk_add_f32 v[52:53], v[8:9], v[12:13] op_sel_hi:[1,0] neg_lo:[0,1] neg_hi:[0,1]
	v_pk_fma_f32 v[14:15], v[80:81], v[80:81], v[14:15]
	v_pk_add_f32 v[48:49], v[6:7], v[12:13] op_sel_hi:[1,0] neg_lo:[0,1] neg_hi:[0,1]
	v_pk_fma_f32 v[14:15], v[74:75], v[74:75], v[14:15]
	v_pk_add_f32 v[42:43], v[4:5], v[12:13] op_sel_hi:[1,0] neg_lo:[0,1] neg_hi:[0,1]
	v_pk_fma_f32 v[8:9], v[52:53], v[52:53], v[14:15]
	v_pk_add_f32 v[36:37], v[0:1], v[12:13] op_sel_hi:[1,0] neg_lo:[0,1] neg_hi:[0,1]
	v_pk_fma_f32 v[6:7], v[48:49], v[48:49], v[8:9]
	s_nop 0
	v_pk_fma_f32 v[4:5], v[42:43], v[42:43], v[6:7]
	s_nop 0
	v_pk_fma_f32 v[0:1], v[36:37], v[36:37], v[4:5]
	v_mov_b32_e32 v5, v10
	v_mov_b32_e32 v4, v0
	v_mov_b32_e32 v10, v1
	v_pk_add_f32 v[0:1], v[4:5], v[10:11]
	s_nop 1
	v_add_f32_dpp v0, v0, v0 quad_perm:[1,0,3,2] row_mask:0xf bank_mask:0xf
	v_add_f32_dpp v1, v1, v1 quad_perm:[1,0,3,2] row_mask:0xf bank_mask:0xf
	s_nop 1
	v_add_f32_dpp v0, v0, v0 quad_perm:[2,3,0,1] row_mask:0xf bank_mask:0xf
	v_add_f32_dpp v1, v1, v1 quad_perm:[2,3,0,1] row_mask:0xf bank_mask:0xf
	s_nop 1
	v_add_f32_dpp v0, v0, v0 row_half_mirror row_mask:0xf bank_mask:0xf
	v_add_f32_dpp v1, v1, v1 row_half_mirror row_mask:0xf bank_mask:0xf
	s_nop 1
	v_add_f32_dpp v0, v0, v0 row_mirror row_mask:0xf bank_mask:0xf
	v_add_f32_dpp v1, v1, v1 row_mirror row_mask:0xf bank_mask:0xf
	ds_bpermute_b32 v5, v55, v1
	ds_bpermute_b32 v4, v55, v0
	s_waitcnt lgkmcnt(0)
; __device__ __forceinline__ unsigned cvt_pk_bf16(float lo, float hi) { unsigned r; asm volatile("v_cvt_pk_bf16_f32 %0, %1, %2" : "=v"(r) : "v"(lo), "v"(hi)); return r; }
; __device__ __forceinline__ void conv_phase(LAS unsigned char* lds, const bf16_t* U, bf16_t* C, const float* wdw, const float* bdw, const float* lng, const float* lnb,
;                                            int first, int stride, int end, int tid, int wave, int lane) {
;     ...
;             rstd[j] = rsqrtf(wave_sum(q2.x + q2.y) * (1.f / D) + LN_EPS); }
; #pragma unroll
;         for (int p = 0; p < 2; ++p) {
;             const f32x4 g0 = *(const f32x4*)(lng + p * 512 + lane * 8), g1 = *(const f32x4*)(lng + p * 512 + lane * 8 + 4);
;             const f32x4 c0 = *(const f32x4*)(lnb + p * 512 + lane * 8), c1 = *(const f32x4*)(lnb + p * 512 + lane * 8 + 4);
;             const f32x2 gg2[4] = {(f32x2){g0.x, g0.y}, (f32x2){g0.z, g0.w}, (f32x2){g1.x, g1.y}, (f32x2){g1.z, g1.w}}, bb2[4] = {(f32x2){c0.x, c0.y}, (f32x2){c0.z, c0.w}, (f32x2){c1.x, c1.y}, (f32x2){c1.z, c1.w}};
; #pragma unroll
;             for (int j = 0; j < 4; ++j) { unsigned wv[4];
; #pragma unroll
;                 for (int c = 0; c < 4; ++c) {
;                     const f32x2 y = __builtin_elementwise_fma(acc[p][j][c] - mean[j], gg2[c] * rstd[j], bb2[c]);
;                     const f32x2 ne = y * (-LOG2E);
;                     const f32x2 dd = (f32x2){__builtin_amdgcn_exp2f(ne.x), __builtin_amdgcn_exp2f(ne.y)} + 1.0f;
;                     const f32x2 oo = y * (f32x2){__builtin_amdgcn_rcpf(dd.x), __builtin_amdgcn_rcpf(dd.y)};
;                     wv[c] = cvt_pk_bf16(oo.x, oo.y); }
;                 u32x4 w; w.x = wv[0]; w.y = wv[1]; w.z = wv[2]; w.w = wv[3];
;                 *(u32x4*)(C + (size_t)(t0 + 4 * wave + j) * D + p * 512 + lane * 8) = w; }
	v_pk_add_f32 v[0:1], v[0:1], v[4:5]
	ds_bpermute_b32 v5, v76, v1
	ds_bpermute_b32 v4, v76, v0
	v_add_u32_e32 v76, s48, v141
	v_ashrrev_i32_e32 v77, 31, v76
	s_waitcnt lgkmcnt(0)
	v_pk_add_f32 v[0:1], v[0:1], v[4:5]
	s_nop 0
	v_pk_fma_f32 v[0:1], v[0:1], s[4:5], v[2:3] op_sel_hi:[1,0,0]
	s_nop 0
	v_mul_f32_e32 v2, 0x4b800000, v1
	v_cmp_gt_f32_e64 s[42:43], s7, v1
	v_cmp_gt_f32_e64 s[40:41], s7, v0
	s_nop 0
	v_cndmask_b32_e64 v1, v1, v2, s[42:43]
	v_rsq_f32_e32 v1, v1
	s_nop 0
	v_mul_f32_e32 v2, 0x45800000, v1
	v_cndmask_b32_e64 v54, v1, v2, s[42:43]
	v_mul_f32_e32 v1, 0x4b800000, v0
	v_cndmask_b32_e64 v0, v0, v1, s[40:41]
	v_rsq_f32_e32 v0, v0
	s_nop 0
	v_mul_f32_e32 v1, 0x45800000, v0
	v_cndmask_b32_e64 v44, v0, v1, s[40:41]
	global_load_dwordx4 v[0:3], v[88:89], off offset:16
	global_load_dwordx4 v[8:11], v[88:89], off
	global_load_dwordx4 v[4:7], v[90:91], off offset:16
	global_load_dwordx4 v[12:15], v[90:91], off
	v_cmp_le_i32_e64 s[40:41], s37, v140
	s_or_b64 s[46:47], s[40:41], s[46:47]
	s_waitcnt vmcnt(2)
	v_pk_mul_f32 v[100:101], v[40:41], v[8:9] op_sel_hi:[0,1]
	s_waitcnt vmcnt(0)
	v_pk_fma_f32 v[66:67], v[66:67], v[100:101], v[12:13]
	s_nop 0
	v_pk_mul_f32 v[100:101], v[66:67], s[8:9] op_sel_hi:[1,0]
	s_nop 0
	v_exp_f32_e32 v100, v100
	v_exp_f32_e32 v101, v101
	s_nop 0
	v_pk_add_f32 v[100:101], v[100:101], 1.0 op_sel_hi:[1,0]
	s_nop 0
	v_rcp_f32_e32 v100, v100
	v_rcp_f32_e32 v101, v101
	s_nop 0
	v_pk_mul_f32 v[66:67], v[66:67], v[100:101]
	s_nop 0
	v_cvt_pk_bf16_f32 v100, v66, v67
	v_pk_mul_f32 v[66:67], v[40:41], v[10:11] op_sel_hi:[0,1]
	v_pk_fma_f32 v[62:63], v[62:63], v[66:67], v[14:15]
	s_nop 0
	v_pk_mul_f32 v[66:67], v[62:63], s[8:9] op_sel_hi:[1,0]
	s_nop 0
	v_exp_f32_e32 v66, v66
	v_exp_f32_e32 v67, v67
	s_nop 0
	v_pk_add_f32 v[66:67], v[66:67], 1.0 op_sel_hi:[1,0]
	s_nop 0
	v_rcp_f32_e32 v66, v66
	v_rcp_f32_e32 v67, v67
	s_nop 0
	v_pk_mul_f32 v[62:63], v[62:63], v[66:67]
	s_nop 0
	v_cvt_pk_bf16_f32 v101, v62, v63
	v_pk_mul_f32 v[62:63], v[40:41], v[0:1] op_sel_hi:[0,1]
	v_pk_fma_f32 v[58:59], v[58:59], v[62:63], v[4:5]
	s_nop 0
	v_pk_mul_f32 v[62:63], v[58:59], s[8:9] op_sel_hi:[1,0]
	s_nop 0
	v_exp_f32_e32 v62, v62
	v_exp_f32_e32 v63, v63
	s_nop 0
	v_pk_add_f32 v[62:63], v[62:63], 1.0 op_sel_hi:[1,0]
	s_nop 0
	v_rcp_f32_e32 v62, v62
	v_rcp_f32_e32 v63, v63
	s_nop 0
	v_pk_mul_f32 v[58:59], v[58:59], v[62:63]
	s_nop 0
	v_cvt_pk_bf16_f32 v102, v58, v59
	v_pk_mul_f32 v[58:59], v[40:41], v[2:3] op_sel_hi:[0,1]
	v_pk_fma_f32 v[56:57], v[56:57], v[58:59], v[6:7]
	s_nop 0
	v_pk_mul_f32 v[58:59], v[56:57], s[8:9] op_sel_hi:[1,0]
	s_nop 0
	v_exp_f32_e32 v58, v58
	v_exp_f32_e32 v59, v59
	s_nop 0
	v_pk_add_f32 v[58:59], v[58:59], 1.0 op_sel_hi:[1,0]
	s_nop 0
	v_rcp_f32_e32 v58, v58
	v_rcp_f32_e32 v59, v59
	s_nop 0
	v_pk_mul_f32 v[56:57], v[56:57], v[58:59]
	v_pk_mul_f32 v[58:59], v[26:27], v[8:9] op_sel_hi:[0,1]
	v_pk_fma_f32 v[58:59], v[70:71], v[58:59], v[12:13]
	v_cvt_pk_bf16_f32 v103, v56, v57
	v_lshlrev_b64 v[56:57], 11, v[76:77]
	v_pk_mul_f32 v[62:63], v[58:59], s[8:9] op_sel_hi:[1,0]
	v_lshl_add_u64 v[56:57], v[92:93], 0, v[56:57]
	v_exp_f32_e32 v62, v62
	v_exp_f32_e32 v63, v63
	global_store_dwordx4 v[56:57], v[100:103], off
	v_pk_add_f32 v[62:63], v[62:63], 1.0 op_sel_hi:[1,0]
	s_nop 0
	v_rcp_f32_e32 v62, v62
	v_rcp_f32_e32 v63, v63
	s_nop 0
	v_pk_mul_f32 v[58:59], v[58:59], v[62:63]
	s_nop 0
	v_cvt_pk_bf16_f32 v62, v58, v59
	v_pk_mul_f32 v[58:59], v[26:27], v[10:11] op_sel_hi:[0,1]
	v_pk_fma_f32 v[58:59], v[68:69], v[58:59], v[14:15]
	s_nop 0
	v_pk_mul_f32 v[66:67], v[58:59], s[8:9] op_sel_hi:[1,0]
	s_nop 0
	v_exp_f32_e32 v66, v66
	v_exp_f32_e32 v67, v67
	s_nop 0
	v_pk_add_f32 v[66:67], v[66:67], 1.0 op_sel_hi:[1,0]
	s_nop 0
	v_rcp_f32_e32 v66, v66
	v_rcp_f32_e32 v67, v67
	s_nop 0
	v_pk_mul_f32 v[58:59], v[58:59], v[66:67]
	s_nop 0
	v_cvt_pk_bf16_f32 v63, v58, v59
	v_pk_mul_f32 v[58:59], v[26:27], v[0:1] op_sel_hi:[0,1]
	v_pk_fma_f32 v[58:59], v[64:65], v[58:59], v[4:5]
	s_nop 0
	v_pk_mul_f32 v[64:65], v[58:59], s[8:9] op_sel_hi:[1,0]
	s_nop 0
	v_exp_f32_e32 v64, v64
	v_exp_f32_e32 v65, v65
	s_nop 0
	v_pk_add_f32 v[64:65], v[64:65], 1.0 op_sel_hi:[1,0]
	s_nop 0
	v_rcp_f32_e32 v64, v64
	v_rcp_f32_e32 v65, v65
	s_nop 0
	v_pk_mul_f32 v[58:59], v[58:59], v[64:65]
	s_nop 0
	v_cvt_pk_bf16_f32 v64, v58, v59
	v_pk_mul_f32 v[58:59], v[26:27], v[2:3] op_sel_hi:[0,1]
	v_pk_fma_f32 v[58:59], v[60:61], v[58:59], v[6:7]
	s_nop 0
	v_pk_mul_f32 v[60:61], v[58:59], s[8:9] op_sel_hi:[1,0]
	s_nop 0
	v_exp_f32_e32 v60, v60
	v_exp_f32_e32 v61, v61
	s_nop 0
	v_pk_add_f32 v[60:61], v[60:61], 1.0 op_sel_hi:[1,0]
	s_nop 0
	v_rcp_f32_e32 v60, v60
	v_rcp_f32_e32 v61, v61
	s_nop 0
	v_pk_mul_f32 v[58:59], v[58:59], v[60:61]
	s_nop 0
	v_cvt_pk_bf16_f32 v65, v58, v59
	v_or_b32_e32 v58, 1, v76
	v_ashrrev_i32_e32 v59, 31, v58
	v_lshlrev_b64 v[58:59], 11, v[58:59]
	v_pk_mul_f32 v[60:61], v[8:9], v[54:55] op_sel_hi:[1,0]
	v_lshl_add_u64 v[58:59], v[92:93], 0, v[58:59]
	v_pk_fma_f32 v[60:61], v[112:113], v[60:61], v[12:13]
	global_store_dwordx4 v[58:59], v[62:65], off
	v_pk_mul_f32 v[8:9], v[8:9], v[44:45] op_sel_hi:[1,0]
	s_nop 0
	v_pk_mul_f32 v[62:63], v[60:61], s[8:9] op_sel_hi:[1,0]
	v_pk_fma_f32 v[8:9], v[108:109], v[8:9], v[12:13]
	v_exp_f32_e32 v62, v62
	v_exp_f32_e32 v63, v63
	v_pk_mul_f32 v[12:13], v[8:9], s[8:9] op_sel_hi:[1,0]
	v_pk_add_f32 v[62:63], v[62:63], 1.0 op_sel_hi:[1,0]
	s_nop 0
	v_rcp_f32_e32 v62, v62
	v_rcp_f32_e32 v63, v63
	v_exp_f32_e32 v12, v12
	v_exp_f32_e32 v13, v13
	v_pk_mul_f32 v[60:61], v[60:61], v[62:63]
	s_nop 0
	v_cvt_pk_bf16_f32 v62, v60, v61
	v_pk_mul_f32 v[60:61], v[10:11], v[54:55] op_sel_hi:[1,0]
; __device__ __forceinline__ unsigned cvt_pk_bf16(float lo, float hi) { unsigned r; asm volatile("v_cvt_pk_bf16_f32 %0, %1, %2" : "=v"(r) : "v"(lo), "v"(hi)); return r; }
; __device__ __forceinline__ void conv_phase(LAS unsigned char* lds, const bf16_t* U, bf16_t* C, const float* wdw, const float* bdw, const float* lng, const float* lnb,
;                                            int first, int stride, int end, int tid, int wave, int lane) {
;     ...
;         for (int p = 0; p < 2; ++p) {
;             const f32x4 g0 = *(const f32x4*)(lng + p * 512 + lane * 8), g1 = *(const f32x4*)(lng + p * 512 + lane * 8 + 4);
;             const f32x4 c0 = *(const f32x4*)(lnb + p * 512 + lane * 8), c1 = *(const f32x4*)(lnb + p * 512 + lane * 8 + 4);
;             const f32x2 gg2[4] = {(f32x2){g0.x, g0.y}, (f32x2){g0.z, g0.w}, (f32x2){g1.x, g1.y}, (f32x2){g1.z, g1.w}}, bb2[4] = {(f32x2){c0.x, c0.y}, (f32x2){c0.z, c0.w}, (f32x2){c1.x, c1.y}, (f32x2){c1.z, c1.w}};
; #pragma unroll
;             for (int j = 0; j < 4; ++j) { unsigned wv[4];
; #pragma unroll
;                 for (int c = 0; c < 4; ++c) {
;                     const f32x2 y = __builtin_elementwise_fma(acc[p][j][c] - mean[j], gg2[c] * rstd[j], bb2[c]);
;                     const f32x2 ne = y * (-LOG2E);
;                     const f32x2 dd = (f32x2){__builtin_amdgcn_exp2f(ne.x), __builtin_amdgcn_exp2f(ne.y)} + 1.0f;
;                     const f32x2 oo = y * (f32x2){__builtin_amdgcn_rcpf(dd.x), __builtin_amdgcn_rcpf(dd.y)};
;                     wv[c] = cvt_pk_bf16(oo.x, oo.y); }
;                 u32x4 w; w.x = wv[0]; w.y = wv[1]; w.z = wv[2]; w.w = wv[3];
;                 *(u32x4*)(C + (size_t)(t0 + 4 * wave + j) * D + p * 512 + lane * 8) = w; }
	v_pk_add_f32 v[12:13], v[12:13], 1.0 op_sel_hi:[1,0]
	v_pk_fma_f32 v[60:61], v[82:83], v[60:61], v[14:15]
	v_rcp_f32_e32 v12, v12
	v_pk_mul_f32 v[64:65], v[60:61], s[8:9] op_sel_hi:[1,0]
	v_rcp_f32_e32 v13, v13
	v_exp_f32_e32 v64, v64
	v_exp_f32_e32 v65, v65
	v_pk_mul_f32 v[10:11], v[10:11], v[44:45] op_sel_hi:[1,0]
	v_pk_mul_f32 v[8:9], v[8:9], v[12:13]
	v_pk_fma_f32 v[10:11], v[104:105], v[10:11], v[14:15]
	v_pk_add_f32 v[64:65], v[64:65], 1.0 op_sel_hi:[1,0]
	v_pk_mul_f32 v[12:13], v[10:11], s[8:9] op_sel_hi:[1,0]
	v_rcp_f32_e32 v64, v64
	v_rcp_f32_e32 v65, v65
	v_exp_f32_e32 v12, v12
	v_exp_f32_e32 v13, v13
	v_pk_mul_f32 v[60:61], v[60:61], v[64:65]
	s_nop 0
	v_cvt_pk_bf16_f32 v63, v60, v61
	v_pk_mul_f32 v[60:61], v[0:1], v[54:55] op_sel_hi:[1,0]
	v_pk_mul_f32 v[0:1], v[0:1], v[44:45] op_sel_hi:[1,0]
	v_pk_fma_f32 v[60:61], v[78:79], v[60:61], v[4:5]
	v_pk_fma_f32 v[0:1], v[80:81], v[0:1], v[4:5]
	v_pk_mul_f32 v[64:65], v[60:61], s[8:9] op_sel_hi:[1,0]
	v_pk_mul_f32 v[4:5], v[0:1], s[8:9] op_sel_hi:[1,0]
	v_exp_f32_e32 v64, v64
	v_exp_f32_e32 v65, v65
	v_exp_f32_e32 v4, v4
	v_exp_f32_e32 v5, v5
	v_pk_add_f32 v[12:13], v[12:13], 1.0 op_sel_hi:[1,0]
	v_pk_add_f32 v[64:65], v[64:65], 1.0 op_sel_hi:[1,0]
	v_rcp_f32_e32 v12, v12
	v_rcp_f32_e32 v64, v64
	v_rcp_f32_e32 v65, v65
	v_pk_add_f32 v[4:5], v[4:5], 1.0 op_sel_hi:[1,0]
	v_rcp_f32_e32 v13, v13
	v_rcp_f32_e32 v4, v4
	v_pk_mul_f32 v[60:61], v[60:61], v[64:65]
	v_rcp_f32_e32 v5, v5
	v_cvt_pk_bf16_f32 v64, v60, v61
	v_pk_mul_f32 v[60:61], v[2:3], v[54:55] op_sel_hi:[1,0]
	v_pk_mul_f32 v[10:11], v[10:11], v[12:13]
	v_pk_fma_f32 v[60:61], v[72:73], v[60:61], v[6:7]
	v_pk_mul_f32 v[0:1], v[0:1], v[4:5]
	v_pk_mul_f32 v[66:67], v[60:61], s[8:9] op_sel_hi:[1,0]
	s_nop 0
	v_exp_f32_e32 v66, v66
	v_exp_f32_e32 v67, v67
	s_nop 0
	v_pk_add_f32 v[66:67], v[66:67], 1.0 op_sel_hi:[1,0]
	s_nop 0
	v_rcp_f32_e32 v66, v66
	v_rcp_f32_e32 v67, v67
	s_nop 0
	v_pk_mul_f32 v[60:61], v[60:61], v[66:67]
	s_nop 0
	v_cvt_pk_bf16_f32 v65, v60, v61
	v_or_b32_e32 v60, 2, v76
	v_ashrrev_i32_e32 v61, 31, v60
	v_lshlrev_b64 v[60:61], 11, v[60:61]
	v_lshl_add_u64 v[60:61], v[92:93], 0, v[60:61]
	global_store_dwordx4 v[60:61], v[62:65], off
	v_cvt_pk_bf16_f32 v8, v8, v9
	v_cvt_pk_bf16_f32 v9, v10, v11
	v_cvt_pk_bf16_f32 v10, v0, v1
	v_pk_mul_f32 v[0:1], v[2:3], v[44:45] op_sel_hi:[1,0]
	s_nop 0
	v_pk_fma_f32 v[0:1], v[74:75], v[0:1], v[6:7]
	s_nop 0
	v_pk_mul_f32 v[2:3], v[0:1], s[8:9] op_sel_hi:[1,0]
	s_nop 0
	v_exp_f32_e32 v2, v2
	v_exp_f32_e32 v3, v3
	s_nop 0
	v_pk_add_f32 v[2:3], v[2:3], 1.0 op_sel_hi:[1,0]
	s_nop 0
	v_rcp_f32_e32 v2, v2
	v_rcp_f32_e32 v3, v3
	s_nop 0
	v_pk_mul_f32 v[0:1], v[0:1], v[2:3]
	s_nop 0
	v_cvt_pk_bf16_f32 v11, v0, v1
	v_or_b32_e32 v0, 3, v76
	v_ashrrev_i32_e32 v1, 31, v0
	v_lshlrev_b64 v[0:1], 11, v[0:1]
	v_lshl_add_u64 v[62:63], v[92:93], 0, v[0:1]
	global_store_dwordx4 v[62:63], v[8:11], off
	global_load_dwordx4 v[0:3], v[88:89], off offset:2064
	s_nop 0
	global_load_dwordx4 v[8:11], v[88:89], off offset:2048
	global_load_dwordx4 v[4:7], v[90:91], off offset:2064
	global_load_dwordx4 v[12:15], v[90:91], off offset:2048
	s_waitcnt vmcnt(2)
	v_pk_mul_f32 v[64:65], v[40:41], v[8:9] op_sel_hi:[0,1]
	s_waitcnt vmcnt(0)
; __device__ __forceinline__ unsigned cvt_pk_bf16(float lo, float hi) { unsigned r; asm volatile("v_cvt_pk_bf16_f32 %0, %1, %2" : "=v"(r) : "v"(lo), "v"(hi)); return r; }
; __device__ __forceinline__ void conv_phase(LAS unsigned char* lds, const bf16_t* U, bf16_t* C, const float* wdw, const float* bdw, const float* lng, const float* lnb,
;                                            int first, int stride, int end, int tid, int wave, int lane) {
;     ...
;             for (int j = 0; j < 4; ++j) { unsigned wv[4];
; #pragma unroll
;                 for (int c = 0; c < 4; ++c) {
;                     const f32x2 y = __builtin_elementwise_fma(acc[p][j][c] - mean[j], gg2[c] * rstd[j], bb2[c]);
;                     const f32x2 ne = y * (-LOG2E);
;                     const f32x2 dd = (f32x2){__builtin_amdgcn_exp2f(ne.x), __builtin_amdgcn_exp2f(ne.y)} + 1.0f;
;                     const f32x2 oo = y * (f32x2){__builtin_amdgcn_rcpf(dd.x), __builtin_amdgcn_rcpf(dd.y)};
;                     wv[c] = cvt_pk_bf16(oo.x, oo.y); }
;                 u32x4 w; w.x = wv[0]; w.y = wv[1]; w.z = wv[2]; w.w = wv[3];
;                 *(u32x4*)(C + (size_t)(t0 + 4 * wave + j) * D + p * 512 + lane * 8) = w; }
;         }
;         asm volatile("s_waitcnt lgkmcnt(0)" ::: "memory"); __builtin_amdgcn_s_barrier(); asm volatile("" ::: "memory");
	v_pk_fma_f32 v[28:29], v[28:29], v[64:65], v[12:13]
	s_nop 0
	v_pk_mul_f32 v[64:65], v[28:29], s[8:9] op_sel_hi:[1,0]
	s_nop 0
	v_exp_f32_e32 v64, v64
	v_exp_f32_e32 v65, v65
	s_nop 0
	v_pk_add_f32 v[64:65], v[64:65], 1.0 op_sel_hi:[1,0]
	s_nop 0
	v_rcp_f32_e32 v64, v64
	v_rcp_f32_e32 v65, v65
	s_nop 0
	v_pk_mul_f32 v[28:29], v[28:29], v[64:65]
	s_nop 0
	v_cvt_pk_bf16_f32 v64, v28, v29
	v_pk_mul_f32 v[28:29], v[40:41], v[10:11] op_sel_hi:[0,1]
	v_pk_fma_f32 v[22:23], v[22:23], v[28:29], v[14:15]
	s_nop 0
	v_pk_mul_f32 v[28:29], v[22:23], s[8:9] op_sel_hi:[1,0]
	s_nop 0
	v_exp_f32_e32 v28, v28
	v_exp_f32_e32 v29, v29
	s_nop 0
	v_pk_add_f32 v[28:29], v[28:29], 1.0 op_sel_hi:[1,0]
	s_nop 0
	v_rcp_f32_e32 v28, v28
	v_rcp_f32_e32 v29, v29
	s_nop 0
	v_pk_mul_f32 v[22:23], v[22:23], v[28:29]
	s_nop 0
	v_cvt_pk_bf16_f32 v65, v22, v23
	v_pk_mul_f32 v[22:23], v[40:41], v[0:1] op_sel_hi:[0,1]
	v_pk_fma_f32 v[18:19], v[18:19], v[22:23], v[4:5]
	s_nop 0
	v_pk_mul_f32 v[22:23], v[18:19], s[8:9] op_sel_hi:[1,0]
	s_nop 0
	v_exp_f32_e32 v22, v22
	v_exp_f32_e32 v23, v23
	s_nop 0
	v_pk_add_f32 v[22:23], v[22:23], 1.0 op_sel_hi:[1,0]
	s_nop 0
	v_rcp_f32_e32 v22, v22
	v_rcp_f32_e32 v23, v23
	s_nop 0
	v_pk_mul_f32 v[18:19], v[18:19], v[22:23]
	s_nop 0
	v_cvt_pk_bf16_f32 v66, v18, v19
	v_pk_mul_f32 v[18:19], v[40:41], v[2:3] op_sel_hi:[0,1]
	v_pk_fma_f32 v[16:17], v[16:17], v[18:19], v[6:7]
	s_nop 0
	v_pk_mul_f32 v[18:19], v[16:17], s[8:9] op_sel_hi:[1,0]
	s_nop 0
	v_exp_f32_e32 v18, v18
	v_exp_f32_e32 v19, v19
	s_nop 0
	v_pk_add_f32 v[18:19], v[18:19], 1.0 op_sel_hi:[1,0]
	s_nop 0
	v_rcp_f32_e32 v18, v18
	v_rcp_f32_e32 v19, v19
	s_nop 0
	v_pk_mul_f32 v[16:17], v[16:17], v[18:19]
	s_nop 0
	v_cvt_pk_bf16_f32 v67, v16, v17
	v_pk_mul_f32 v[16:17], v[26:27], v[8:9] op_sel_hi:[0,1]
	v_pk_fma_f32 v[16:17], v[32:33], v[16:17], v[12:13]
	global_store_dwordx4 v[56:57], v[64:67], off offset:1024
	v_pk_mul_f32 v[18:19], v[16:17], s[8:9] op_sel_hi:[1,0]
	s_nop 0
	v_exp_f32_e32 v18, v18
	v_exp_f32_e32 v19, v19
	s_nop 0
	v_pk_add_f32 v[18:19], v[18:19], 1.0 op_sel_hi:[1,0]
	s_nop 0
	v_rcp_f32_e32 v18, v18
	v_rcp_f32_e32 v19, v19
	s_nop 0
	v_pk_mul_f32 v[16:17], v[16:17], v[18:19]
	v_pk_mul_f32 v[18:19], v[26:27], v[10:11] op_sel_hi:[0,1]
	v_pk_fma_f32 v[18:19], v[30:31], v[18:19], v[14:15]
	v_cvt_pk_bf16_f32 v16, v16, v17
	s_nop 0
	v_pk_mul_f32 v[22:23], v[18:19], s[8:9] op_sel_hi:[1,0]
	s_nop 0
	v_exp_f32_e32 v22, v22
	v_exp_f32_e32 v23, v23
	s_nop 0
	v_pk_add_f32 v[22:23], v[22:23], 1.0 op_sel_hi:[1,0]
	s_nop 0
	v_rcp_f32_e32 v22, v22
	v_rcp_f32_e32 v23, v23
	s_nop 0
	v_pk_mul_f32 v[18:19], v[18:19], v[22:23]
	s_nop 0
	v_cvt_pk_bf16_f32 v17, v18, v19
	v_pk_mul_f32 v[18:19], v[26:27], v[0:1] op_sel_hi:[0,1]
	v_pk_fma_f32 v[18:19], v[24:25], v[18:19], v[4:5]
	s_nop 0
	v_pk_mul_f32 v[22:23], v[18:19], s[8:9] op_sel_hi:[1,0]
	s_nop 0
	v_exp_f32_e32 v22, v22
	v_exp_f32_e32 v23, v23
	s_nop 0
	v_pk_add_f32 v[22:23], v[22:23], 1.0 op_sel_hi:[1,0]
	s_nop 0
	v_rcp_f32_e32 v22, v22
	v_rcp_f32_e32 v23, v23
	s_nop 0
	v_pk_mul_f32 v[18:19], v[18:19], v[22:23]
	v_pk_mul_f32 v[22:23], v[26:27], v[2:3] op_sel_hi:[0,1]
	v_pk_fma_f32 v[20:21], v[20:21], v[22:23], v[6:7]
	v_cvt_pk_bf16_f32 v18, v18, v19
	s_nop 0
	v_pk_mul_f32 v[22:23], v[20:21], s[8:9] op_sel_hi:[1,0]
	s_nop 0
	v_exp_f32_e32 v22, v22
	v_exp_f32_e32 v23, v23
	s_nop 0
	v_pk_add_f32 v[22:23], v[22:23], 1.0 op_sel_hi:[1,0]
	s_nop 0
	v_rcp_f32_e32 v22, v22
	v_rcp_f32_e32 v23, v23
	s_nop 0
	v_pk_mul_f32 v[20:21], v[20:21], v[22:23]
	s_nop 0
	v_cvt_pk_bf16_f32 v19, v20, v21
	global_store_dwordx4 v[58:59], v[16:19], off offset:1024
	s_nop 1
	v_pk_mul_f32 v[16:17], v[54:55], v[8:9] op_sel_hi:[0,1]
	v_pk_fma_f32 v[16:17], v[50:51], v[16:17], v[12:13]
	v_pk_mul_f32 v[8:9], v[44:45], v[8:9] op_sel_hi:[0,1]
	v_pk_mul_f32 v[18:19], v[16:17], s[8:9] op_sel_hi:[1,0]
	v_pk_fma_f32 v[8:9], v[52:53], v[8:9], v[12:13]
	v_exp_f32_e32 v18, v18
	v_exp_f32_e32 v19, v19
	v_pk_mul_f32 v[12:13], v[8:9], s[8:9] op_sel_hi:[1,0]
	v_pk_add_f32 v[18:19], v[18:19], 1.0 op_sel_hi:[1,0]
	s_nop 0
	v_rcp_f32_e32 v18, v18
	v_rcp_f32_e32 v19, v19
	v_exp_f32_e32 v12, v12
	v_exp_f32_e32 v13, v13
	v_pk_mul_f32 v[16:17], v[16:17], v[18:19]
	v_pk_mul_f32 v[18:19], v[54:55], v[10:11] op_sel_hi:[0,1]
	v_pk_fma_f32 v[18:19], v[46:47], v[18:19], v[14:15]
	v_cvt_pk_bf16_f32 v16, v16, v17
	v_pk_add_f32 v[12:13], v[12:13], 1.0 op_sel_hi:[1,0]
	v_pk_mul_f32 v[20:21], v[18:19], s[8:9] op_sel_hi:[1,0]
	v_rcp_f32_e32 v12, v12
	v_exp_f32_e32 v20, v20
	v_exp_f32_e32 v21, v21
	v_rcp_f32_e32 v13, v13
	v_pk_mul_f32 v[10:11], v[44:45], v[10:11] op_sel_hi:[0,1]
	v_pk_fma_f32 v[10:11], v[48:49], v[10:11], v[14:15]
	v_pk_add_f32 v[20:21], v[20:21], 1.0 op_sel_hi:[1,0]
	v_pk_mul_f32 v[8:9], v[8:9], v[12:13]
	v_rcp_f32_e32 v20, v20
	v_rcp_f32_e32 v21, v21
	v_pk_mul_f32 v[12:13], v[10:11], s[8:9] op_sel_hi:[1,0]
	v_pk_mul_f32 v[18:19], v[18:19], v[20:21]
	s_nop 0
	v_cvt_pk_bf16_f32 v17, v18, v19
	v_pk_mul_f32 v[18:19], v[54:55], v[0:1] op_sel_hi:[0,1]
	v_pk_fma_f32 v[18:19], v[38:39], v[18:19], v[4:5]
	v_pk_mul_f32 v[0:1], v[44:45], v[0:1] op_sel_hi:[0,1]
	v_pk_mul_f32 v[20:21], v[18:19], s[8:9] op_sel_hi:[1,0]
	v_pk_fma_f32 v[0:1], v[42:43], v[0:1], v[4:5]
	v_exp_f32_e32 v20, v20
	v_exp_f32_e32 v21, v21
	v_pk_mul_f32 v[4:5], v[0:1], s[8:9] op_sel_hi:[1,0]
	v_exp_f32_e32 v12, v12
	v_exp_f32_e32 v13, v13
	v_pk_add_f32 v[20:21], v[20:21], 1.0 op_sel_hi:[1,0]
	v_exp_f32_e32 v4, v4
	v_rcp_f32_e32 v20, v20
	v_rcp_f32_e32 v21, v21
	v_exp_f32_e32 v5, v5
	v_pk_add_f32 v[12:13], v[12:13], 1.0 op_sel_hi:[1,0]
	v_pk_mul_f32 v[18:19], v[18:19], v[20:21]
	v_pk_mul_f32 v[20:21], v[54:55], v[2:3] op_sel_hi:[0,1]
	v_pk_fma_f32 v[20:21], v[34:35], v[20:21], v[6:7]
	v_pk_add_f32 v[4:5], v[4:5], 1.0 op_sel_hi:[1,0]
	v_pk_mul_f32 v[22:23], v[20:21], s[8:9] op_sel_hi:[1,0]
	v_rcp_f32_e32 v12, v12
	v_exp_f32_e32 v22, v22
	v_exp_f32_e32 v23, v23
	v_rcp_f32_e32 v13, v13
	v_rcp_f32_e32 v4, v4
	v_rcp_f32_e32 v5, v5
	v_pk_add_f32 v[22:23], v[22:23], 1.0 op_sel_hi:[1,0]
	v_pk_mul_f32 v[10:11], v[10:11], v[12:13]
	v_rcp_f32_e32 v22, v22
	v_rcp_f32_e32 v23, v23
	v_pk_mul_f32 v[0:1], v[0:1], v[4:5]
	v_cvt_pk_bf16_f32 v18, v18, v19
	v_pk_mul_f32 v[20:21], v[20:21], v[22:23]
	s_nop 0
	v_cvt_pk_bf16_f32 v19, v20, v21
	global_store_dwordx4 v[60:61], v[16:19], off offset:1024
	v_cvt_pk_bf16_f32 v8, v8, v9
	v_cvt_pk_bf16_f32 v9, v10, v11
	v_cvt_pk_bf16_f32 v10, v0, v1
	v_pk_mul_f32 v[0:1], v[44:45], v[2:3] op_sel_hi:[0,1]
	v_pk_fma_f32 v[0:1], v[36:37], v[0:1], v[6:7]
	s_nop 0
	v_pk_mul_f32 v[2:3], v[0:1], s[8:9] op_sel_hi:[1,0]
	s_nop 0
	v_exp_f32_e32 v2, v2
	v_exp_f32_e32 v3, v3
	s_nop 0
	v_pk_add_f32 v[2:3], v[2:3], 1.0 op_sel_hi:[1,0]
	s_nop 0
	v_rcp_f32_e32 v2, v2
	v_rcp_f32_e32 v3, v3
	s_nop 0
	v_pk_mul_f32 v[0:1], v[0:1], v[2:3]
	s_nop 0
	v_cvt_pk_bf16_f32 v11, v0, v1
	global_store_dwordx4 v[62:63], v[8:11], off offset:1024
	s_waitcnt lgkmcnt(0)
	s_barrier
	s_andn2_b64 exec, exec, s[46:47]
	s_cbranch_execz .LBB0_95

; __device__ __forceinline__ unsigned cvt_pk_bf16(float lo, float hi) { unsigned r; asm volatile("v_cvt_pk_bf16_f32 %0, %1, %2" : "=v"(r) : "v"(lo), "v"(hi)); return r; }
; #define LAS __attribute__((address_space(3)))
; __device__ __forceinline__ void rs_finish(LAS unsigned char* lds, int buf, int tid, const f32x4& a, const f32x4& b) {
;     float t = ((a.x + a.y) + (a.z + a.w)) + ((b.x + b.y) + (b.z + b.w)); t += __shfl_xor(t, 1);
;     if (!(tid & 1)) ((LAS float*)(lds + RS_LDS_OFF))[buf * 256 + (tid >> 1)] = rsqrtf(t * (1.f / D) + RMS_EPS);
; }
;     __device__ __forceinline__ void operator()(const f32x4 (&acc)[2][2][4][2], const Unit& u, int wr, int wc, int fr, int fq, LAS unsigned char* lds, int tid, int ui, const Unit& nxt, bool has_next) const {
;         f32x4 na, nb; if (has_next) rs_issue(ssp, nxt, tid, na, nb);
;         const int row0 = u.pm * 256 + wr * 64 + fr; const int t = u.pn >> 2;
;         bf16_t* base = O + (size_t)t * tstride; const int col0 = (u.pn & 3) * 256 + wc * 32 + 8 * fq;
;         float rsv[2][4]; rs_read(lds, ui & 1, wr, fr, rsv);
; #pragma unroll
;         for (int ai = 0; ai < 2; ++ai)
; #pragma unroll
;             for (int m = 0; m < 4; ++m) {
;                 const int row = row0 + ai * 128 + m * 16;
;                 const float rs = rsv[ai][m];
; #pragma unroll
;                 for (int bj = 0; bj < 2; ++bj) {
;                     const f32x4 v0 = acc[ai][bj][m][0] * rs, v1 = acc[ai][bj][m][1] * rs;
;                     u32x4 w; w.x = cvt_pk_bf16(v0[0], v0[1]); w.y = cvt_pk_bf16(v0[2], v0[3]); w.z = cvt_pk_bf16(v1[0], v1[1]); w.w = cvt_pk_bf16(v1[2], v1[3]);
;                     *(u32x4*)(base + (size_t)row * D + col0 + bj * 128) = w;
;                 }
;             }
;         if (has_next) rs_finish(lds, (ui + 1) & 1, tid, na, nb);
.Lmy_epibar_qkv:
	v_pk_mul_f32 v[54:55], v[54:55], v[154:155] op_sel_hi:[1,0]
	v_pk_mul_f32 v[52:53], v[52:53], v[154:155] op_sel_hi:[1,0]
	v_or_b32_e32 v92, 32, v164
	v_ashrrev_i32_e32 v93, 31, v92
	v_lshlrev_b64 v[92:93], 11, v[92:93]
	v_lshl_add_u64 v[92:93], v[170:171], 0, v[92:93]
	v_pk_mul_f32 v[94:95], v[98:99], v[168:169] op_sel_hi:[1,0]
	v_pk_mul_f32 v[98:99], v[90:91], v[168:169] op_sel_hi:[1,0]
	v_pk_mul_f32 v[90:91], v[88:89], v[168:169] op_sel_hi:[1,0]
	v_cvt_pk_bf16_f32 v88, v96, v97
	v_cvt_pk_bf16_f32 v89, v94, v95
	v_pk_mul_f32 v[32:33], v[32:33], v[152:153] op_sel_hi:[1,0]
	v_cvt_pk_bf16_f32 v90, v90, v91
	v_cvt_pk_bf16_f32 v91, v98, v99
	global_store_dwordx4 v[92:93], v[88:91], off
	v_pk_mul_f32 v[22:23], v[22:23], v[152:153] op_sel_hi:[1,0]
	v_pk_mul_f32 v[20:21], v[20:21], v[152:153] op_sel_hi:[1,0]
	v_pk_mul_f32 v[88:89], v[78:79], v[168:169] op_sel_hi:[1,0]
	v_pk_mul_f32 v[78:79], v[76:77], v[168:169] op_sel_hi:[1,0]
	v_cvt_pk_bf16_f32 v76, v84, v85
	v_cvt_pk_bf16_f32 v77, v86, v87
	s_nop 0
	v_cvt_pk_bf16_f32 v78, v78, v79
	v_cvt_pk_bf16_f32 v79, v88, v89
	global_store_dwordx4 v[92:93], v[76:79], off offset:256
	s_nop 1
	v_or_b32_e32 v76, 48, v164
	v_ashrrev_i32_e32 v77, 31, v76
	v_lshlrev_b64 v[76:77], 11, v[76:77]
	v_mov_b32_e32 v78, v169
	v_lshl_add_u64 v[76:77], v[170:171], 0, v[76:77]
	v_pk_mul_f32 v[82:83], v[82:83], v[78:79] op_sel_hi:[1,0]
	v_pk_mul_f32 v[80:81], v[80:81], v[78:79] op_sel_hi:[1,0]
	v_pk_mul_f32 v[84:85], v[74:75], v[78:79] op_sel_hi:[1,0]
	v_pk_mul_f32 v[74:75], v[72:73], v[78:79] op_sel_hi:[1,0]
	v_cvt_pk_bf16_f32 v72, v80, v81
	v_cvt_pk_bf16_f32 v73, v82, v83
	v_pk_mul_f32 v[70:71], v[70:71], v[78:79] op_sel_hi:[1,0]
	v_cvt_pk_bf16_f32 v74, v74, v75
	v_cvt_pk_bf16_f32 v75, v84, v85
	global_store_dwordx4 v[76:77], v[72:75], off
	v_pk_mul_f32 v[68:69], v[68:69], v[78:79] op_sel_hi:[1,0]
	s_nop 0
	v_pk_mul_f32 v[72:73], v[66:67], v[78:79] op_sel_hi:[1,0]
	v_pk_mul_f32 v[66:67], v[64:65], v[78:79] op_sel_hi:[1,0]
	v_cvt_pk_bf16_f32 v64, v68, v69
	v_cvt_pk_bf16_f32 v65, v70, v71
	s_nop 0
	v_cvt_pk_bf16_f32 v66, v66, v67
	v_cvt_pk_bf16_f32 v67, v72, v73
	global_store_dwordx4 v[76:77], v[64:67], off offset:256
	s_nop 1
	v_pk_mul_f32 v[66:67], v[58:59], v[154:155] op_sel_hi:[1,0]
	v_pk_mul_f32 v[58:59], v[56:57], v[154:155] op_sel_hi:[1,0]
	v_cvt_pk_bf16_f32 v56, v60, v61
	v_add_co_u32_e32 v60, vcc, s33, v150
	v_cvt_pk_bf16_f32 v57, v62, v63
	v_cvt_pk_bf16_f32 v58, v58, v59
	v_cvt_pk_bf16_f32 v59, v66, v67
	v_lshl_add_u64 v[64:65], v[150:151], 0, s[4:5]
	s_nop 0
	v_addc_co_u32_e32 v61, vcc, 0, v151, vcc
	global_store_dwordx4 v[60:61], v[56:59], off
	s_mov_b64 s[4:5], 0x48000
	s_nop 0
	v_pk_mul_f32 v[56:57], v[46:47], v[154:155] op_sel_hi:[1,0]
	v_pk_mul_f32 v[46:47], v[44:45], v[154:155] op_sel_hi:[1,0]
	v_cvt_pk_bf16_f32 v44, v52, v53
	v_cvt_pk_bf16_f32 v45, v54, v55
	s_nop 0
	v_cvt_pk_bf16_f32 v46, v46, v47
	v_cvt_pk_bf16_f32 v47, v56, v57
	global_store_dwordx4 v[64:65], v[44:47], off offset:256
	s_nop 1
	v_mov_b32_e32 v46, v155
	v_pk_mul_f32 v[48:49], v[48:49], v[46:47] op_sel_hi:[1,0]
	v_pk_mul_f32 v[52:53], v[42:43], v[46:47] op_sel_hi:[1,0]
	v_pk_mul_f32 v[42:43], v[40:41], v[46:47] op_sel_hi:[1,0]
	v_cvt_pk_bf16_f32 v40, v48, v49
	v_add_co_u32_e32 v48, vcc, s86, v150
	v_pk_mul_f32 v[50:51], v[50:51], v[46:47] op_sel_hi:[1,0]
	s_nop 0
	v_addc_co_u32_e32 v49, vcc, 0, v151, vcc
	v_cvt_pk_bf16_f32 v41, v50, v51
	v_cvt_pk_bf16_f32 v42, v42, v43
	v_cvt_pk_bf16_f32 v43, v52, v53
	global_store_dwordx4 v[48:49], v[40:43], off
	v_lshl_add_u64 v[44:45], v[150:151], 0, s[4:5]
	v_pk_mul_f32 v[38:39], v[38:39], v[46:47] op_sel_hi:[1,0]
	v_pk_mul_f32 v[40:41], v[30:31], v[46:47] op_sel_hi:[1,0]
	v_pk_mul_f32 v[30:31], v[28:29], v[46:47] op_sel_hi:[1,0]
	v_pk_mul_f32 v[36:37], v[36:37], v[46:47] op_sel_hi:[1,0]
	s_mov_b64 s[4:5], 0x50000
	v_cvt_pk_bf16_f32 v28, v36, v37
	v_cvt_pk_bf16_f32 v29, v38, v39
	v_cvt_pk_bf16_f32 v30, v30, v31
	v_cvt_pk_bf16_f32 v31, v40, v41
	global_store_dwordx4 v[44:45], v[28:31], off offset:256
	s_nop 1
	v_pk_mul_f32 v[30:31], v[34:35], v[152:153] op_sel_hi:[1,0]
	v_pk_mul_f32 v[34:35], v[26:27], v[152:153] op_sel_hi:[1,0]
	v_pk_mul_f32 v[26:27], v[24:25], v[152:153] op_sel_hi:[1,0]
	v_cvt_pk_bf16_f32 v24, v32, v33
	v_cvt_pk_bf16_f32 v25, v30, v31
	v_add_co_u32_e32 v30, vcc, s87, v150
	v_cvt_pk_bf16_f32 v26, v26, v27
	v_cvt_pk_bf16_f32 v27, v34, v35
	v_lshl_add_u64 v[28:29], v[150:151], 0, s[4:5]
	s_nop 0
	v_addc_co_u32_e32 v31, vcc, 0, v151, vcc
	global_store_dwordx4 v[30:31], v[24:27], off
	s_mov_b64 s[4:5], 0x58000
	s_nop 0
	v_pk_mul_f32 v[24:25], v[14:15], v[152:153] op_sel_hi:[1,0]
	v_pk_mul_f32 v[14:15], v[12:13], v[152:153] op_sel_hi:[1,0]
	v_cvt_pk_bf16_f32 v12, v20, v21
	v_cvt_pk_bf16_f32 v13, v22, v23
	s_nop 0
	v_cvt_pk_bf16_f32 v14, v14, v15
	v_cvt_pk_bf16_f32 v15, v24, v25
	global_store_dwordx4 v[28:29], v[12:15], off offset:256
	s_nop 1
	v_mov_b32_e32 v14, v153
	v_lshl_add_u64 v[12:13], v[150:151], 0, s[4:5]
	v_pk_mul_f32 v[16:17], v[16:17], v[14:15] op_sel_hi:[1,0]
	s_mov_b32 s4, 0x58000
	v_pk_mul_f32 v[20:21], v[10:11], v[14:15] op_sel_hi:[1,0]
	v_pk_mul_f32 v[10:11], v[8:9], v[14:15] op_sel_hi:[1,0]
	v_cvt_pk_bf16_f32 v8, v16, v17
	v_add_co_u32_e32 v16, vcc, s4, v150
	v_pk_mul_f32 v[18:19], v[18:19], v[14:15] op_sel_hi:[1,0]
	s_nop 0
	v_addc_co_u32_e32 v17, vcc, 0, v151, vcc
	v_cvt_pk_bf16_f32 v9, v18, v19
	v_cvt_pk_bf16_f32 v10, v10, v11
	v_cvt_pk_bf16_f32 v11, v20, v21
	global_store_dwordx4 v[16:17], v[8:11], off
	s_and_b64 vcc, exec, s[42:43]
	s_mov_b64 s[4:5], -1
	v_pk_mul_f32 v[8:9], v[2:3], v[14:15] op_sel_hi:[1,0]
	v_pk_mul_f32 v[2:3], v[0:1], v[14:15] op_sel_hi:[1,0]
	v_pk_mul_f32 v[6:7], v[6:7], v[14:15] op_sel_hi:[1,0]
	v_pk_mul_f32 v[4:5], v[4:5], v[14:15] op_sel_hi:[1,0]
	s_nop 0
	v_cvt_pk_bf16_f32 v0, v4, v5
	v_cvt_pk_bf16_f32 v1, v6, v7
	v_cvt_pk_bf16_f32 v2, v2, v3
	v_cvt_pk_bf16_f32 v3, v8, v9
	global_store_dwordx4 v[12:13], v[0:3], off offset:256
	s_cbranch_vccnz .LBB0_120
	s_waitcnt vmcnt(16)
	v_add_f32_e32 v0, v132, v133
	v_add_f32_e32 v1, v134, v135
	v_add_f32_e32 v0, v0, v1
	v_add_f32_e32 v1, v128, v129
	v_add_f32_e32 v2, v130, v131
	v_add_f32_e32 v1, v1, v2
	v_add_f32_e32 v0, v1, v0
	s_nop 1
	v_add_f32_dpp v0, v0, v0 quad_perm:[1,0,3,2] row_mask:0xf bank_mask:0xf
	s_and_saveexec_b64 s[4:5], s[40:41]
	s_cbranch_execz .LBB0_132
	s_waitcnt lgkmcnt(0)
	s_nop 0
	v_fmamk_f32 v0, v0, 0x3a800000, v222
	v_cmp_gt_f32_e32 vcc, s7, v0
	v_mul_f32_e32 v1, 0x4b800000, v0
	s_xor_b32 s28, s28, 0x400
	v_cndmask_b32_e32 v0, v0, v1, vcc
	v_rsq_f32_e32 v0, v0
	s_nop 0
	v_mul_f32_e32 v1, 0x45800000, v0
	v_cndmask_b32_e32 v0, v0, v1, vcc
	v_add_u32_e32 v1, s28, v160
	ds_write_b32 v1, v0

; __device__ __forceinline__ unsigned cvt_pk_bf16(float lo, float hi) { unsigned r; asm volatile("v_cvt_pk_bf16_f32 %0, %1, %2" : "=v"(r) : "v"(lo), "v"(hi)); return r; }
; __device__ __forceinline__ float sigm(float x) { return __builtin_amdgcn_rcpf(1.f + __builtin_amdgcn_exp2f(-LOG2E * x)); }
;     __device__ __forceinline__ void operator()(const f32x4 (&acc)[2][2][4][2], const Unit& u, int wr, int wc, int fr, int fq, LAS unsigned char* lds, int tid, int ui, const Unit& nxt, bool has_next) const {
;     ...
;         for (int ai = 0; ai < 2; ++ai)
; #pragma unroll
;             for (int m = 0; m < 4; ++m) {
;                 const int row = row0 + ai * 128 + m * 16;
;                 const float rs = rsv[ai][m];
;                 float o[8];
; #pragma unroll
;                 for (int n = 0; n < 2; ++n)
; #pragma unroll
;                     for (int e = 0; e < 4; ++e) { const float v = acc[ai][0][m][n][e] * rs + bv[0][n][e], g = acc[ai][1][m][n][e] * rs + bv[1][n][e]; o[n * 4 + e] = v * sigm(g); }
;                 u32x4 w; w.x = cvt_pk_bf16(o[0], o[1]); w.y = cvt_pk_bf16(o[2], o[3]); w.z = cvt_pk_bf16(o[4], o[5]); w.w = cvt_pk_bf16(o[6], o[7]);
;                 *(u32x4*)(O + (size_t)row * D + col0) = w;
;             }
.Lmy_epibar_glu:
	v_fma_f32 v144, v144, v172, v68
	v_fma_f32 v132, v132, v173, v80
	v_fma_f32 v124, v124, v173, v68
	v_fma_f32 v116, v116, v170, v80
	v_fma_f32 v108, v108, v170, v68
	v_fma_f32 v100, v100, v171, v80
	v_fma_f32 v92, v92, v171, v68
	v_fma_f32 v128, v128, v173, v88
	v_fma_f32 v136, v136, v172, v76
	v_mul_f32_e32 v136, 0xbfb8aa3b, v136
	v_fma_f32 v137, v137, v172, v77
	v_mul_f32_e32 v128, 0xbfb8aa3b, v128
	v_fma_f32 v129, v129, v173, v89
	v_exp_f32_e32 v136, v136
	v_mul_f32_e32 v137, 0xbfb8aa3b, v137
	v_exp_f32_e32 v128, v128
	v_mul_f32_e32 v129, 0xbfb8aa3b, v129
	v_fma_f32 v130, v130, v173, v90
	v_exp_f32_e32 v137, v137
	v_exp_f32_e32 v129, v129
	v_mul_f32_e32 v130, 0xbfb8aa3b, v130
	v_fma_f32 v131, v131, v173, v91
	v_fma_f32 v120, v120, v173, v76
	v_exp_f32_e32 v130, v130
	v_mul_f32_e32 v131, 0xbfb8aa3b, v131
	v_mul_f32_e32 v120, 0xbfb8aa3b, v120
	v_fma_f32 v121, v121, v173, v77
	v_fma_f32 v112, v112, v170, v88
	v_exp_f32_e32 v131, v131
	v_exp_f32_e32 v120, v120
	v_mul_f32_e32 v121, 0xbfb8aa3b, v121
	v_mul_f32_e32 v112, 0xbfb8aa3b, v112
	v_fma_f32 v113, v113, v170, v89
	v_add_f32_e32 v136, 1.0, v136
	v_add_f32_e32 v128, 1.0, v128
	v_exp_f32_e32 v121, v121
	v_exp_f32_e32 v112, v112
	v_mul_f32_e32 v113, 0xbfb8aa3b, v113
	v_fma_f32 v114, v114, v170, v90
	v_rcp_f32_e32 v136, v136
	v_add_f32_e32 v137, 1.0, v137
	v_rcp_f32_e32 v128, v128
	v_add_f32_e32 v129, 1.0, v129
	v_exp_f32_e32 v113, v113
	v_mul_f32_e32 v114, 0xbfb8aa3b, v114
	v_fma_f32 v115, v115, v170, v91
	v_fma_f32 v104, v104, v170, v76
	v_rcp_f32_e32 v137, v137
	v_rcp_f32_e32 v129, v129
	v_add_f32_e32 v130, 1.0, v130
	v_exp_f32_e32 v114, v114
	v_mul_f32_e32 v115, 0xbfb8aa3b, v115
	v_mul_f32_e32 v104, 0xbfb8aa3b, v104
	v_fma_f32 v105, v105, v170, v77
	v_fma_f32 v96, v96, v171, v88
	v_rcp_f32_e32 v130, v130
	v_add_f32_e32 v131, 1.0, v131
	v_add_f32_e32 v120, 1.0, v120
	v_exp_f32_e32 v115, v115
	v_exp_f32_e32 v104, v104
	v_mul_f32_e32 v105, 0xbfb8aa3b, v105
	v_mul_f32_e32 v96, 0xbfb8aa3b, v96
	v_fma_f32 v97, v97, v171, v89
	v_rcp_f32_e32 v131, v131
	v_rcp_f32_e32 v120, v120
	v_add_f32_e32 v121, 1.0, v121
	v_add_f32_e32 v112, 1.0, v112
	v_exp_f32_e32 v105, v105
	v_exp_f32_e32 v96, v96
	v_mul_f32_e32 v97, 0xbfb8aa3b, v97
	v_fma_f32 v98, v98, v171, v90
	v_mul_f32_e32 v144, v144, v136
	v_fma_f32 v136, v145, v172, v69
	v_mul_f32_e32 v128, v132, v128
	v_fma_f32 v132, v133, v173, v81
	v_rcp_f32_e32 v121, v121
	v_rcp_f32_e32 v112, v112
	v_add_f32_e32 v113, 1.0, v113
	v_exp_f32_e32 v97, v97
	v_mul_f32_e32 v98, 0xbfb8aa3b, v98
	v_fma_f32 v99, v99, v171, v91
	v_fma_f32 v84, v84, v171, v76
	v_mul_f32_e32 v145, v136, v137
	v_fma_f32 v137, v138, v172, v78
	v_mul_f32_e32 v129, v132, v129
	v_fma_f32 v132, v134, v173, v82
	v_rcp_f32_e32 v113, v113
	v_add_f32_e32 v114, 1.0, v114
	v_exp_f32_e32 v98, v98
	v_mul_f32_e32 v99, 0xbfb8aa3b, v99
	v_mul_f32_e32 v84, 0xbfb8aa3b, v84
	v_fma_f32 v85, v85, v171, v77
	v_mul_f32_e32 v137, 0xbfb8aa3b, v137
	v_mul_f32_e32 v130, v132, v130
	v_fma_f32 v132, v135, v173, v83
	v_rcp_f32_e32 v114, v114
	v_add_f32_e32 v115, 1.0, v115
	v_add_f32_e32 v104, 1.0, v104
	v_exp_f32_e32 v99, v99
	v_exp_f32_e32 v84, v84
	v_mul_f32_e32 v85, 0xbfb8aa3b, v85
	v_exp_f32_e32 v137, v137
	v_mul_f32_e32 v131, v132, v131
	v_mul_f32_e32 v132, v124, v120
	v_fma_f32 v120, v125, v173, v69
	v_rcp_f32_e32 v115, v115
	v_rcp_f32_e32 v104, v104
	v_add_f32_e32 v105, 1.0, v105
	v_add_f32_e32 v96, 1.0, v96
	v_exp_f32_e32 v85, v85
	v_mul_f32_e32 v125, v120, v121
	v_fma_f32 v121, v122, v173, v78
	v_mul_f32_e32 v112, v116, v112
	v_fma_f32 v116, v117, v170, v81
	v_rcp_f32_e32 v105, v105
	v_rcp_f32_e32 v96, v96
	v_add_f32_e32 v97, 1.0, v97
	v_fma_f32 v48, v48, v166, v76
	v_mul_f32_e32 v121, 0xbfb8aa3b, v121
	v_mul_f32_e32 v113, v116, v113
	v_fma_f32 v116, v118, v170, v82
	v_rcp_f32_e32 v97, v97
	v_add_f32_e32 v98, 1.0, v98
	v_mul_f32_e32 v48, 0xbfb8aa3b, v48
	v_fma_f32 v49, v49, v166, v77
	v_exp_f32_e32 v121, v121
	v_mul_f32_e32 v114, v116, v114
	v_fma_f32 v116, v119, v170, v83
	v_rcp_f32_e32 v98, v98
	v_add_f32_e32 v99, 1.0, v99
	v_add_f32_e32 v84, 1.0, v84
	v_exp_f32_e32 v48, v48
	v_mul_f32_e32 v49, 0xbfb8aa3b, v49
	v_fma_f32 v32, v32, v167, v76
	v_add_f32_e32 v137, 1.0, v137
	v_mul_f32_e32 v115, v116, v115
	v_mul_f32_e32 v116, v108, v104
	v_fma_f32 v104, v109, v170, v69
	v_rcp_f32_e32 v99, v99
	v_rcp_f32_e32 v84, v84
	v_add_f32_e32 v85, 1.0, v85
	v_exp_f32_e32 v49, v49
	v_mul_f32_e32 v32, 0xbfb8aa3b, v32
	v_fma_f32 v33, v33, v167, v77
	v_rcp_f32_e32 v137, v137
	v_mul_f32_e32 v109, v104, v105
	v_fma_f32 v105, v106, v170, v78
	v_mul_f32_e32 v96, v100, v96
	v_fma_f32 v100, v101, v171, v81
	v_rcp_f32_e32 v85, v85
	v_exp_f32_e32 v32, v32
	v_mul_f32_e32 v33, 0xbfb8aa3b, v33
	v_fma_f32 v16, v16, v164, v76
	v_fma_f32 v140, v140, v172, v88
	v_mul_f32_e32 v105, 0xbfb8aa3b, v105
	v_mul_f32_e32 v97, v100, v97
	v_fma_f32 v100, v102, v171, v82
	v_exp_f32_e32 v33, v33
	v_mul_f32_e32 v16, 0xbfb8aa3b, v16
	v_fma_f32 v17, v17, v164, v77
	v_mul_f32_e32 v140, 0xbfb8aa3b, v140
	v_fma_f32 v141, v141, v172, v89
	v_add_f32_e32 v121, 1.0, v121
	v_exp_f32_e32 v105, v105
	v_mul_f32_e32 v98, v100, v98
	v_fma_f32 v100, v103, v171, v83
	v_add_f32_e32 v48, 1.0, v48
	v_exp_f32_e32 v16, v16
	v_mul_f32_e32 v17, 0xbfb8aa3b, v17
	v_exp_f32_e32 v140, v140
	v_mul_f32_e32 v141, 0xbfb8aa3b, v141
	v_fma_f32 v142, v142, v172, v90
	v_fma_f32 v136, v146, v172, v70
	v_rcp_f32_e32 v121, v121
	v_mul_f32_e32 v99, v100, v99
	v_mul_f32_e32 v100, v92, v84
	v_fma_f32 v84, v93, v171, v69
	v_rcp_f32_e32 v48, v48
	v_add_f32_e32 v49, 1.0, v49
	v_exp_f32_e32 v17, v17
	v_fma_f32 v0, v0, v165, v76
	v_exp_f32_e32 v141, v141
	v_mul_f32_e32 v142, 0xbfb8aa3b, v142
; __device__ __forceinline__ unsigned cvt_pk_bf16(float lo, float hi) { unsigned r; asm volatile("v_cvt_pk_bf16_f32 %0, %1, %2" : "=v"(r) : "v"(lo), "v"(hi)); return r; }
; __device__ __forceinline__ float sigm(float x) { return __builtin_amdgcn_rcpf(1.f + __builtin_amdgcn_exp2f(-LOG2E * x)); }
;     __device__ __forceinline__ void operator()(const f32x4 (&acc)[2][2][4][2], const Unit& u, int wr, int wc, int fr, int fq, LAS unsigned char* lds, int tid, int ui, const Unit& nxt, bool has_next) const {
;     ...
;         for (int ai = 0; ai < 2; ++ai)
; #pragma unroll
;             for (int m = 0; m < 4; ++m) {
;                 const int row = row0 + ai * 128 + m * 16;
;                 const float rs = rsv[ai][m];
;                 float o[8];
; #pragma unroll
;                 for (int n = 0; n < 2; ++n)
; #pragma unroll
;                     for (int e = 0; e < 4; ++e) { const float v = acc[ai][0][m][n][e] * rs + bv[0][n][e], g = acc[ai][1][m][n][e] * rs + bv[1][n][e]; o[n * 4 + e] = v * sigm(g); }
;                 u32x4 w; w.x = cvt_pk_bf16(o[0], o[1]); w.y = cvt_pk_bf16(o[2], o[3]); w.z = cvt_pk_bf16(o[4], o[5]); w.w = cvt_pk_bf16(o[6], o[7]);
;                 *(u32x4*)(O + (size_t)row * D + col0) = w;
;             }
	v_fma_f32 v143, v143, v172, v91
	v_mul_f32_e32 v146, v136, v137
	v_fma_f32 v137, v139, v172, v79
	v_mul_f32_e32 v93, v84, v85
	v_fma_f32 v85, v86, v171, v78
	v_rcp_f32_e32 v49, v49
	v_add_f32_e32 v32, 1.0, v32
	v_mul_f32_e32 v0, 0xbfb8aa3b, v0
	v_fma_f32 v1, v1, v165, v77
	v_exp_f32_e32 v142, v142
	v_mul_f32_e32 v143, 0xbfb8aa3b, v143
	v_mul_f32_e32 v137, 0xbfb8aa3b, v137
	v_mul_f32_e32 v85, 0xbfb8aa3b, v85
	v_rcp_f32_e32 v32, v32
	v_add_f32_e32 v33, 1.0, v33
	v_exp_f32_e32 v0, v0
	v_mul_f32_e32 v1, 0xbfb8aa3b, v1
	v_exp_f32_e32 v143, v143
	v_exp_f32_e32 v137, v137
	v_fma_f32 v120, v126, v173, v70
	v_add_f32_e32 v105, 1.0, v105
	v_exp_f32_e32 v85, v85
	v_fma_f32 v52, v52, v166, v68
	v_rcp_f32_e32 v33, v33
	v_add_f32_e32 v16, 1.0, v16
	v_exp_f32_e32 v1, v1
	v_add_f32_e32 v140, 1.0, v140
	v_mul_f32_e32 v126, v120, v121
	v_fma_f32 v121, v123, v173, v79
	v_rcp_f32_e32 v105, v105
	v_mul_f32_e32 v52, v52, v48
	v_fma_f32 v48, v53, v166, v69
	v_rcp_f32_e32 v16, v16
	v_add_f32_e32 v17, 1.0, v17
	v_rcp_f32_e32 v140, v140
	v_add_f32_e32 v141, 1.0, v141
	v_mul_f32_e32 v121, 0xbfb8aa3b, v121
	v_mul_f32_e32 v53, v48, v49
	v_fma_f32 v49, v50, v166, v78
	v_fma_f32 v36, v36, v167, v68
	v_rcp_f32_e32 v17, v17
	v_rcp_f32_e32 v141, v141
	v_add_f32_e32 v142, 1.0, v142
	v_exp_f32_e32 v121, v121
	v_mul_f32_e32 v49, 0xbfb8aa3b, v49
	v_mul_f32_e32 v36, v36, v32
	v_fma_f32 v32, v37, v167, v69
	v_add_f32_e32 v0, 1.0, v0
	v_rcp_f32_e32 v142, v142
	v_add_f32_e32 v143, 1.0, v143
	v_add_f32_e32 v137, 1.0, v137
	v_fma_f32 v104, v110, v170, v70
	v_add_f32_e32 v85, 1.0, v85
	v_exp_f32_e32 v49, v49
	v_mul_f32_e32 v37, v32, v33
	v_fma_f32 v33, v34, v167, v78
	v_fma_f32 v20, v20, v164, v68
	v_rcp_f32_e32 v0, v0
	v_add_f32_e32 v1, 1.0, v1
	v_fma_f32 v148, v148, v172, v80
	v_rcp_f32_e32 v143, v143
	v_rcp_f32_e32 v137, v137
	v_mul_f32_e32 v110, v104, v105
	v_fma_f32 v105, v107, v170, v79
	v_rcp_f32_e32 v85, v85
	v_mul_f32_e32 v33, 0xbfb8aa3b, v33
	v_mul_f32_e32 v20, v20, v16
	v_fma_f32 v16, v21, v164, v69
	v_rcp_f32_e32 v1, v1
	v_mul_f32_e32 v140, v148, v140
	v_fma_f32 v148, v149, v172, v81
	v_mul_f32_e32 v105, 0xbfb8aa3b, v105
	v_exp_f32_e32 v33, v33
	v_mul_f32_e32 v21, v16, v17
	v_fma_f32 v17, v18, v164, v78
	v_mul_f32_e32 v141, v148, v141
	v_fma_f32 v148, v150, v172, v82
	v_add_f32_e32 v121, 1.0, v121
	v_exp_f32_e32 v105, v105
	v_mul_f32_e32 v17, 0xbfb8aa3b, v17
	v_fma_f32 v4, v4, v165, v68
	v_mul_f32_e32 v142, v148, v142
	v_fma_f32 v148, v151, v172, v83
	v_fma_f32 v136, v147, v172, v71
	v_rcp_f32_e32 v121, v121
	v_fma_f32 v84, v94, v171, v70
	v_add_f32_e32 v49, 1.0, v49
	v_exp_f32_e32 v17, v17
	v_mul_f32_e32 v4, v4, v0
	v_fma_f32 v0, v5, v165, v69
	v_mul_f32_e32 v143, v148, v143
	v_mul_f32_e32 v139, v136, v137
	v_cvt_pk_bf16_f32 v136, v140, v141
	v_lshlrev_b64 v[140:141], 11, v[168:169]
	v_mul_f32_e32 v94, v84, v85
	v_fma_f32 v85, v87, v171, v79
	v_rcp_f32_e32 v49, v49
	v_mul_f32_e32 v5, v0, v1
	v_fma_f32 v1, v2, v165, v78
	v_cvt_pk_bf16_f32 v137, v142, v143
	v_lshl_add_u64 v[140:141], s[24:25], 0, v[140:141]
	v_lshlrev_b64 v[142:143], 1, v[174:175]
	v_mul_f32_e32 v85, 0xbfb8aa3b, v85
	v_fma_f32 v64, v64, v166, v88
	v_add_f32_e32 v33, 1.0, v33
	v_mul_f32_e32 v1, 0xbfb8aa3b, v1
	v_lshl_add_u64 v[140:141], v[140:141], 0, v[142:143]
	v_fma_f32 v120, v127, v173, v71
	v_or_b32_e32 v124, 16, v168
	v_add_f32_e32 v105, 1.0, v105
	v_exp_f32_e32 v85, v85
	v_mul_f32_e32 v64, 0xbfb8aa3b, v64
	v_fma_f32 v65, v65, v166, v89
	v_rcp_f32_e32 v33, v33
	v_exp_f32_e32 v1, v1
	v_cvt_pk_bf16_f32 v138, v144, v145
	v_cvt_pk_bf16_f32 v139, v146, v139
	global_store_dwordx4 v[140:141], v[136:139], off
	v_mul_f32_e32 v123, v120, v121
	v_cvt_pk_bf16_f32 v120, v128, v129
	v_cvt_pk_bf16_f32 v121, v130, v131
	v_cvt_pk_bf16_f32 v122, v132, v125
	v_ashrrev_i32_e32 v125, 31, v124
	v_rcp_f32_e32 v105, v105
	v_exp_f32_e32 v64, v64
	v_mul_f32_e32 v65, 0xbfb8aa3b, v65
	v_fma_f32 v66, v66, v166, v90
	v_fma_f32 v48, v54, v166, v70
	v_fma_f32 v40, v40, v167, v88
	v_add_f32_e32 v17, 1.0, v17
	v_lshlrev_b64 v[124:125], 11, v[124:125]
	v_exp_f32_e32 v65, v65
	v_mul_f32_e32 v66, 0xbfb8aa3b, v66
	v_fma_f32 v67, v67, v166, v91
	v_mul_f32_e32 v54, v48, v49
	v_fma_f32 v49, v51, v166, v79
	v_mul_f32_e32 v40, 0xbfb8aa3b, v40
	v_fma_f32 v41, v41, v167, v89
	v_rcp_f32_e32 v17, v17
	v_lshl_add_u64 v[124:125], s[24:25], 0, v[124:125]
	v_exp_f32_e32 v66, v66
	v_mul_f32_e32 v67, 0xbfb8aa3b, v67
	v_mul_f32_e32 v49, 0xbfb8aa3b, v49
	v_exp_f32_e32 v40, v40
	v_mul_f32_e32 v41, 0xbfb8aa3b, v41
	v_fma_f32 v42, v42, v167, v90
	v_fma_f32 v32, v38, v167, v70
	v_fma_f32 v24, v24, v164, v88
	v_lshl_add_u64 v[124:125], v[124:125], 0, v[142:143]
	v_fma_f32 v104, v111, v170, v71
	v_or_b32_e32 v108, 32, v168
	v_add_f32_e32 v85, 1.0, v85
	v_exp_f32_e32 v67, v67
	v_exp_f32_e32 v49, v49
	v_exp_f32_e32 v41, v41
	v_mul_f32_e32 v42, 0xbfb8aa3b, v42
	v_fma_f32 v43, v43, v167, v91
	v_mul_f32_e32 v38, v32, v33
	v_fma_f32 v33, v35, v167, v79
	v_mul_f32_e32 v24, 0xbfb8aa3b, v24
	v_fma_f32 v25, v25, v164, v89
	v_add_f32_e32 v1, 1.0, v1
	v_cvt_pk_bf16_f32 v123, v126, v123
	global_store_dwordx4 v[124:125], v[120:123], off
	v_mul_f32_e32 v107, v104, v105
	v_cvt_pk_bf16_f32 v104, v112, v113
	v_cvt_pk_bf16_f32 v105, v114, v115
	v_cvt_pk_bf16_f32 v106, v116, v109
	v_ashrrev_i32_e32 v109, 31, v108
	v_rcp_f32_e32 v85, v85
	v_add_f32_e32 v64, 1.0, v64
	v_exp_f32_e32 v42, v42
	v_mul_f32_e32 v43, 0xbfb8aa3b, v43
	v_mul_f32_e32 v33, 0xbfb8aa3b, v33
	v_exp_f32_e32 v24, v24
	v_mul_f32_e32 v25, 0xbfb8aa3b, v25
	v_fma_f32 v26, v26, v164, v90
	v_fma_f32 v16, v22, v164, v70
; __device__ __forceinline__ unsigned cvt_pk_bf16(float lo, float hi) { unsigned r; asm volatile("v_cvt_pk_bf16_f32 %0, %1, %2" : "=v"(r) : "v"(lo), "v"(hi)); return r; }
; #define LAS __attribute__((address_space(3)))
; __device__ __forceinline__ float sigm(float x) { return __builtin_amdgcn_rcpf(1.f + __builtin_amdgcn_exp2f(-LOG2E * x)); }
; __device__ __forceinline__ void rs_finish(LAS unsigned char* lds, int buf, int tid, const f32x4& a, const f32x4& b) {
;     float t = ((a.x + a.y) + (a.z + a.w)) + ((b.x + b.y) + (b.z + b.w)); t += __shfl_xor(t, 1);
;     if (!(tid & 1)) ((LAS float*)(lds + RS_LDS_OFF))[buf * 256 + (tid >> 1)] = rsqrtf(t * (1.f / D) + RMS_EPS);
; }
;     __device__ __forceinline__ void operator()(const f32x4 (&acc)[2][2][4][2], const Unit& u, int wr, int wc, int fr, int fq, LAS unsigned char* lds, int tid, int ui, const Unit& nxt, bool has_next) const {
;     ...
;         for (int ai = 0; ai < 2; ++ai)
; #pragma unroll
;             for (int m = 0; m < 4; ++m) {
;                 const int row = row0 + ai * 128 + m * 16;
;                 const float rs = rsv[ai][m];
;                 float o[8];
; #pragma unroll
;                 for (int n = 0; n < 2; ++n)
; #pragma unroll
;                     for (int e = 0; e < 4; ++e) { const float v = acc[ai][0][m][n][e] * rs + bv[0][n][e], g = acc[ai][1][m][n][e] * rs + bv[1][n][e]; o[n * 4 + e] = v * sigm(g); }
;                 u32x4 w; w.x = cvt_pk_bf16(o[0], o[1]); w.y = cvt_pk_bf16(o[2], o[3]); w.z = cvt_pk_bf16(o[4], o[5]); w.w = cvt_pk_bf16(o[6], o[7]);
;                 *(u32x4*)(O + (size_t)row * D + col0) = w;
;             }
;         if (has_next) rs_finish(lds, (ui + 1) & 1, tid, na, nb);
	v_rcp_f32_e32 v1, v1
	v_lshlrev_b64 v[108:109], 11, v[108:109]
	v_rcp_f32_e32 v64, v64
	v_add_f32_e32 v65, 1.0, v65
	v_exp_f32_e32 v43, v43
	v_exp_f32_e32 v33, v33
	v_exp_f32_e32 v25, v25
	v_mul_f32_e32 v26, 0xbfb8aa3b, v26
	v_fma_f32 v27, v27, v164, v91
	v_mul_f32_e32 v22, v16, v17
	v_fma_f32 v17, v19, v164, v79
	v_fma_f32 v8, v8, v165, v88
	v_lshl_add_u64 v[108:109], s[24:25], 0, v[108:109]
	v_rcp_f32_e32 v65, v65
	v_add_f32_e32 v66, 1.0, v66
	v_add_f32_e32 v40, 1.0, v40
	v_exp_f32_e32 v26, v26
	v_mul_f32_e32 v27, 0xbfb8aa3b, v27
	v_mul_f32_e32 v17, 0xbfb8aa3b, v17
	v_mul_f32_e32 v8, 0xbfb8aa3b, v8
	v_fma_f32 v9, v9, v165, v89
	v_lshl_add_u64 v[108:109], v[108:109], 0, v[142:143]
	v_fma_f32 v84, v95, v171, v71
	v_or_b32_e32 v92, 48, v168
	v_rcp_f32_e32 v66, v66
	v_add_f32_e32 v67, 1.0, v67
	v_add_f32_e32 v49, 1.0, v49
	v_rcp_f32_e32 v40, v40
	v_add_f32_e32 v41, 1.0, v41
	v_exp_f32_e32 v27, v27
	v_exp_f32_e32 v17, v17
	v_exp_f32_e32 v8, v8
	v_mul_f32_e32 v9, 0xbfb8aa3b, v9
	v_fma_f32 v10, v10, v165, v90
	v_fmac_f32_e32 v91, v11, v165
	v_fma_f32 v0, v6, v165, v70
	v_fmac_f32_e32 v79, v3, v165
	v_cvt_pk_bf16_f32 v107, v110, v107
	global_store_dwordx4 v[108:109], v[104:107], off
	v_mul_f32_e32 v87, v84, v85
	v_cvt_pk_bf16_f32 v84, v96, v97
	v_cvt_pk_bf16_f32 v85, v98, v99
	v_cvt_pk_bf16_f32 v86, v100, v93
	v_ashrrev_i32_e32 v93, 31, v92
	v_fma_f32 v72, v72, v166, v80
	v_rcp_f32_e32 v67, v67
	v_rcp_f32_e32 v49, v49
	v_rcp_f32_e32 v41, v41
	v_add_f32_e32 v42, 1.0, v42
	v_add_f32_e32 v24, 1.0, v24
	v_exp_f32_e32 v9, v9
	v_mul_f32_e32 v10, 0xbfb8aa3b, v10
	v_mul_f32_e32 v11, 0xbfb8aa3b, v91
	v_mul_f32_e32 v6, v0, v1
	v_mul_f32_e32 v0, 0xbfb8aa3b, v79
	v_lshlrev_b64 v[92:93], 11, v[92:93]
	v_mul_f32_e32 v64, v72, v64
	v_fma_f32 v72, v73, v166, v81
	v_rcp_f32_e32 v42, v42
	v_add_f32_e32 v43, 1.0, v43
	v_add_f32_e32 v33, 1.0, v33
	v_rcp_f32_e32 v24, v24
	v_add_f32_e32 v25, 1.0, v25
	v_exp_f32_e32 v10, v10
	v_exp_f32_e32 v11, v11
	v_exp_f32_e32 v0, v0
	v_lshl_add_u64 v[92:93], s[24:25], 0, v[92:93]
	v_mul_f32_e32 v65, v72, v65
	v_fma_f32 v72, v74, v166, v82
	v_fma_f32 v44, v44, v167, v80
	v_rcp_f32_e32 v43, v43
	v_rcp_f32_e32 v33, v33
	v_rcp_f32_e32 v25, v25
	v_add_f32_e32 v26, 1.0, v26
	v_lshl_add_u64 v[92:93], v[92:93], 0, v[142:143]
	v_mul_f32_e32 v66, v72, v66
	v_fma_f32 v72, v75, v166, v83
	v_fma_f32 v48, v55, v166, v71
	v_mul_f32_e32 v40, v44, v40
	v_fma_f32 v44, v45, v167, v81
	v_rcp_f32_e32 v26, v26
	v_add_f32_e32 v27, 1.0, v27
	v_add_f32_e32 v17, 1.0, v17
	v_add_f32_e32 v8, 1.0, v8
	v_cvt_pk_bf16_f32 v87, v94, v87
	global_store_dwordx4 v[92:93], v[84:87], off
	v_mul_f32_e32 v67, v72, v67
	v_mul_f32_e32 v51, v48, v49
	v_cvt_pk_bf16_f32 v48, v64, v65
	v_cvt_pk_bf16_f32 v49, v66, v67
	v_cvt_pk_bf16_f32 v50, v52, v53
	v_add_co_u32_e32 v52, vcc, s33, v140
	v_mul_f32_e32 v41, v44, v41
	v_fma_f32 v44, v46, v167, v82
	v_fma_f32 v28, v28, v164, v80
	v_rcp_f32_e32 v27, v27
	v_rcp_f32_e32 v17, v17
	v_rcp_f32_e32 v8, v8
	v_add_f32_e32 v9, 1.0, v9
	v_addc_co_u32_e32 v53, vcc, 0, v141, vcc
	v_mul_f32_e32 v42, v44, v42
	v_fma_f32 v44, v47, v167, v83
	v_fma_f32 v32, v39, v167, v71
	v_mul_f32_e32 v24, v28, v24
	v_fma_f32 v28, v29, v164, v81
	v_rcp_f32_e32 v9, v9
	v_add_f32_e32 v10, 1.0, v10
	v_add_f32_e32 v11, 1.0, v11
	v_add_f32_e32 v0, 1.0, v0
	v_cvt_pk_bf16_f32 v51, v54, v51
	global_store_dwordx4 v[52:53], v[48:51], off
	v_mul_f32_e32 v43, v44, v43
	v_mul_f32_e32 v35, v32, v33
	v_cvt_pk_bf16_f32 v32, v40, v41
	v_cvt_pk_bf16_f32 v33, v42, v43
	v_cvt_pk_bf16_f32 v34, v36, v37
	v_add_co_u32_e32 v36, vcc, s86, v140
	v_mul_f32_e32 v25, v28, v25
	v_fma_f32 v28, v30, v164, v82
	v_rcp_f32_e32 v10, v10
	v_rcp_f32_e32 v11, v11
	v_rcp_f32_e32 v0, v0
	v_addc_co_u32_e32 v37, vcc, 0, v141, vcc
	v_mul_f32_e32 v26, v28, v26
	v_fma_f32 v28, v31, v164, v83
	v_fma_f32 v16, v23, v164, v71
	v_fma_f32 v12, v12, v165, v80
	v_cvt_pk_bf16_f32 v35, v38, v35
	global_store_dwordx4 v[36:37], v[32:35], off
	v_mul_f32_e32 v27, v28, v27
	v_mul_f32_e32 v19, v16, v17
	v_cvt_pk_bf16_f32 v16, v24, v25
	v_cvt_pk_bf16_f32 v17, v26, v27
	v_cvt_pk_bf16_f32 v18, v20, v21
	v_add_co_u32_e32 v20, vcc, s87, v140
	v_mul_f32_e32 v8, v12, v8
	v_fma_f32 v12, v13, v165, v81
	v_addc_co_u32_e32 v21, vcc, 0, v141, vcc
	v_mul_f32_e32 v9, v12, v9
	v_fma_f32 v12, v14, v165, v82
	v_fmac_f32_e32 v83, v15, v165
	v_fmac_f32_e32 v71, v7, v165
	v_cvt_pk_bf16_f32 v19, v22, v19
	global_store_dwordx4 v[20:21], v[16:19], off
	v_mul_f32_e32 v10, v12, v10
	v_mul_f32_e32 v11, v83, v11
	v_mul_f32_e32 v3, v71, v0
	v_cvt_pk_bf16_f32 v0, v8, v9
	v_cvt_pk_bf16_f32 v1, v10, v11
	v_cvt_pk_bf16_f32 v2, v4, v5
	v_add_co_u32_e32 v4, vcc, 0x58000, v140
	v_cvt_pk_bf16_f32 v3, v6, v3
	s_nop 1
	v_addc_co_u32_e32 v5, vcc, 0, v141, vcc
	s_and_b64 vcc, exec, s[40:41]
	global_store_dwordx4 v[4:5], v[0:3], off
	s_cbranch_vccnz .LBB0_148
	s_nop 0
	v_add_f32_e32 v0, v60, v61
	v_add_f32_e32 v1, v62, v63
	v_add_f32_e32 v0, v0, v1
	v_add_f32_e32 v1, v56, v57
	v_add_f32_e32 v2, v58, v59
	v_add_f32_e32 v1, v1, v2
	v_add_f32_e32 v0, v1, v0
	s_nop 1
	v_add_f32_dpp v0, v0, v0 quad_perm:[1,0,3,2] row_mask:0xf bank_mask:0xf
	s_and_saveexec_b64 s[4:5], s[38:39]
	s_cbranch_execz .LBB0_164
	s_waitcnt lgkmcnt(0)
	s_nop 0
	v_fmamk_f32 v0, v0, 0x3a800000, v222
	v_cmp_gt_f32_e32 vcc, s7, v0
	v_mul_f32_e32 v1, 0x4b800000, v0
	s_xor_b32 s28, s28, 0x400
	v_cndmask_b32_e32 v0, v0, v1, vcc
	v_rsq_f32_e32 v0, v0
	s_nop 0
	v_mul_f32_e32 v1, 0x45800000, v0
	v_cndmask_b32_e32 v0, v0, v1, vcc
	v_add_u32_e32 v1, s28, v190
	ds_write_b32 v1, v0

; __device__ __forceinline__ unsigned cvt_pk_bf16(float lo, float hi) { unsigned r; asm volatile("v_cvt_pk_bf16_f32 %0, %1, %2" : "=v"(r) : "v"(lo), "v"(hi)); return r; }
; #define LAS __attribute__((address_space(3)))
;     __device__ __forceinline__ void operator()(const f32x4 (&acc)[2][2][4][2], const Unit& u, int wr, int wc, int fr, int fq, LAS unsigned char* lds, int tid, int ui, const Unit& nxt, bool has_next) const {
;         f32x4 na, nb; if (has_next) rs_issue(ssp, nxt, tid, na, nb);
;         const int row0 = u.pm * 256 + wr * 64 + fr, col0 = u.pn * 128 + wc * 32 + 8 * fq;
;         float rsv[2][4]; rs_read(lds, ui & 1, wr, fr, rsv);
; #pragma unroll
;         for (int ai = 0; ai < 2; ++ai)
; #pragma unroll
;             for (int m = 0; m < 4; ++m) {
;                 const int row = row0 + ai * 128 + m * 16;
;                 const float rs = rsv[ai][m];
;                 typedef float f32x2 __attribute__((ext_vector_type(2)));
;                 const f32x2 rs2 = (f32x2){rs, rs}, nrs2 = (f32x2){-LOG2E * rs, -LOG2E * rs};
;                 unsigned wv[4];
; #pragma unroll
;                 for (int n = 0; n < 2; ++n)
; #pragma unroll
;                     for (int hp = 0; hp < 2; ++hp) {
;                         const f32x2 ag = (f32x2){acc[ai][0][m][n][2 * hp], acc[ai][0][m][n][2 * hp + 1]}, au = (f32x2){acc[ai][1][m][n][2 * hp], acc[ai][1][m][n][2 * hp + 1]};
;                         const f32x2 g = ag * rs2, up = au * rs2, ne = ag * nrs2;
;                         const f32x2 dd = (f32x2){__builtin_amdgcn_exp2f(ne.x), __builtin_amdgcn_exp2f(ne.y)} + 1.0f;
;                         const f32x2 rr = (f32x2){__builtin_amdgcn_rcpf(dd.x), __builtin_amdgcn_rcpf(dd.y)};
;                         const f32x2 oo = (g * rr) * up;
;                         wv[n * 2 + hp] = cvt_pk_bf16(oo.x, oo.y);
;                     }
;                 u32x4 w; w.x = wv[0]; w.y = wv[1]; w.z = wv[2]; w.w = wv[3];
;                 __builtin_nontemporal_store(w, (u32x4*)(O + (size_t)row * FF + col0));
;             }
.Lmy_epibar_swiglu:
	v_mul_f32_e32 v170, 0xbfb8aa3b, v157
	v_mul_f32_e32 v172, v157, v157
	v_add_u32_e32 v167, 16, v166
	v_rcp_f32_e32 v172, v172
	v_mad_i64_i32 v[174:175], s[4:5], v167, s6, v[186:187]
	v_lshl_add_u64 v[174:175], v[174:175], 0, v[188:189]
	v_pk_mul_f32 v[112:113], v[116:117], v[112:113]
	v_pk_mul_f32 v[116:117], v[116:117], v[170:171] op_sel_hi:[1,0]
	v_pk_mul_f32 v[114:115], v[118:119], v[114:115]
	v_pk_mul_f32 v[118:119], v[118:119], v[170:171] op_sel_hi:[1,0]
	v_exp_f32_e32 v116, v116
	v_exp_f32_e32 v117, v117
	v_exp_f32_e32 v118, v118
	v_exp_f32_e32 v119, v119
	v_pk_fma_f32 v[116:117], v[116:117], v[172:173], v[172:173] op_sel_hi:[1,0,0]
	v_pk_fma_f32 v[118:119], v[118:119], v[172:173], v[172:173] op_sel_hi:[1,0,0]
	v_rcp_f32_e32 v116, v116
	v_rcp_f32_e32 v117, v117
	v_rcp_f32_e32 v118, v118
	v_rcp_f32_e32 v119, v119
	v_pk_mul_f32 v[112:113], v[112:113], v[116:117]
	v_pk_mul_f32 v[114:115], v[114:115], v[118:119]
	v_cvt_pk_bf16_f32 v116, v112, v113
	v_cvt_pk_bf16_f32 v117, v114, v115
	v_pk_mul_f32 v[104:105], v[108:109], v[104:105]
	v_pk_mul_f32 v[108:109], v[108:109], v[170:171] op_sel_hi:[1,0]
	v_pk_mul_f32 v[106:107], v[110:111], v[106:107]
	v_pk_mul_f32 v[110:111], v[110:111], v[170:171] op_sel_hi:[1,0]
	v_exp_f32_e32 v108, v108
	v_exp_f32_e32 v109, v109
	v_exp_f32_e32 v110, v110
	v_exp_f32_e32 v111, v111
	v_pk_fma_f32 v[108:109], v[108:109], v[172:173], v[172:173] op_sel_hi:[1,0,0]
	v_pk_fma_f32 v[110:111], v[110:111], v[172:173], v[172:173] op_sel_hi:[1,0,0]
	v_rcp_f32_e32 v108, v108
	v_rcp_f32_e32 v109, v109
	v_rcp_f32_e32 v110, v110
	v_rcp_f32_e32 v111, v111
	v_pk_mul_f32 v[104:105], v[104:105], v[108:109]
	v_pk_mul_f32 v[106:107], v[106:107], v[110:111]
	v_cvt_pk_bf16_f32 v118, v104, v105
	v_cvt_pk_bf16_f32 v119, v106, v107
	global_store_dwordx4 v[174:175], v[116:119], off
	v_mul_f32_e32 v170, 0xbfb8aa3b, v152
	v_mul_f32_e32 v172, v152, v152
	v_add_u32_e32 v167, 32, v166
	v_rcp_f32_e32 v172, v172
	v_mad_i64_i32 v[174:175], s[4:5], v167, s6, v[186:187]
	v_lshl_add_u64 v[174:175], v[174:175], 0, v[188:189]
	v_pk_mul_f32 v[96:97], v[100:101], v[96:97]
	v_pk_mul_f32 v[100:101], v[100:101], v[170:171] op_sel_hi:[1,0]
	v_pk_mul_f32 v[98:99], v[102:103], v[98:99]
	v_pk_mul_f32 v[102:103], v[102:103], v[170:171] op_sel_hi:[1,0]
	v_exp_f32_e32 v100, v100
	v_exp_f32_e32 v101, v101
	v_exp_f32_e32 v102, v102
	v_exp_f32_e32 v103, v103
	v_pk_fma_f32 v[100:101], v[100:101], v[172:173], v[172:173] op_sel_hi:[1,0,0]
	v_pk_fma_f32 v[102:103], v[102:103], v[172:173], v[172:173] op_sel_hi:[1,0,0]
	v_rcp_f32_e32 v100, v100
	v_rcp_f32_e32 v101, v101
	v_rcp_f32_e32 v102, v102
	v_rcp_f32_e32 v103, v103
	v_pk_mul_f32 v[96:97], v[96:97], v[100:101]
	v_pk_mul_f32 v[98:99], v[98:99], v[102:103]
	v_cvt_pk_bf16_f32 v100, v96, v97
	v_cvt_pk_bf16_f32 v101, v98, v99
	v_pk_mul_f32 v[88:89], v[92:93], v[88:89]
	v_pk_mul_f32 v[92:93], v[92:93], v[170:171] op_sel_hi:[1,0]
	v_pk_mul_f32 v[90:91], v[94:95], v[90:91]
	v_pk_mul_f32 v[94:95], v[94:95], v[170:171] op_sel_hi:[1,0]
	v_exp_f32_e32 v92, v92
	v_exp_f32_e32 v93, v93
	v_exp_f32_e32 v94, v94
	v_exp_f32_e32 v95, v95
	v_pk_fma_f32 v[92:93], v[92:93], v[172:173], v[172:173] op_sel_hi:[1,0,0]
	v_pk_fma_f32 v[94:95], v[94:95], v[172:173], v[172:173] op_sel_hi:[1,0,0]
	v_rcp_f32_e32 v92, v92
	v_rcp_f32_e32 v93, v93
	v_rcp_f32_e32 v94, v94
	v_rcp_f32_e32 v95, v95
	v_pk_mul_f32 v[88:89], v[88:89], v[92:93]
	v_pk_mul_f32 v[90:91], v[90:91], v[94:95]
	v_cvt_pk_bf16_f32 v102, v88, v89
	v_cvt_pk_bf16_f32 v103, v90, v91
	global_store_dwordx4 v[174:175], v[100:103], off
	v_mul_f32_e32 v170, 0xbfb8aa3b, v153
	v_mul_f32_e32 v172, v153, v153
	v_add_u32_e32 v167, 48, v166
	v_rcp_f32_e32 v172, v172
	v_mad_i64_i32 v[174:175], s[4:5], v167, s6, v[186:187]
	v_lshl_add_u64 v[174:175], v[174:175], 0, v[188:189]
	v_pk_mul_f32 v[80:81], v[84:85], v[80:81]
	v_pk_mul_f32 v[84:85], v[84:85], v[170:171] op_sel_hi:[1,0]
	v_pk_mul_f32 v[82:83], v[86:87], v[82:83]
	v_pk_mul_f32 v[86:87], v[86:87], v[170:171] op_sel_hi:[1,0]
	v_exp_f32_e32 v84, v84
	v_exp_f32_e32 v85, v85
	v_exp_f32_e32 v86, v86
	v_exp_f32_e32 v87, v87
	v_pk_fma_f32 v[84:85], v[84:85], v[172:173], v[172:173] op_sel_hi:[1,0,0]
	v_pk_fma_f32 v[86:87], v[86:87], v[172:173], v[172:173] op_sel_hi:[1,0,0]
	v_rcp_f32_e32 v84, v84
	v_rcp_f32_e32 v85, v85
	v_rcp_f32_e32 v86, v86
	v_rcp_f32_e32 v87, v87
	v_pk_mul_f32 v[80:81], v[80:81], v[84:85]
	v_pk_mul_f32 v[82:83], v[82:83], v[86:87]
	v_cvt_pk_bf16_f32 v84, v80, v81
	v_cvt_pk_bf16_f32 v85, v82, v83
	v_pk_mul_f32 v[72:73], v[76:77], v[72:73]
	v_pk_mul_f32 v[76:77], v[76:77], v[170:171] op_sel_hi:[1,0]
	v_pk_mul_f32 v[74:75], v[78:79], v[74:75]
	v_pk_mul_f32 v[78:79], v[78:79], v[170:171] op_sel_hi:[1,0]
	v_exp_f32_e32 v76, v76
	v_exp_f32_e32 v77, v77
	v_exp_f32_e32 v78, v78
	v_exp_f32_e32 v79, v79
	v_pk_fma_f32 v[76:77], v[76:77], v[172:173], v[172:173] op_sel_hi:[1,0,0]
	v_pk_fma_f32 v[78:79], v[78:79], v[172:173], v[172:173] op_sel_hi:[1,0,0]
	v_rcp_f32_e32 v76, v76
	v_rcp_f32_e32 v77, v77
	v_rcp_f32_e32 v78, v78
	v_rcp_f32_e32 v79, v79
	v_pk_mul_f32 v[72:73], v[72:73], v[76:77]
	v_pk_mul_f32 v[74:75], v[74:75], v[78:79]
	v_cvt_pk_bf16_f32 v86, v72, v73
	v_cvt_pk_bf16_f32 v87, v74, v75
	global_store_dwordx4 v[174:175], v[84:87], off
	v_mul_f32_e32 v170, 0xbfb8aa3b, v150
	v_mul_f32_e32 v172, v150, v150
	v_add_u32_e32 v167, 128, v166
	v_rcp_f32_e32 v172, v172
	v_mad_i64_i32 v[174:175], s[4:5], v167, s6, v[186:187]
	v_lshl_add_u64 v[174:175], v[174:175], 0, v[188:189]
	v_pk_mul_f32 v[64:65], v[68:69], v[64:65]
	v_pk_mul_f32 v[68:69], v[68:69], v[170:171] op_sel_hi:[1,0]
	v_pk_mul_f32 v[66:67], v[70:71], v[66:67]
; __device__ __forceinline__ unsigned cvt_pk_bf16(float lo, float hi) { unsigned r; asm volatile("v_cvt_pk_bf16_f32 %0, %1, %2" : "=v"(r) : "v"(lo), "v"(hi)); return r; }
; #define LAS __attribute__((address_space(3)))
;     __device__ __forceinline__ void operator()(const f32x4 (&acc)[2][2][4][2], const Unit& u, int wr, int wc, int fr, int fq, LAS unsigned char* lds, int tid, int ui, const Unit& nxt, bool has_next) const {
;         f32x4 na, nb; if (has_next) rs_issue(ssp, nxt, tid, na, nb);
;         const int row0 = u.pm * 256 + wr * 64 + fr, col0 = u.pn * 128 + wc * 32 + 8 * fq;
;         float rsv[2][4]; rs_read(lds, ui & 1, wr, fr, rsv);
; #pragma unroll
;         for (int ai = 0; ai < 2; ++ai)
; #pragma unroll
;             for (int m = 0; m < 4; ++m) {
;                 const int row = row0 + ai * 128 + m * 16;
;                 const float rs = rsv[ai][m];
;                 typedef float f32x2 __attribute__((ext_vector_type(2)));
;                 const f32x2 rs2 = (f32x2){rs, rs}, nrs2 = (f32x2){-LOG2E * rs, -LOG2E * rs};
;                 unsigned wv[4];
; #pragma unroll
;                 for (int n = 0; n < 2; ++n)
; #pragma unroll
;                     for (int hp = 0; hp < 2; ++hp) {
;                         const f32x2 ag = (f32x2){acc[ai][0][m][n][2 * hp], acc[ai][0][m][n][2 * hp + 1]}, au = (f32x2){acc[ai][1][m][n][2 * hp], acc[ai][1][m][n][2 * hp + 1]};
;                         const f32x2 g = ag * rs2, up = au * rs2, ne = ag * nrs2;
;                         const f32x2 dd = (f32x2){__builtin_amdgcn_exp2f(ne.x), __builtin_amdgcn_exp2f(ne.y)} + 1.0f;
;                         const f32x2 rr = (f32x2){__builtin_amdgcn_rcpf(dd.x), __builtin_amdgcn_rcpf(dd.y)};
;                         const f32x2 oo = (g * rr) * up;
;                         wv[n * 2 + hp] = cvt_pk_bf16(oo.x, oo.y);
;                     }
;                 u32x4 w; w.x = wv[0]; w.y = wv[1]; w.z = wv[2]; w.w = wv[3];
;                 __builtin_nontemporal_store(w, (u32x4*)(O + (size_t)row * FF + col0));
;             }
	v_pk_mul_f32 v[70:71], v[70:71], v[170:171] op_sel_hi:[1,0]
	v_exp_f32_e32 v68, v68
	v_exp_f32_e32 v69, v69
	v_exp_f32_e32 v70, v70
	v_exp_f32_e32 v71, v71
	v_pk_fma_f32 v[68:69], v[68:69], v[172:173], v[172:173] op_sel_hi:[1,0,0]
	v_pk_fma_f32 v[70:71], v[70:71], v[172:173], v[172:173] op_sel_hi:[1,0,0]
	v_rcp_f32_e32 v68, v68
	v_rcp_f32_e32 v69, v69
	v_rcp_f32_e32 v70, v70
	v_rcp_f32_e32 v71, v71
	v_pk_mul_f32 v[64:65], v[64:65], v[68:69]
	v_pk_mul_f32 v[66:67], v[66:67], v[70:71]
	v_cvt_pk_bf16_f32 v68, v64, v65
	v_cvt_pk_bf16_f32 v69, v66, v67
	v_pk_mul_f32 v[48:49], v[52:53], v[48:49]
	v_pk_mul_f32 v[52:53], v[52:53], v[170:171] op_sel_hi:[1,0]
	v_pk_mul_f32 v[50:51], v[54:55], v[50:51]
	v_pk_mul_f32 v[54:55], v[54:55], v[170:171] op_sel_hi:[1,0]
	v_exp_f32_e32 v52, v52
	v_exp_f32_e32 v53, v53
	v_exp_f32_e32 v54, v54
	v_exp_f32_e32 v55, v55
	v_pk_fma_f32 v[52:53], v[52:53], v[172:173], v[172:173] op_sel_hi:[1,0,0]
	v_pk_fma_f32 v[54:55], v[54:55], v[172:173], v[172:173] op_sel_hi:[1,0,0]
	v_rcp_f32_e32 v52, v52
	v_rcp_f32_e32 v53, v53
	v_rcp_f32_e32 v54, v54
	v_rcp_f32_e32 v55, v55
	v_pk_mul_f32 v[48:49], v[48:49], v[52:53]
	v_pk_mul_f32 v[50:51], v[50:51], v[54:55]
	v_cvt_pk_bf16_f32 v70, v48, v49
	v_cvt_pk_bf16_f32 v71, v50, v51
	global_store_dwordx4 v[174:175], v[68:71], off
	v_mul_f32_e32 v170, 0xbfb8aa3b, v151
	v_mul_f32_e32 v172, v151, v151
	v_add_u32_e32 v167, 144, v166
	v_rcp_f32_e32 v172, v172
	v_mad_i64_i32 v[174:175], s[4:5], v167, s6, v[186:187]
	v_lshl_add_u64 v[174:175], v[174:175], 0, v[188:189]
	v_pk_mul_f32 v[40:41], v[44:45], v[40:41]
	v_pk_mul_f32 v[44:45], v[44:45], v[170:171] op_sel_hi:[1,0]
	v_pk_mul_f32 v[42:43], v[46:47], v[42:43]
	v_pk_mul_f32 v[46:47], v[46:47], v[170:171] op_sel_hi:[1,0]
	v_exp_f32_e32 v44, v44
	v_exp_f32_e32 v45, v45
	v_exp_f32_e32 v46, v46
	v_exp_f32_e32 v47, v47
	v_pk_fma_f32 v[44:45], v[44:45], v[172:173], v[172:173] op_sel_hi:[1,0,0]
	v_pk_fma_f32 v[46:47], v[46:47], v[172:173], v[172:173] op_sel_hi:[1,0,0]
	v_rcp_f32_e32 v44, v44
	v_rcp_f32_e32 v45, v45
	v_rcp_f32_e32 v46, v46
	v_rcp_f32_e32 v47, v47
	v_pk_mul_f32 v[40:41], v[40:41], v[44:45]
	v_pk_mul_f32 v[42:43], v[42:43], v[46:47]
	v_cvt_pk_bf16_f32 v44, v40, v41
	v_cvt_pk_bf16_f32 v45, v42, v43
	v_pk_mul_f32 v[32:33], v[36:37], v[32:33]
	v_pk_mul_f32 v[36:37], v[36:37], v[170:171] op_sel_hi:[1,0]
	v_pk_mul_f32 v[34:35], v[38:39], v[34:35]
	v_pk_mul_f32 v[38:39], v[38:39], v[170:171] op_sel_hi:[1,0]
	v_exp_f32_e32 v36, v36
	v_exp_f32_e32 v37, v37
	v_exp_f32_e32 v38, v38
	v_exp_f32_e32 v39, v39
	v_pk_fma_f32 v[36:37], v[36:37], v[172:173], v[172:173] op_sel_hi:[1,0,0]
	v_pk_fma_f32 v[38:39], v[38:39], v[172:173], v[172:173] op_sel_hi:[1,0,0]
	v_rcp_f32_e32 v36, v36
	v_rcp_f32_e32 v37, v37
	v_rcp_f32_e32 v38, v38
	v_rcp_f32_e32 v39, v39
	v_pk_mul_f32 v[32:33], v[32:33], v[36:37]
	v_pk_mul_f32 v[34:35], v[34:35], v[38:39]
	v_cvt_pk_bf16_f32 v46, v32, v33
	v_cvt_pk_bf16_f32 v47, v34, v35
	global_store_dwordx4 v[174:175], v[44:47], off
	v_mul_f32_e32 v170, 0xbfb8aa3b, v148
	v_mul_f32_e32 v172, v148, v148
	v_add_u32_e32 v167, 160, v166
	v_rcp_f32_e32 v172, v172
	v_mad_i64_i32 v[174:175], s[4:5], v167, s6, v[186:187]
	v_lshl_add_u64 v[174:175], v[174:175], 0, v[188:189]
	v_pk_mul_f32 v[24:25], v[28:29], v[24:25]
	v_pk_mul_f32 v[28:29], v[28:29], v[170:171] op_sel_hi:[1,0]
	v_pk_mul_f32 v[26:27], v[30:31], v[26:27]
	v_pk_mul_f32 v[30:31], v[30:31], v[170:171] op_sel_hi:[1,0]
	v_exp_f32_e32 v28, v28
	v_exp_f32_e32 v29, v29
	v_exp_f32_e32 v30, v30
	v_exp_f32_e32 v31, v31
	v_pk_fma_f32 v[28:29], v[28:29], v[172:173], v[172:173] op_sel_hi:[1,0,0]
	v_pk_fma_f32 v[30:31], v[30:31], v[172:173], v[172:173] op_sel_hi:[1,0,0]
	v_rcp_f32_e32 v28, v28
	v_rcp_f32_e32 v29, v29
	v_rcp_f32_e32 v30, v30
	v_rcp_f32_e32 v31, v31
	v_pk_mul_f32 v[24:25], v[24:25], v[28:29]
	v_pk_mul_f32 v[26:27], v[26:27], v[30:31]
	v_cvt_pk_bf16_f32 v28, v24, v25
	v_cvt_pk_bf16_f32 v29, v26, v27
	v_pk_mul_f32 v[16:17], v[20:21], v[16:17]
	v_pk_mul_f32 v[20:21], v[20:21], v[170:171] op_sel_hi:[1,0]
	v_pk_mul_f32 v[18:19], v[22:23], v[18:19]
	v_pk_mul_f32 v[22:23], v[22:23], v[170:171] op_sel_hi:[1,0]
	v_exp_f32_e32 v20, v20
	v_exp_f32_e32 v21, v21
	v_exp_f32_e32 v22, v22
	v_exp_f32_e32 v23, v23
	v_pk_fma_f32 v[20:21], v[20:21], v[172:173], v[172:173] op_sel_hi:[1,0,0]
	v_pk_fma_f32 v[22:23], v[22:23], v[172:173], v[172:173] op_sel_hi:[1,0,0]
	v_rcp_f32_e32 v20, v20
	v_rcp_f32_e32 v21, v21
	v_rcp_f32_e32 v22, v22
	v_rcp_f32_e32 v23, v23
	v_pk_mul_f32 v[16:17], v[16:17], v[20:21]
	v_pk_mul_f32 v[18:19], v[18:19], v[22:23]
	v_cvt_pk_bf16_f32 v30, v16, v17
	v_cvt_pk_bf16_f32 v31, v18, v19
	global_store_dwordx4 v[174:175], v[28:31], off
	v_mul_f32_e32 v170, 0xbfb8aa3b, v149
	v_mul_f32_e32 v172, v149, v149
	v_add_u32_e32 v167, 176, v166
	v_rcp_f32_e32 v172, v172
	v_mad_i64_i32 v[174:175], s[4:5], v167, s6, v[186:187]
	v_lshl_add_u64 v[174:175], v[174:175], 0, v[188:189]
	v_pk_mul_f32 v[8:9], v[12:13], v[8:9]
	v_pk_mul_f32 v[12:13], v[12:13], v[170:171] op_sel_hi:[1,0]
	v_pk_mul_f32 v[10:11], v[14:15], v[10:11]
	v_pk_mul_f32 v[14:15], v[14:15], v[170:171] op_sel_hi:[1,0]
	v_exp_f32_e32 v12, v12
	v_exp_f32_e32 v13, v13
	v_exp_f32_e32 v14, v14
	v_exp_f32_e32 v15, v15
	v_pk_fma_f32 v[12:13], v[12:13], v[172:173], v[172:173] op_sel_hi:[1,0,0]
	v_pk_fma_f32 v[14:15], v[14:15], v[172:173], v[172:173] op_sel_hi:[1,0,0]
	v_rcp_f32_e32 v12, v12
	v_rcp_f32_e32 v13, v13
	v_rcp_f32_e32 v14, v14
	v_rcp_f32_e32 v15, v15
	v_pk_mul_f32 v[8:9], v[8:9], v[12:13]
	v_pk_mul_f32 v[10:11], v[10:11], v[14:15]
	v_cvt_pk_bf16_f32 v12, v8, v9
	v_cvt_pk_bf16_f32 v13, v10, v11
	v_pk_mul_f32 v[0:1], v[4:5], v[0:1]
	v_pk_mul_f32 v[4:5], v[4:5], v[170:171] op_sel_hi:[1,0]
	v_pk_mul_f32 v[2:3], v[6:7], v[2:3]
	v_pk_mul_f32 v[6:7], v[6:7], v[170:171] op_sel_hi:[1,0]
	v_exp_f32_e32 v4, v4
	v_exp_f32_e32 v5, v5
	v_exp_f32_e32 v6, v6
	v_exp_f32_e32 v7, v7
	v_pk_fma_f32 v[4:5], v[4:5], v[172:173], v[172:173] op_sel_hi:[1,0,0]
	v_pk_fma_f32 v[6:7], v[6:7], v[172:173], v[172:173] op_sel_hi:[1,0,0]
	v_rcp_f32_e32 v4, v4
	v_rcp_f32_e32 v5, v5
	v_rcp_f32_e32 v6, v6
	v_rcp_f32_e32 v7, v7
	v_pk_mul_f32 v[0:1], v[0:1], v[4:5]
	v_pk_mul_f32 v[2:3], v[2:3], v[6:7]
	v_cvt_pk_bf16_f32 v14, v0, v1
	v_cvt_pk_bf16_f32 v15, v2, v3
	global_store_dwordx4 v[174:175], v[12:15], off
	s_and_b64 vcc, exec, s[40:41]
	s_mov_b64 s[4:5], -1
	s_cbranch_vccnz .LBB0_232
; #define LAS __attribute__((address_space(3)))
; __device__ __forceinline__ void rs_finish(LAS unsigned char* lds, int buf, int tid, const f32x4& a, const f32x4& b) {
;     float t = ((a.x + a.y) + (a.z + a.w)) + ((b.x + b.y) + (b.z + b.w)); t += __shfl_xor(t, 1);
;     if (!(tid & 1)) ((LAS float*)(lds + RS_LDS_OFF))[buf * 256 + (tid >> 1)] = rsqrtf(t * (1.f / D) + RMS_EPS);
; }
;     __device__ __forceinline__ void operator()(const f32x4 (&acc)[2][2][4][2], const Unit& u, int wr, int wc, int fr, int fq, LAS unsigned char* lds, int tid, int ui, const Unit& nxt, bool has_next) const {
;     ...
;         if (has_next) rs_finish(lds, (ui + 1) & 1, tid, na, nb);
	s_waitcnt vmcnt(8)
	v_add_f32_e32 v0, v60, v61
	v_add_f32_e32 v1, v62, v63
	v_add_f32_e32 v0, v0, v1
	v_add_f32_e32 v1, v56, v57
	v_add_f32_e32 v2, v58, v59
	v_add_f32_e32 v1, v1, v2
	v_add_f32_e32 v0, v1, v0
	s_nop 1
	v_add_f32_dpp v0, v0, v0 quad_perm:[1,0,3,2] row_mask:0xf bank_mask:0xf
	s_and_saveexec_b64 s[4:5], s[38:39]
	s_cbranch_execz .LBB0_244
	s_waitcnt lgkmcnt(0)
	s_nop 0
	v_fmamk_f32 v0, v0, 0x3a800000, v222
	v_cmp_gt_f32_e32 vcc, s7, v0
	v_mul_f32_e32 v1, 0x4b800000, v0
	s_xor_b32 s25, s25, 0x400
	v_cndmask_b32_e32 v0, v0, v1, vcc
	v_rsq_f32_e32 v0, v0
	s_nop 0
	v_mul_f32_e32 v1, 0x45800000, v0
	v_cndmask_b32_e32 v0, v0, v1, vcc
	v_add_u32_e32 v1, s25, v162
	ds_write_b32 v1, v0
